# combo3b: like combo3 but lgkmcnt(0) kept after the pre-MFMA barrier (original wait placement), setprio 1 before barrier
# speedup vs baseline: 1.0003x; 1.0003x over previous
; #define PG8_STAGE(bufoff, gbase, voff) do { _Pragma("unroll") for (int _i = 0; _i < 2; ++_i) \
;     __builtin_amdgcn_global_load_lds((const unsigned*)((const char*)(gbase) + (voff)[_i]), (LAS unsigned*)(lds + (bufoff) + ldsw + _i * 8192), 16, 0, 0); } while (0)
; #define PG8_LDA(dst, b, h) do { _Pragma("unroll") for (int m = 0; m < 4; ++m) _Pragma("unroll") for (int k = 0; k < 2; ++k) dst[m][k] = *(const LAS bf16x8*)(lds + PG8_SA(b, h) + aoff + m * 2048 + k * 1024); } while (0)
; #define PG8_LDB(dst, b, h) do { _Pragma("unroll") for (int n = 0; n < 2; ++n) _Pragma("unroll") for (int k = 0; k < 2; ++k) dst[n][k] = *(const LAS bf16x8*)(lds + PG8_SB(b, h) + boff + n * 2048 + k * 1024); } while (0)
; #define PG8_WAIT_V(n) asm volatile("s_waitcnt vmcnt(" #n ")" ::: "memory")
; #define PG8_WAIT_L(n) asm volatile("s_waitcnt lgkmcnt(" #n ")" ::: "memory")
; #define PG8_BAR __builtin_amdgcn_s_barrier()
; #define PG8_SCHED __builtin_amdgcn_sched_barrier(0)
; template <class Epi, class Sched = StaticOrder>
; DI void gemm_phase(LAS unsigned char* lds, const Gemm g, const Sched& S, const Epi& E) {
;     ...
;     for (int t = 0; t < nt; t += 2) {
;       const bool last = (t == nt - 2);
;       const char* a1 = cA + (size_t)(t + 1) * kstep;
;       const char* a2 = last ? nA : cA + (size_t)(t + 2) * kstep; const char* b2 = last ? nB : cB + (size_t)(t + 2) * kstep;
;       const char* a3 = a2 + kstep; const char* b3 = b2 + kstep;
;       PG8_LDB(B0, 0, 0); PG8_SCHED; PG8_LDA(At, 0, 0); PG8_STAGE(PG8_SA(1, 1), a1 + hstep, voffA);
;       PG8_WAIT_L(8); PG8_BAR; PG8_WAIT_L(0); PG8_MMA(0, 0, At, B0); PG8_BAR; PG8_SCHED;
;       PG8_LDB(B1, 0, 1); PG8_STAGE(PG8_SB(0, 0), b2, voffB);
;       PG8_BAR; PG8_WAIT_L(0); PG8_MMA(0, 1, At, B1); PG8_BAR;
;       PG8_LDA(At, 0, 1); PG8_STAGE(PG8_SA(0, 0), a2, voffA);
;       PG8_BAR; PG8_WAIT_L(0); PG8_MMA(1, 0, At, B0); PG8_BAR; PG8_SCHED;
;       PG8_STAGE(PG8_SB(0, 1), b2 + hstep, voffB);
;       PG8_WAIT_V(6); PG8_BAR; PG8_MMA(1, 1, At, B1); PG8_BAR;
;       PG8_LDB(B0, 1, 0); PG8_SCHED; PG8_LDA(At, 1, 0); PG8_STAGE(PG8_SA(0, 1), a2 + hstep, voffA);
;       PG8_WAIT_L(8); PG8_BAR; PG8_WAIT_L(0); PG8_MMA(0, 0, At, B0); PG8_BAR; PG8_SCHED;
;       PG8_LDB(B1, 1, 1); PG8_STAGE(PG8_SB(1, 0), b3, voffB);
;       PG8_BAR; PG8_WAIT_L(0); PG8_MMA(0, 1, At, B1); PG8_BAR;
.LBB0_346:
	s_add_u32 s8, s6, 0xfff80080
	s_addc_u32 s9, s7, -1
	s_cmp_eq_u32 s52, 28
	s_cselect_b32 s11, s31, s9
	s_cselect_b32 s10, s42, s8
	s_cselect_b32 s9, s29, s45
	s_cselect_b32 s8, s43, s44
	s_add_i32 m0, s48, 0xc000
	ds_read_b128 v[162:165], v174
	ds_read_b128 v[166:169], v174 offset:1024
	ds_read_b128 v[178:181], v174 offset:2048
	ds_read_b128 v[182:185], v174 offset:3072
	ds_read_b128 v[186:189], v174 offset:4096
	ds_read_b128 v[190:193], v174 offset:5120
	ds_read_b128 v[194:197], v174 offset:6144
	ds_read_b128 v[198:201], v174 offset:7168
	global_load_lds_dwordx4 v146, s[6:7]
	s_add_i32 m0, s48, 0xe000
	s_nop 0
	global_load_lds_dwordx4 v148, s[6:7]
	s_waitcnt lgkmcnt(8)
	s_setprio 1
	s_barrier
	s_waitcnt lgkmcnt(0)
	v_mfma_f32_16x16x32_bf16 v[124:127], v[128:131], v[162:165], v[124:127]
	v_mfma_f32_16x16x32_bf16 v[120:123], v[154:157], v[162:165], v[120:123]
	v_mfma_f32_16x16x32_bf16 v[108:111], v[128:131], v[178:181], v[108:111]
	v_mfma_f32_16x16x32_bf16 v[104:107], v[154:157], v[178:181], v[104:107]
	v_mfma_f32_16x16x32_bf16 v[100:103], v[128:131], v[186:189], v[100:103]
	v_mfma_f32_16x16x32_bf16 v[92:95], v[154:157], v[186:189], v[92:95]
	v_mfma_f32_16x16x32_bf16 v[84:87], v[128:131], v[194:197], v[84:87]
	v_mfma_f32_16x16x32_bf16 v[76:79], v[154:157], v[194:197], v[76:79]
	v_mfma_f32_16x16x32_bf16 v[124:127], v[132:135], v[166:169], v[124:127]
	v_mfma_f32_16x16x32_bf16 v[120:123], v[158:161], v[166:169], v[120:123]
	v_mfma_f32_16x16x32_bf16 v[108:111], v[132:135], v[182:185], v[108:111]
	v_mfma_f32_16x16x32_bf16 v[104:107], v[158:161], v[182:185], v[104:107]
	v_mfma_f32_16x16x32_bf16 v[100:103], v[132:135], v[190:193], v[100:103]
	v_mfma_f32_16x16x32_bf16 v[92:95], v[158:161], v[190:193], v[92:95]
	v_mfma_f32_16x16x32_bf16 v[84:87], v[132:135], v[198:201], v[84:87]
	v_mfma_f32_16x16x32_bf16 v[76:79], v[158:161], v[198:201], v[76:79]
	s_barrier
	s_setprio 0
	s_add_i32 s53, s65, s41
	s_add_u32 s98, s8, 0x80
	s_addc_u32 s99, s9, 0
	s_add_u32 s100, s10, 0x80
	s_addc_u32 s101, s11, 0
	s_mov_b32 m0, s53
	ds_read_b128 v[202:205], v175
	ds_read_b128 v[206:209], v175 offset:1024
	ds_read_b128 v[212:215], v175 offset:2048
	ds_read_b128 v[216:219], v175 offset:3072
	global_load_lds_dwordx4 v140, s[8:9]
	s_add_i32 m0, s53, 0x2000
	s_nop 0
	global_load_lds_dwordx4 v136, s[8:9]
	s_setprio 1
	s_barrier
	s_waitcnt lgkmcnt(0)
	v_mfma_f32_16x16x32_bf16 v[116:119], v[202:205], v[162:165], v[116:119]
	v_mfma_f32_16x16x32_bf16 v[112:115], v[212:215], v[162:165], v[112:115]
	v_mfma_f32_16x16x32_bf16 v[96:99], v[202:205], v[178:181], v[96:99]
	v_mfma_f32_16x16x32_bf16 v[88:91], v[212:215], v[178:181], v[88:91]
	v_mfma_f32_16x16x32_bf16 v[80:83], v[202:205], v[186:189], v[80:83]
	v_mfma_f32_16x16x32_bf16 v[72:75], v[212:215], v[186:189], v[72:75]
	v_mfma_f32_16x16x32_bf16 v[68:71], v[202:205], v[194:197], v[68:71]
	v_mfma_f32_16x16x32_bf16 v[64:67], v[212:215], v[194:197], v[64:67]
	v_mfma_f32_16x16x32_bf16 v[116:119], v[206:209], v[166:169], v[116:119]
	v_mfma_f32_16x16x32_bf16 v[112:115], v[216:219], v[166:169], v[112:115]
	v_mfma_f32_16x16x32_bf16 v[96:99], v[206:209], v[182:185], v[96:99]
	v_mfma_f32_16x16x32_bf16 v[88:91], v[216:219], v[182:185], v[88:91]
	v_mfma_f32_16x16x32_bf16 v[80:83], v[206:209], v[190:193], v[80:83]
	v_mfma_f32_16x16x32_bf16 v[72:75], v[216:219], v[190:193], v[72:75]
	v_mfma_f32_16x16x32_bf16 v[68:71], v[206:209], v[198:201], v[68:71]
	v_mfma_f32_16x16x32_bf16 v[64:67], v[216:219], v[198:201], v[64:67]
	s_barrier
	s_setprio 0
	s_mov_b32 m0, s48
	ds_read_b128 v[162:165], v174 offset:16384
	ds_read_b128 v[166:169], v174 offset:17408
	ds_read_b128 v[178:181], v174 offset:18432
	ds_read_b128 v[182:185], v174 offset:19456
	ds_read_b128 v[186:189], v174 offset:20480
	ds_read_b128 v[190:193], v174 offset:21504
	ds_read_b128 v[194:197], v174 offset:22528
	ds_read_b128 v[198:201], v174 offset:23552
	global_load_lds_dwordx4 v142, s[10:11]
	s_mov_b32 m0, s49
	s_nop 0
	global_load_lds_dwordx4 v138, s[10:11]
	s_waitcnt vmcnt(10)
	s_setprio 1
	s_barrier
	s_waitcnt lgkmcnt(0)
	v_mfma_f32_16x16x32_bf16 v[60:63], v[128:131], v[162:165], v[60:63]
	v_mfma_f32_16x16x32_bf16 v[56:59], v[154:157], v[162:165], v[56:59]
	v_mfma_f32_16x16x32_bf16 v[52:55], v[128:131], v[178:181], v[52:55]
	v_mfma_f32_16x16x32_bf16 v[44:47], v[154:157], v[178:181], v[44:47]
	v_mfma_f32_16x16x32_bf16 v[36:39], v[128:131], v[186:189], v[36:39]
	v_mfma_f32_16x16x32_bf16 v[28:31], v[154:157], v[186:189], v[28:31]
	v_mfma_f32_16x16x32_bf16 v[20:23], v[128:131], v[194:197], v[20:23]
	v_mfma_f32_16x16x32_bf16 v[12:15], v[154:157], v[194:197], v[12:15]
	v_mfma_f32_16x16x32_bf16 v[60:63], v[132:135], v[166:169], v[60:63]
	v_mfma_f32_16x16x32_bf16 v[56:59], v[158:161], v[166:169], v[56:59]
	v_mfma_f32_16x16x32_bf16 v[52:55], v[132:135], v[182:185], v[52:55]
	v_mfma_f32_16x16x32_bf16 v[44:47], v[158:161], v[182:185], v[44:47]
	v_mfma_f32_16x16x32_bf16 v[36:39], v[132:135], v[190:193], v[36:39]
	v_mfma_f32_16x16x32_bf16 v[28:31], v[158:161], v[190:193], v[28:31]
	v_mfma_f32_16x16x32_bf16 v[20:23], v[132:135], v[198:201], v[20:23]
	v_mfma_f32_16x16x32_bf16 v[12:15], v[158:161], v[198:201], v[12:15]
	s_barrier
	s_setprio 0
	s_add_u32 s54, s8, 0x80000
	s_addc_u32 s55, s9, 0
	s_add_i32 s53, s72, s41
	s_mov_b32 m0, s53
	s_nop 0
	global_load_lds_dwordx4 v140, s[54:55]
	s_add_i32 m0, s53, 0x2000
	s_nop 0
	global_load_lds_dwordx4 v136, s[54:55]
	s_add_i32 s53, 0, 0x18000
	v_add_u32_e32 v158, s53, v171
	ds_read_b128 v[128:131], v158
	ds_read_b128 v[132:135], v158 offset:1024
	ds_read_b128 v[154:157], v158 offset:2048
	ds_read_b128 v[158:161], v158 offset:3072
	s_waitcnt vmcnt(6)
	s_setprio 1
	s_barrier
; #define PG8_STAGE(bufoff, gbase, voff) do { _Pragma("unroll") for (int _i = 0; _i < 2; ++_i) \
;     __builtin_amdgcn_global_load_lds((const unsigned*)((const char*)(gbase) + (voff)[_i]), (LAS unsigned*)(lds + (bufoff) + ldsw + _i * 8192), 16, 0, 0); } while (0)
; #define PG8_LDA(dst, b, h) do { _Pragma("unroll") for (int m = 0; m < 4; ++m) _Pragma("unroll") for (int k = 0; k < 2; ++k) dst[m][k] = *(const LAS bf16x8*)(lds + PG8_SA(b, h) + aoff + m * 2048 + k * 1024); } while (0)
; #define PG8_LDB(dst, b, h) do { _Pragma("unroll") for (int n = 0; n < 2; ++n) _Pragma("unroll") for (int k = 0; k < 2; ++k) dst[n][k] = *(const LAS bf16x8*)(lds + PG8_SB(b, h) + boff + n * 2048 + k * 1024); } while (0)
; #define PG8_MMA(ai, bj, At, Bt) do { __builtin_amdgcn_s_setprio(1); _Pragma("unroll") for (int m = 0; m < 4; ++m) _Pragma("unroll") for (int n = 0; n < 2; ++n) _Pragma("unroll") for (int k = 0; k < 2; ++k) \
;     acc[ai][bj][m][n] = __builtin_amdgcn_mfma_f32_16x16x32_bf16(Bt[n][k], At[m][k], acc[ai][bj][m][n], 0, 0, 0); __builtin_amdgcn_s_setprio(0); } while (0)
; #define PG8_WAIT_V(n) asm volatile("s_waitcnt vmcnt(" #n ")" ::: "memory")
; #define PG8_WAIT_L(n) asm volatile("s_waitcnt lgkmcnt(" #n ")" ::: "memory")
; #define PG8_BAR __builtin_amdgcn_s_barrier()
; #define PG8_SCHED __builtin_amdgcn_sched_barrier(0)
; template <class Epi, class Sched = StaticOrder>
; DI void gemm_phase(LAS unsigned char* lds, const Gemm g, const Sched& S, const Epi& E) {
;     ...
;       PG8_WAIT_V(6); PG8_BAR; PG8_MMA(1, 1, At, B1); PG8_BAR;
;       PG8_LDB(B0, 1, 0); PG8_SCHED; PG8_LDA(At, 1, 0); PG8_STAGE(PG8_SA(0, 1), a2 + hstep, voffA);
;       PG8_WAIT_L(8); PG8_BAR; PG8_WAIT_L(0); PG8_MMA(0, 0, At, B0); PG8_BAR; PG8_SCHED;
;       PG8_LDB(B1, 1, 1); PG8_STAGE(PG8_SB(1, 0), b3, voffB);
;       PG8_BAR; PG8_WAIT_L(0); PG8_MMA(0, 1, At, B1); PG8_BAR;
;       PG8_LDA(At, 1, 1); PG8_STAGE(PG8_SA(1, 0), a3, voffA);
;       PG8_BAR; PG8_WAIT_L(0); PG8_MMA(1, 0, At, B0); PG8_BAR; PG8_SCHED;
;       PG8_STAGE(PG8_SB(1, 1), b3 + hstep, voffB);
;       PG8_WAIT_V(6); PG8_BAR; PG8_MMA(1, 1, At, B1); PG8_BAR;
	v_mfma_f32_16x16x32_bf16 v[48:51], v[202:205], v[162:165], v[48:51]
	v_mfma_f32_16x16x32_bf16 v[40:43], v[212:215], v[162:165], v[40:43]
	v_mfma_f32_16x16x32_bf16 v[32:35], v[202:205], v[178:181], v[32:35]
	v_mfma_f32_16x16x32_bf16 v[24:27], v[212:215], v[178:181], v[24:27]
	v_mfma_f32_16x16x32_bf16 v[16:19], v[202:205], v[186:189], v[16:19]
	v_mfma_f32_16x16x32_bf16 v[8:11], v[212:215], v[186:189], v[8:11]
	v_mfma_f32_16x16x32_bf16 v[4:7], v[202:205], v[194:197], v[4:7]
	v_mfma_f32_16x16x32_bf16 v[0:3], v[212:215], v[194:197], v[0:3]
	v_mfma_f32_16x16x32_bf16 v[48:51], v[206:209], v[166:169], v[48:51]
	v_mfma_f32_16x16x32_bf16 v[40:43], v[216:219], v[166:169], v[40:43]
	v_mfma_f32_16x16x32_bf16 v[32:35], v[206:209], v[182:185], v[32:35]
	v_mfma_f32_16x16x32_bf16 v[24:27], v[216:219], v[182:185], v[24:27]
	v_mfma_f32_16x16x32_bf16 v[16:19], v[206:209], v[190:193], v[16:19]
	v_mfma_f32_16x16x32_bf16 v[8:11], v[216:219], v[190:193], v[8:11]
	v_mfma_f32_16x16x32_bf16 v[4:7], v[206:209], v[198:201], v[4:7]
	v_mfma_f32_16x16x32_bf16 v[0:3], v[216:219], v[198:201], v[0:3]
	s_barrier
	s_setprio 0
	s_add_u32 s10, s10, 0x80000
	s_addc_u32 s11, s11, 0
	s_mov_b32 m0, s50
	ds_read_b128 v[162:165], v174 offset:32768
	ds_read_b128 v[166:169], v174 offset:33792
	ds_read_b128 v[178:181], v174 offset:34816
	ds_read_b128 v[182:185], v174 offset:35840
	ds_read_b128 v[186:189], v174 offset:36864
	ds_read_b128 v[190:193], v174 offset:37888
	ds_read_b128 v[194:197], v174 offset:38912
	ds_read_b128 v[198:201], v174 offset:39936
	global_load_lds_dwordx4 v142, s[10:11]
	s_mov_b32 m0, s51
	s_nop 0
	global_load_lds_dwordx4 v138, s[10:11]
	s_waitcnt lgkmcnt(8)
	s_setprio 1
	s_barrier
	s_waitcnt lgkmcnt(0)
	v_mfma_f32_16x16x32_bf16 v[124:127], v[128:131], v[162:165], v[124:127]
	v_mfma_f32_16x16x32_bf16 v[120:123], v[154:157], v[162:165], v[120:123]
	v_mfma_f32_16x16x32_bf16 v[108:111], v[128:131], v[178:181], v[108:111]
	v_mfma_f32_16x16x32_bf16 v[104:107], v[154:157], v[178:181], v[104:107]
	v_mfma_f32_16x16x32_bf16 v[100:103], v[128:131], v[186:189], v[100:103]
	v_mfma_f32_16x16x32_bf16 v[92:95], v[154:157], v[186:189], v[92:95]
	v_mfma_f32_16x16x32_bf16 v[84:87], v[128:131], v[194:197], v[84:87]
	v_mfma_f32_16x16x32_bf16 v[76:79], v[154:157], v[194:197], v[76:79]
	v_mfma_f32_16x16x32_bf16 v[124:127], v[132:135], v[166:169], v[124:127]
	v_mfma_f32_16x16x32_bf16 v[120:123], v[158:161], v[166:169], v[120:123]
	v_mfma_f32_16x16x32_bf16 v[108:111], v[132:135], v[182:185], v[108:111]
	v_mfma_f32_16x16x32_bf16 v[104:107], v[158:161], v[182:185], v[104:107]
	v_mfma_f32_16x16x32_bf16 v[100:103], v[132:135], v[190:193], v[100:103]
	v_mfma_f32_16x16x32_bf16 v[92:95], v[158:161], v[190:193], v[92:95]
	v_mfma_f32_16x16x32_bf16 v[84:87], v[132:135], v[198:201], v[84:87]
	v_mfma_f32_16x16x32_bf16 v[76:79], v[158:161], v[198:201], v[76:79]
	s_barrier
	s_setprio 0
	s_add_i32 s10, 0, 0x1c000
	s_add_i32 s11, s53, s41
	v_add_u32_e32 v177, s10, v171
	s_mov_b32 m0, s11
	ds_read_b128 v[202:205], v177
	ds_read_b128 v[206:209], v177 offset:1024
	ds_read_b128 v[212:215], v177 offset:2048
	ds_read_b128 v[216:219], v177 offset:3072
	global_load_lds_dwordx4 v140, s[98:99]
	s_add_i32 m0, s11, 0x2000
	s_nop 0
	global_load_lds_dwordx4 v136, s[98:99]
	s_setprio 1
	s_barrier
	s_waitcnt lgkmcnt(0)
	v_mfma_f32_16x16x32_bf16 v[116:119], v[202:205], v[162:165], v[116:119]
	v_mfma_f32_16x16x32_bf16 v[112:115], v[212:215], v[162:165], v[112:115]
	v_mfma_f32_16x16x32_bf16 v[96:99], v[202:205], v[178:181], v[96:99]
	v_mfma_f32_16x16x32_bf16 v[88:91], v[212:215], v[178:181], v[88:91]
	v_mfma_f32_16x16x32_bf16 v[80:83], v[202:205], v[186:189], v[80:83]
	v_mfma_f32_16x16x32_bf16 v[72:75], v[212:215], v[186:189], v[72:75]
	v_mfma_f32_16x16x32_bf16 v[68:71], v[202:205], v[194:197], v[68:71]
	v_mfma_f32_16x16x32_bf16 v[64:67], v[212:215], v[194:197], v[64:67]
	v_mfma_f32_16x16x32_bf16 v[116:119], v[206:209], v[166:169], v[116:119]
	v_mfma_f32_16x16x32_bf16 v[112:115], v[216:219], v[166:169], v[112:115]
	v_mfma_f32_16x16x32_bf16 v[96:99], v[206:209], v[182:185], v[96:99]
	v_mfma_f32_16x16x32_bf16 v[88:91], v[216:219], v[182:185], v[88:91]
	v_mfma_f32_16x16x32_bf16 v[80:83], v[206:209], v[190:193], v[80:83]
	v_mfma_f32_16x16x32_bf16 v[72:75], v[216:219], v[190:193], v[72:75]
	v_mfma_f32_16x16x32_bf16 v[68:71], v[206:209], v[198:201], v[68:71]
	v_mfma_f32_16x16x32_bf16 v[64:67], v[216:219], v[198:201], v[64:67]
	s_barrier
	s_setprio 0
	s_mov_b32 m0, s56
	ds_read_b128 v[162:165], v174 offset:49152
	ds_read_b128 v[166:169], v174 offset:50176
	ds_read_b128 v[178:181], v174 offset:51200
	ds_read_b128 v[182:185], v174 offset:52224
	ds_read_b128 v[186:189], v174 offset:53248
	ds_read_b128 v[190:193], v174 offset:54272
	ds_read_b128 v[194:197], v174 offset:55296
	ds_read_b128 v[198:201], v174 offset:56320
	global_load_lds_dwordx4 v142, s[100:101]
	s_mov_b32 m0, s57
	s_nop 0
	global_load_lds_dwordx4 v138, s[100:101]
	s_waitcnt vmcnt(10)
	s_setprio 1
	s_barrier
	s_waitcnt lgkmcnt(0)
	v_mfma_f32_16x16x32_bf16 v[60:63], v[128:131], v[162:165], v[60:63]
	v_mfma_f32_16x16x32_bf16 v[56:59], v[154:157], v[162:165], v[56:59]
	v_mfma_f32_16x16x32_bf16 v[52:55], v[128:131], v[178:181], v[52:55]
	v_mfma_f32_16x16x32_bf16 v[44:47], v[154:157], v[178:181], v[44:47]
	v_mfma_f32_16x16x32_bf16 v[36:39], v[128:131], v[186:189], v[36:39]
	v_mfma_f32_16x16x32_bf16 v[28:31], v[154:157], v[186:189], v[28:31]
	v_mfma_f32_16x16x32_bf16 v[20:23], v[128:131], v[194:197], v[20:23]
	v_mfma_f32_16x16x32_bf16 v[12:15], v[154:157], v[194:197], v[12:15]
	v_mfma_f32_16x16x32_bf16 v[60:63], v[132:135], v[166:169], v[60:63]
	v_mfma_f32_16x16x32_bf16 v[56:59], v[158:161], v[166:169], v[56:59]
	v_mfma_f32_16x16x32_bf16 v[52:55], v[132:135], v[182:185], v[52:55]
	v_mfma_f32_16x16x32_bf16 v[44:47], v[158:161], v[182:185], v[44:47]
	v_mfma_f32_16x16x32_bf16 v[36:39], v[132:135], v[190:193], v[36:39]
	v_mfma_f32_16x16x32_bf16 v[28:31], v[158:161], v[190:193], v[28:31]
	v_mfma_f32_16x16x32_bf16 v[20:23], v[132:135], v[198:201], v[20:23]
	v_mfma_f32_16x16x32_bf16 v[12:15], v[158:161], v[198:201], v[12:15]
	s_barrier
; #define PG8_STAGE(bufoff, gbase, voff) do { _Pragma("unroll") for (int _i = 0; _i < 2; ++_i) \
;     __builtin_amdgcn_global_load_lds((const unsigned*)((const char*)(gbase) + (voff)[_i]), (LAS unsigned*)(lds + (bufoff) + ldsw + _i * 8192), 16, 0, 0); } while (0)
; #define PG8_MMA(ai, bj, At, Bt) do { __builtin_amdgcn_s_setprio(1); _Pragma("unroll") for (int m = 0; m < 4; ++m) _Pragma("unroll") for (int n = 0; n < 2; ++n) _Pragma("unroll") for (int k = 0; k < 2; ++k) \
;     acc[ai][bj][m][n] = __builtin_amdgcn_mfma_f32_16x16x32_bf16(Bt[n][k], At[m][k], acc[ai][bj][m][n], 0, 0, 0); __builtin_amdgcn_s_setprio(0); } while (0)
; #define PG8_WAIT_V(n) asm volatile("s_waitcnt vmcnt(" #n ")" ::: "memory")
; #define PG8_BAR __builtin_amdgcn_s_barrier()
; DI float row_rstd(const float* ssq, int row, int fq) {
;   const f32x4 a = *(const f32x4*)(ssq + (size_t)row * 32 + fq * 8), b = *(const f32x4*)(ssq + (size_t)row * 32 + fq * 8 + 4);
;   float sm = ((a[0] + a[1]) + (a[2] + a[3])) + ((b[0] + b[1]) + (b[2] + b[3]));
;   sm += __shfl_xor(sm, 16); sm += __shfl_xor(sm, 32);
;   return rsqrtf(sm * (1.0f / 2048.f) + 1e-6f);
;   DI void operator()(const f32x4 (&acc)[2][2][4][2], const Unit& u, int wr, int wc, int fr, int fq) const {
;     const int row0 = u.pm * BM + wr * 64 + fr, col0 = u.pn * BM + wc * 32 + 8 * fq;
;     float rsv[2][4];
; #pragma unroll
;     for (int ai = 0; ai < 2; ++ai)
; #pragma unroll
;       for (int m = 0; m < 4; ++m) rsv[ai][m] = row_rstd(ssq, row0 + ai * HALF + m * 16, fq);
; template <class Epi, class Sched = StaticOrder>
; DI void gemm_phase(LAS unsigned char* lds, const Gemm g, const Sched& S, const Epi& E) {
;     ...
;       PG8_STAGE(PG8_SB(1, 1), b3 + hstep, voffB);
;       PG8_WAIT_V(6); PG8_BAR; PG8_MMA(1, 1, At, B1); PG8_BAR;
;     }
;     E(acc, cur, wr, wc, fr, fq);
	s_setprio 0
	s_add_u32 s8, s8, 0x80080
	s_addc_u32 s9, s9, 0
	s_add_i32 s10, s10, s41
	s_mov_b32 m0, s10
	s_nop 0
	global_load_lds_dwordx4 v140, s[8:9]
	s_add_i32 m0, s10, 0x2000
	s_nop 0
	global_load_lds_dwordx4 v136, s[8:9]
	ds_read_b128 v[128:131], v173
	ds_read_b128 v[132:135], v173 offset:1024
	ds_read_b128 v[154:157], v173 offset:2048
	ds_read_b128 v[158:161], v173 offset:3072
	s_waitcnt vmcnt(6)
	s_setprio 1
	s_barrier
	v_mfma_f32_16x16x32_bf16 v[48:51], v[202:205], v[162:165], v[48:51]
	v_mfma_f32_16x16x32_bf16 v[40:43], v[212:215], v[162:165], v[40:43]
	v_mfma_f32_16x16x32_bf16 v[32:35], v[202:205], v[178:181], v[32:35]
	v_mfma_f32_16x16x32_bf16 v[24:27], v[212:215], v[178:181], v[24:27]
	v_mfma_f32_16x16x32_bf16 v[16:19], v[202:205], v[186:189], v[16:19]
	v_mfma_f32_16x16x32_bf16 v[8:11], v[212:215], v[186:189], v[8:11]
	v_mfma_f32_16x16x32_bf16 v[4:7], v[202:205], v[194:197], v[4:7]
	v_mfma_f32_16x16x32_bf16 v[0:3], v[212:215], v[194:197], v[0:3]
	v_mfma_f32_16x16x32_bf16 v[48:51], v[206:209], v[166:169], v[48:51]
	v_mfma_f32_16x16x32_bf16 v[40:43], v[216:219], v[166:169], v[40:43]
	v_mfma_f32_16x16x32_bf16 v[32:35], v[206:209], v[182:185], v[32:35]
	v_mfma_f32_16x16x32_bf16 v[24:27], v[216:219], v[182:185], v[24:27]
	v_mfma_f32_16x16x32_bf16 v[16:19], v[206:209], v[190:193], v[16:19]
	v_mfma_f32_16x16x32_bf16 v[8:11], v[216:219], v[190:193], v[8:11]
	v_mfma_f32_16x16x32_bf16 v[4:7], v[206:209], v[198:201], v[4:7]
	v_mfma_f32_16x16x32_bf16 v[0:3], v[216:219], v[198:201], v[0:3]
	s_add_i32 s52, s52, 2
	s_add_u32 s6, s6, 0x100
	s_addc_u32 s7, s7, 0
	s_add_u32 s44, s44, 0x100
	s_addc_u32 s45, s45, 0
	s_cmp_gt_u32 s52, 29
	s_barrier
	s_setprio 0
	s_cbranch_scc0 .LBB0_346
	s_waitcnt lgkmcnt(0)
	v_lshl_add_u32 v168, s4, 8, v170
	v_ashrrev_i32_e32 v169, 31, v168
	v_or_b32_e32 v154, 16, v168
	v_lshlrev_b64 v[128:129], 7, v[168:169]
	v_ashrrev_i32_e32 v155, 31, v154
	v_lshl_add_u64 v[128:129], v[144:145], 0, v[128:129]
	v_lshlrev_b64 v[156:157], 7, v[154:155]
	global_load_dwordx4 v[132:135], v[128:129], off
	s_nop 0
	global_load_dwordx4 v[128:131], v[128:129], off offset:16
	v_lshl_add_u64 v[156:157], v[144:145], 0, v[156:157]
	global_load_dwordx4 v[178:181], v[156:157], off
	global_load_dwordx4 v[182:185], v[156:157], off offset:16
	v_or_b32_e32 v160, 32, v168
	v_ashrrev_i32_e32 v161, 31, v160
	v_lshlrev_b64 v[156:157], 7, v[160:161]
	v_lshl_add_u64 v[156:157], v[144:145], 0, v[156:157]
	global_load_dwordx4 v[186:189], v[156:157], off
	global_load_dwordx4 v[190:193], v[156:157], off offset:16
	v_or_b32_e32 v156, 48, v168
	v_ashrrev_i32_e32 v157, 31, v156
	v_lshlrev_b64 v[158:159], 7, v[156:157]
	v_lshl_add_u64 v[158:159], v[144:145], 0, v[158:159]
	global_load_dwordx4 v[194:197], v[158:159], off
	global_load_dwordx4 v[198:201], v[158:159], off offset:16
	v_add_u32_e32 v164, 0x80, v168
	v_ashrrev_i32_e32 v165, 31, v164
	v_lshlrev_b64 v[158:159], 7, v[164:165]
	v_lshl_add_u64 v[158:159], v[144:145], 0, v[158:159]
	global_load_dwordx4 v[202:205], v[158:159], off
	global_load_dwordx4 v[206:209], v[158:159], off offset:16
	v_add_u32_e32 v158, 0x90, v168
	v_ashrrev_i32_e32 v159, 31, v158
	v_lshlrev_b64 v[162:163], 7, v[158:159]
	v_lshl_add_u64 v[162:163], v[144:145], 0, v[162:163]
	global_load_dwordx4 v[212:215], v[162:163], off
	global_load_dwordx4 v[216:219], v[162:163], off offset:16
	v_add_u32_e32 v166, 0xa0, v168
	v_ashrrev_i32_e32 v167, 31, v166
	v_lshlrev_b64 v[162:163], 7, v[166:167]
	v_lshl_add_u64 v[162:163], v[144:145], 0, v[162:163]
	global_load_dwordx4 v[220:223], v[162:163], off
	global_load_dwordx4 v[224:227], v[162:163], off offset:16
	v_add_u32_e32 v162, 0xb0, v168
	v_ashrrev_i32_e32 v163, 31, v162
	v_lshlrev_b64 v[228:229], 7, v[162:163]
	v_lshl_add_u64 v[232:233], v[144:145], 0, v[228:229]
	global_load_dwordx4 v[228:231], v[232:233], off
	s_nop 0
	global_load_dwordx4 v[232:235], v[232:233], off offset:16
	s_waitcnt vmcnt(0)
	v_mov_b32_e32 v236, v132
	v_mov_b32_e32 v237, v128
	v_mov_b32_e32 v128, v133
	v_mov_b32_e32 v132, v134
	v_mov_b32_e32 v133, v130
	v_mov_b32_e32 v130, v135
	v_pk_add_f32 v[130:131], v[132:133], v[130:131]
	v_mov_b32_e32 v132, v178
	v_mov_b32_e32 v133, v182
	v_mov_b32_e32 v182, v179
	v_mov_b32_e32 v134, v180
	v_mov_b32_e32 v135, v184
	v_mov_b32_e32 v184, v181
	v_pk_add_f32 v[128:129], v[236:237], v[128:129]
	v_pk_add_f32 v[132:133], v[132:133], v[182:183]
	v_pk_add_f32 v[134:135], v[134:135], v[184:185]
	v_pk_add_f32 v[128:129], v[128:129], v[130:131]
	v_pk_add_f32 v[130:131], v[132:133], v[134:135]
	v_mov_b32_e32 v133, v128
	v_mov_b32_e32 v132, v130
	v_and_b32_e32 v130, 64, v176
	v_add_u32_e32 v155, 64, v130
	v_xor_b32_e32 v130, 16, v176
	v_cmp_lt_i32_e32 vcc, v130, v155
	v_mov_b32_e32 v128, v131
	v_pk_add_f32 v[128:129], v[132:133], v[128:129]
	v_cndmask_b32_e32 v130, v176, v130, vcc
	v_lshlrev_b32_e32 v157, 2, v130
	ds_bpermute_b32 v131, v157, v129
	ds_bpermute_b32 v130, v157, v128
	v_mov_b32_e32 v178, v186
	v_mov_b32_e32 v179, v190
	v_mov_b32_e32 v190, v187
	v_mov_b32_e32 v186, v194
	s_waitcnt lgkmcnt(0)
	v_pk_add_f32 v[128:129], v[128:129], v[130:131]
	v_xor_b32_e32 v130, 32, v176
	v_cmp_lt_i32_e32 vcc, v130, v155
	v_mov_b32_e32 v187, v198
	v_mov_b32_e32 v198, v195
	v_cndmask_b32_e32 v130, v176, v130, vcc
	v_lshlrev_b32_e32 v155, 2, v130
	ds_bpermute_b32 v131, v155, v129
	ds_bpermute_b32 v130, v155, v128
	v_pk_add_f32 v[182:183], v[186:187], v[198:199]
	v_mov_b32_e32 v180, v188
	v_mov_b32_e32 v181, v192
	v_mov_b32_e32 v192, v189
	s_waitcnt lgkmcnt(0)
; DI unsigned pack2(float lo, float hi) { f32x2 v = {lo, hi}; bf16v2 r = __builtin_convertvector(v, bf16v2); return __builtin_bit_cast(unsigned, r); }
; DI float row_rstd(const float* ssq, int row, int fq) {
;   const f32x4 a = *(const f32x4*)(ssq + (size_t)row * 32 + fq * 8), b = *(const f32x4*)(ssq + (size_t)row * 32 + fq * 8 + 4);
;   float sm = ((a[0] + a[1]) + (a[2] + a[3])) + ((b[0] + b[1]) + (b[2] + b[3]));
;   sm += __shfl_xor(sm, 16); sm += __shfl_xor(sm, 32);
;   return rsqrtf(sm * (1.0f / 2048.f) + 1e-6f);
;   DI void operator()(const f32x4 (&acc)[2][2][4][2], const Unit& u, int wr, int wc, int fr, int fq) const {
;     ...
;     for (int ai = 0; ai < 2; ++ai)
; #pragma unroll
;       for (int m = 0; m < 4; ++m) {
;         const int row = row0 + ai * HALF + m * 16;
;         const float rs = rsv[ai][m];
;         bf16_t* rowp = O + (size_t)row * ldc + col0;
; #pragma unroll
;         for (int bj = 0; bj < 2; ++bj) {
;           const f32x4 v0 = acc[ai][bj][m][0] * rs, v1 = acc[ai][bj][m][1] * rs;
;           u32x4 w; w.x = pack2(v0[0], v0[1]); w.y = pack2(v0[2], v0[3]); w.z = pack2(v1[0], v1[1]); w.w = pack2(v1[2], v1[3]);
;           *(u32x4*)(rowp + bj * HALF) = w;
;         }
	v_pk_add_f32 v[128:129], v[128:129], v[130:131]
	v_mov_b64_e32 v[130:131], s[26:27]
	v_pk_fma_f32 v[128:129], v[128:129], s[24:25], v[130:131] op_sel_hi:[1,0,0]
	v_mov_b32_e32 v188, v196
	v_mul_f32_e32 v159, 0x4b800000, v129
	v_cmp_gt_f32_e32 vcc, s73, v129
	v_mov_b32_e32 v189, v200
	v_mov_b32_e32 v200, v197
	v_cndmask_b32_e32 v129, v129, v159, vcc
	v_rsq_f32_e32 v129, v129
	v_pk_add_f32 v[178:179], v[178:179], v[190:191]
	v_pk_add_f32 v[180:181], v[180:181], v[192:193]
	v_pk_add_f32 v[184:185], v[188:189], v[200:201]
	v_mul_f32_e32 v159, 0x45800000, v129
	v_cndmask_b32_e32 v198, v129, v159, vcc
	v_pk_mul_f32 v[126:127], v[126:127], v[198:199] op_sel_hi:[1,0]
	v_pk_mul_f32 v[124:125], v[124:125], v[198:199] op_sel_hi:[1,0]
	v_pk_mul_f32 v[122:123], v[122:123], v[198:199] op_sel_hi:[1,0]
	v_pk_mul_f32 v[120:121], v[120:121], v[198:199] op_sel_hi:[1,0]
	v_cvt_pk_bf16_f32 v124, v124, v125
	v_cvt_pk_bf16_f32 v125, v126, v127
	v_cvt_pk_bf16_f32 v127, v122, v123
	v_lshl_or_b32 v122, s5, 8, v172
	v_cvt_pk_bf16_f32 v126, v120, v121
	v_ashrrev_i32_e32 v123, 31, v122
	v_mov_b64_e32 v[120:121], s[2:3]
	v_mad_i64_i32 v[168:169], s[4:5], v168, s76, v[120:121]
	v_lshlrev_b64 v[122:123], 1, v[122:123]
	v_lshl_add_u64 v[168:169], v[168:169], 0, v[122:123]
	global_store_dwordx4 v[168:169], v[124:127], off
	v_mov_b32_e32 v194, v202
	v_mov_b32_e32 v195, v206
	v_pk_add_f32 v[124:125], v[178:179], v[180:181]
	v_pk_add_f32 v[126:127], v[182:183], v[184:185]
	v_mov_b32_e32 v179, v124
	v_mov_b32_e32 v178, v126
	v_mov_b32_e32 v124, v127
	v_pk_add_f32 v[124:125], v[178:179], v[124:125]
	ds_bpermute_b32 v127, v157, v125
	ds_bpermute_b32 v126, v157, v124
	v_mov_b32_e32 v206, v203
	v_mov_b32_e32 v196, v204
	v_mov_b32_e32 v197, v208
	v_mov_b32_e32 v208, v205
	v_mov_b32_e32 v202, v212
	v_mov_b32_e32 v203, v216
	v_mov_b32_e32 v216, v213
	v_mov_b32_e32 v204, v214
	v_mov_b32_e32 v205, v218
	v_mov_b32_e32 v218, v215
	v_pk_add_f32 v[186:187], v[194:195], v[206:207]
	v_pk_add_f32 v[188:189], v[196:197], v[208:209]
	v_pk_add_f32 v[190:191], v[202:203], v[216:217]
	v_pk_add_f32 v[192:193], v[204:205], v[218:219]
	v_pk_mul_f32 v[178:179], v[114:115], v[198:199] op_sel_hi:[1,0]
	s_waitcnt lgkmcnt(0)
	v_pk_add_f32 v[114:115], v[124:125], v[126:127]
	v_pk_add_f32 v[126:127], v[186:187], v[188:189]
	v_pk_add_f32 v[180:181], v[190:191], v[192:193]
	v_mov_b32_e32 v183, v126
	v_mov_b32_e32 v182, v180
	v_mov_b32_e32 v126, v181
	v_pk_add_f32 v[126:127], v[182:183], v[126:127]
	ds_bpermute_b32 v125, v155, v115
	ds_bpermute_b32 v124, v155, v114
	ds_bpermute_b32 v181, v157, v127
	ds_bpermute_b32 v180, v157, v126
	v_mul_f32_e32 v129, 0x4b800000, v128
	v_cmp_gt_f32_e32 vcc, s73, v128
	s_waitcnt lgkmcnt(2)
	v_pk_add_f32 v[114:115], v[114:115], v[124:125]
	v_mov_b32_e32 v194, v220
	s_waitcnt lgkmcnt(0)
	v_pk_add_f32 v[124:125], v[126:127], v[180:181]
	ds_bpermute_b32 v127, v155, v125
	ds_bpermute_b32 v126, v155, v124
	v_pk_fma_f32 v[114:115], v[114:115], s[24:25], v[130:131] op_sel_hi:[1,0,0]
	v_cndmask_b32_e32 v159, v128, v129, vcc
	v_mul_f32_e32 v128, 0x4b800000, v115
	v_cmp_gt_f32_e64 s[4:5], s73, v115
	v_cmp_gt_f32_e64 s[6:7], s73, v114
	v_mov_b32_e32 v195, v224
	v_cndmask_b32_e64 v161, v115, v128, s[4:5]
	v_mul_f32_e32 v115, 0x4b800000, v114
	v_mov_b32_e32 v224, v221
	v_mov_b32_e32 v196, v222
	v_mov_b32_e32 v197, v226
	v_mov_b32_e32 v226, v223
	v_cndmask_b32_e64 v163, v114, v115, s[6:7]
	s_waitcnt lgkmcnt(0)
	v_pk_add_f32 v[114:115], v[124:125], v[126:127]
	v_pk_add_f32 v[132:133], v[194:195], v[224:225]
	v_pk_add_f32 v[134:135], v[196:197], v[226:227]
	v_mov_b32_e32 v194, v228
	v_mov_b32_e32 v195, v232
	v_mov_b32_e32 v232, v229
	v_mov_b32_e32 v196, v230
	v_mov_b32_e32 v197, v234
	v_mov_b32_e32 v234, v231
	v_pk_fma_f32 v[114:115], v[114:115], s[24:25], v[130:131] op_sel_hi:[1,0,0]
	v_pk_add_f32 v[194:195], v[194:195], v[232:233]
	v_pk_add_f32 v[196:197], v[196:197], v[234:235]
	v_mul_f32_e32 v124, 0x4b800000, v115
	v_cmp_gt_f32_e64 s[8:9], s73, v115
	v_pk_add_f32 v[126:127], v[194:195], v[196:197]
	v_cmp_gt_f32_e64 s[10:11], s73, v114
	v_cndmask_b32_e64 v165, v115, v124, s[8:9]
	v_pk_add_f32 v[124:125], v[132:133], v[134:135]
	v_mov_b32_e32 v128, v126
	v_mov_b32_e32 v129, v124
	v_mov_b32_e32 v124, v127
	v_pk_add_f32 v[124:125], v[128:129], v[124:125]
	ds_bpermute_b32 v127, v157, v125
	ds_bpermute_b32 v126, v157, v124
	v_rsq_f32_e32 v128, v159
	v_mul_f32_e32 v115, 0x4b800000, v114
	v_cndmask_b32_e64 v129, v114, v115, s[10:11]
	v_pk_mul_f32 v[116:117], v[116:117], v[198:199] op_sel_hi:[1,0]
	s_waitcnt lgkmcnt(0)
	v_pk_add_f32 v[114:115], v[124:125], v[126:127]
	ds_bpermute_b32 v125, v155, v115
	ds_bpermute_b32 v124, v155, v114
	v_mul_f32_e32 v126, 0x45800000, v128
	v_rsq_f32_e32 v127, v161
	v_cndmask_b32_e32 v126, v128, v126, vcc
	v_rsq_f32_e32 v128, v163
	s_waitcnt lgkmcnt(0)
; DI unsigned pack2(float lo, float hi) { f32x2 v = {lo, hi}; bf16v2 r = __builtin_convertvector(v, bf16v2); return __builtin_bit_cast(unsigned, r); }
;   DI void operator()(const f32x4 (&acc)[2][2][4][2], const Unit& u, int wr, int wc, int fr, int fq) const {
;     ...
;     for (int ai = 0; ai < 2; ++ai)
; #pragma unroll
;       for (int m = 0; m < 4; ++m) {
;         const int row = row0 + ai * HALF + m * 16;
;         const float rs = rsv[ai][m];
;         bf16_t* rowp = O + (size_t)row * ldc + col0;
; #pragma unroll
;         for (int bj = 0; bj < 2; ++bj) {
;           const f32x4 v0 = acc[ai][bj][m][0] * rs, v1 = acc[ai][bj][m][1] * rs;
;           u32x4 w; w.x = pack2(v0[0], v0[1]); w.y = pack2(v0[2], v0[3]); w.z = pack2(v1[0], v1[1]); w.w = pack2(v1[2], v1[3]);
;           *(u32x4*)(rowp + bj * HALF) = w;
;         }
	v_pk_add_f32 v[114:115], v[114:115], v[124:125]
	v_mul_f32_e32 v124, 0x45800000, v127
	v_cndmask_b32_e64 v124, v127, v124, s[4:5]
	v_mul_f32_e32 v127, 0x45800000, v128
	v_pk_fma_f32 v[114:115], v[114:115], s[24:25], v[130:131] op_sel_hi:[1,0,0]
	v_rsq_f32_e32 v125, v165
	v_cndmask_b32_e64 v128, v128, v127, s[6:7]
	v_rsq_f32_e32 v127, v129
	v_mul_f32_e32 v129, 0x4b800000, v115
	v_cmp_gt_f32_e32 vcc, s73, v115
	v_cmp_gt_f32_e64 s[4:5], s73, v114
	v_pk_mul_f32 v[118:119], v[118:119], v[198:199] op_sel_hi:[1,0]
	v_cndmask_b32_e32 v129, v115, v129, vcc
	v_mul_f32_e32 v115, 0x4b800000, v114
	v_cndmask_b32_e64 v131, v114, v115, s[4:5]
	v_cvt_pk_bf16_f32 v114, v116, v117
	v_rsq_f32_e32 v117, v129
	v_cvt_pk_bf16_f32 v115, v118, v119
	v_rsq_f32_e32 v119, v131
	v_mul_f32_e32 v116, 0x45800000, v125
	v_pk_mul_f32 v[112:113], v[112:113], v[198:199] op_sel_hi:[1,0]
	v_cndmask_b32_e64 v118, v125, v116, s[8:9]
	v_mul_f32_e32 v116, 0x45800000, v127
	v_cndmask_b32_e64 v130, v127, v116, s[10:11]
	v_cvt_pk_bf16_f32 v116, v112, v113
	v_mul_f32_e32 v112, 0x45800000, v117
	v_cndmask_b32_e32 v132, v117, v112, vcc
	v_mul_f32_e32 v112, 0x45800000, v119
	v_cvt_pk_bf16_f32 v117, v178, v179
	v_cndmask_b32_e64 v112, v119, v112, s[4:5]
	global_store_dwordx4 v[168:169], v[114:117], off offset:256
	v_pk_mul_f32 v[110:111], v[110:111], v[126:127] op_sel_hi:[1,0]
	v_pk_mul_f32 v[108:109], v[108:109], v[126:127] op_sel_hi:[1,0]
	v_mad_i64_i32 v[114:115], s[4:5], v154, s76, v[120:121]
	v_pk_mul_f32 v[116:117], v[106:107], v[126:127] op_sel_hi:[1,0]
	v_pk_mul_f32 v[106:107], v[104:105], v[126:127] op_sel_hi:[1,0]
	v_lshl_add_u64 v[114:115], v[114:115], 0, v[122:123]
	v_cvt_pk_bf16_f32 v104, v108, v109
	v_cvt_pk_bf16_f32 v105, v110, v111
	v_cvt_pk_bf16_f32 v106, v106, v107
	v_cvt_pk_bf16_f32 v107, v116, v117
	global_store_dwordx4 v[114:115], v[104:107], off
	v_pk_mul_f32 v[98:99], v[98:99], v[126:127] op_sel_hi:[1,0]
	v_pk_mul_f32 v[96:97], v[96:97], v[126:127] op_sel_hi:[1,0]
	v_pk_mul_f32 v[104:105], v[90:91], v[126:127] op_sel_hi:[1,0]
	v_pk_mul_f32 v[90:91], v[88:89], v[126:127] op_sel_hi:[1,0]
	v_cvt_pk_bf16_f32 v88, v96, v97
	v_cvt_pk_bf16_f32 v89, v98, v99
	v_cvt_pk_bf16_f32 v90, v90, v91
	v_cvt_pk_bf16_f32 v91, v104, v105
	global_store_dwordx4 v[114:115], v[88:91], off offset:256
	v_pk_mul_f32 v[94:95], v[94:95], v[124:125] op_sel_hi:[1,0]
	v_pk_mul_f32 v[92:93], v[92:93], v[124:125] op_sel_hi:[1,0]
	v_mad_i64_i32 v[88:89], s[4:5], v160, s76, v[120:121]
	v_lshl_add_u64 v[96:97], v[88:89], 0, v[122:123]
	v_pk_mul_f32 v[90:91], v[102:103], v[124:125] op_sel_hi:[1,0]
	v_pk_mul_f32 v[88:89], v[100:101], v[124:125] op_sel_hi:[1,0]
	v_pk_mul_f32 v[82:83], v[82:83], v[124:125] op_sel_hi:[1,0]
	v_cvt_pk_bf16_f32 v88, v88, v89
	v_cvt_pk_bf16_f32 v89, v90, v91
	v_cvt_pk_bf16_f32 v90, v92, v93
	v_cvt_pk_bf16_f32 v91, v94, v95
	global_store_dwordx4 v[96:97], v[88:91], off
	v_pk_mul_f32 v[80:81], v[80:81], v[124:125] op_sel_hi:[1,0]
	v_pk_mul_f32 v[78:79], v[78:79], v[128:129] op_sel_hi:[1,0]
	v_pk_mul_f32 v[88:89], v[74:75], v[124:125] op_sel_hi:[1,0]
	v_pk_mul_f32 v[74:75], v[72:73], v[124:125] op_sel_hi:[1,0]
	v_cvt_pk_bf16_f32 v72, v80, v81
	v_cvt_pk_bf16_f32 v73, v82, v83
	v_cvt_pk_bf16_f32 v74, v74, v75
	v_cvt_pk_bf16_f32 v75, v88, v89
	global_store_dwordx4 v[96:97], v[72:75], off offset:256
	v_pk_mul_f32 v[76:77], v[76:77], v[128:129] op_sel_hi:[1,0]
	v_pk_mul_f32 v[70:71], v[70:71], v[128:129] op_sel_hi:[1,0]
	v_mad_i64_i32 v[72:73], s[4:5], v156, s76, v[120:121]
	v_lshl_add_u64 v[80:81], v[72:73], 0, v[122:123]
	v_pk_mul_f32 v[74:75], v[86:87], v[128:129] op_sel_hi:[1,0]
	v_pk_mul_f32 v[72:73], v[84:85], v[128:129] op_sel_hi:[1,0]
	v_pk_mul_f32 v[68:69], v[68:69], v[128:129] op_sel_hi:[1,0]
	v_cvt_pk_bf16_f32 v72, v72, v73
	v_cvt_pk_bf16_f32 v73, v74, v75
	v_cvt_pk_bf16_f32 v74, v76, v77
	v_cvt_pk_bf16_f32 v75, v78, v79
	global_store_dwordx4 v[80:81], v[72:75], off
	v_pk_mul_f32 v[62:63], v[62:63], v[118:119] op_sel_hi:[1,0]
	v_pk_mul_f32 v[60:61], v[60:61], v[118:119] op_sel_hi:[1,0]
	v_pk_mul_f32 v[72:73], v[66:67], v[128:129] op_sel_hi:[1,0]
	v_pk_mul_f32 v[66:67], v[64:65], v[128:129] op_sel_hi:[1,0]
; DI unsigned pack2(float lo, float hi) { f32x2 v = {lo, hi}; bf16v2 r = __builtin_convertvector(v, bf16v2); return __builtin_bit_cast(unsigned, r); }
; #define PG8_WAIT_V(n) asm volatile("s_waitcnt vmcnt(" #n ")" ::: "memory")
; #define PG8_BAR __builtin_amdgcn_s_barrier()
;   DI void operator()(const f32x4 (&acc)[2][2][4][2], const Unit& u, int wr, int wc, int fr, int fq) const {
;     ...
;     for (int ai = 0; ai < 2; ++ai)
; #pragma unroll
;       for (int m = 0; m < 4; ++m) {
;         const int row = row0 + ai * HALF + m * 16;
;         const float rs = rsv[ai][m];
;         bf16_t* rowp = O + (size_t)row * ldc + col0;
; #pragma unroll
;         for (int bj = 0; bj < 2; ++bj) {
;           const f32x4 v0 = acc[ai][bj][m][0] * rs, v1 = acc[ai][bj][m][1] * rs;
;           u32x4 w; w.x = pack2(v0[0], v0[1]); w.y = pack2(v0[2], v0[3]); w.z = pack2(v1[0], v1[1]); w.w = pack2(v1[2], v1[3]);
;           *(u32x4*)(rowp + bj * HALF) = w;
;         }
; template <class Epi, class Sched = StaticOrder>
; DI void gemm_phase(LAS unsigned char* lds, const Gemm g, const Sched& S, const Epi& E) {
;     ...
;     E(acc, cur, wr, wc, fr, fq);
;     if (!has_next) break;
; #pragma unroll
;     for (int a = 0; a < 2; ++a)
; #pragma unroll
;       for (int b = 0; b < 2; ++b)
; #pragma unroll
;         for (int m = 0; m < 4; ++m)
; #pragma unroll
;           for (int n = 0; n < 2; ++n) acc[a][b][m][n] = (f32x4){0.f, 0.f, 0.f, 0.f};
;     cur = nxt; cA = nA; cB = nB; ++ui;
;   }
;   PG8_WAIT_V(0);
;   if (wr == 0) PG8_BAR;
;   PG8_BAR;
	v_cvt_pk_bf16_f32 v64, v68, v69
	v_cvt_pk_bf16_f32 v65, v70, v71
	v_cvt_pk_bf16_f32 v66, v66, v67
	v_cvt_pk_bf16_f32 v67, v72, v73
	global_store_dwordx4 v[80:81], v[64:67], off offset:256
	v_pk_mul_f32 v[50:51], v[50:51], v[118:119] op_sel_hi:[1,0]
	v_pk_mul_f32 v[48:49], v[48:49], v[118:119] op_sel_hi:[1,0]
	v_mad_i64_i32 v[64:65], s[4:5], v164, s76, v[120:121]
	v_pk_mul_f32 v[66:67], v[58:59], v[118:119] op_sel_hi:[1,0]
	v_pk_mul_f32 v[58:59], v[56:57], v[118:119] op_sel_hi:[1,0]
	v_lshl_add_u64 v[64:65], v[64:65], 0, v[122:123]
	v_cvt_pk_bf16_f32 v56, v60, v61
	v_cvt_pk_bf16_f32 v57, v62, v63
	v_cvt_pk_bf16_f32 v58, v58, v59
	v_cvt_pk_bf16_f32 v59, v66, v67
	global_store_dwordx4 v[64:65], v[56:59], off
	v_pk_mul_f32 v[46:47], v[46:47], v[130:131] op_sel_hi:[1,0]
	v_pk_mul_f32 v[44:45], v[44:45], v[130:131] op_sel_hi:[1,0]
	v_pk_mul_f32 v[56:57], v[42:43], v[118:119] op_sel_hi:[1,0]
	v_pk_mul_f32 v[42:43], v[40:41], v[118:119] op_sel_hi:[1,0]
	v_cvt_pk_bf16_f32 v40, v48, v49
	v_cvt_pk_bf16_f32 v41, v50, v51
	v_cvt_pk_bf16_f32 v42, v42, v43
	v_cvt_pk_bf16_f32 v43, v56, v57
	global_store_dwordx4 v[64:65], v[40:43], off offset:256
	v_pk_mul_f32 v[34:35], v[34:35], v[130:131] op_sel_hi:[1,0]
	v_pk_mul_f32 v[32:33], v[32:33], v[130:131] op_sel_hi:[1,0]
	v_mad_i64_i32 v[40:41], s[4:5], v158, s76, v[120:121]
	v_lshl_add_u64 v[48:49], v[40:41], 0, v[122:123]
	v_pk_mul_f32 v[42:43], v[54:55], v[130:131] op_sel_hi:[1,0]
	v_pk_mul_f32 v[40:41], v[52:53], v[130:131] op_sel_hi:[1,0]
	v_pk_mul_f32 v[30:31], v[30:31], v[132:133] op_sel_hi:[1,0]
	v_cvt_pk_bf16_f32 v40, v40, v41
	v_cvt_pk_bf16_f32 v41, v42, v43
	v_cvt_pk_bf16_f32 v42, v44, v45
	v_cvt_pk_bf16_f32 v43, v46, v47
	global_store_dwordx4 v[48:49], v[40:43], off
	v_pk_mul_f32 v[28:29], v[28:29], v[132:133] op_sel_hi:[1,0]
	v_pk_mul_f32 v[18:19], v[18:19], v[132:133] op_sel_hi:[1,0]
	v_pk_mul_f32 v[40:41], v[26:27], v[130:131] op_sel_hi:[1,0]
	v_pk_mul_f32 v[26:27], v[24:25], v[130:131] op_sel_hi:[1,0]
	v_cvt_pk_bf16_f32 v24, v32, v33
	v_cvt_pk_bf16_f32 v25, v34, v35
	v_cvt_pk_bf16_f32 v26, v26, v27
	v_cvt_pk_bf16_f32 v27, v40, v41
	global_store_dwordx4 v[48:49], v[24:27], off offset:256
	v_pk_mul_f32 v[16:17], v[16:17], v[132:133] op_sel_hi:[1,0]
	v_pk_mul_f32 v[14:15], v[14:15], v[112:113] op_sel_hi:[1,0]
	v_mad_i64_i32 v[24:25], s[4:5], v166, s76, v[120:121]
	v_lshl_add_u64 v[32:33], v[24:25], 0, v[122:123]
	v_pk_mul_f32 v[26:27], v[38:39], v[132:133] op_sel_hi:[1,0]
	v_pk_mul_f32 v[24:25], v[36:37], v[132:133] op_sel_hi:[1,0]
	v_pk_mul_f32 v[12:13], v[12:13], v[112:113] op_sel_hi:[1,0]
	v_cvt_pk_bf16_f32 v24, v24, v25
	v_cvt_pk_bf16_f32 v25, v26, v27
	v_cvt_pk_bf16_f32 v26, v28, v29
	v_cvt_pk_bf16_f32 v27, v30, v31
	global_store_dwordx4 v[32:33], v[24:27], off
	v_pk_mul_f32 v[6:7], v[6:7], v[112:113] op_sel_hi:[1,0]
	v_pk_mul_f32 v[4:5], v[4:5], v[112:113] op_sel_hi:[1,0]
	v_pk_mul_f32 v[24:25], v[10:11], v[132:133] op_sel_hi:[1,0]
	v_pk_mul_f32 v[10:11], v[8:9], v[132:133] op_sel_hi:[1,0]
	v_cvt_pk_bf16_f32 v8, v16, v17
	v_cvt_pk_bf16_f32 v9, v18, v19
	v_cvt_pk_bf16_f32 v10, v10, v11
	v_cvt_pk_bf16_f32 v11, v24, v25
	global_store_dwordx4 v[32:33], v[8:11], off offset:256
	s_and_b64 vcc, exec, s[0:1]
	s_mov_b64 s[8:9], s[36:37]
	v_mad_i64_i32 v[8:9], s[4:5], v162, s76, v[120:121]
	v_lshl_add_u64 v[16:17], v[8:9], 0, v[122:123]
	v_pk_mul_f32 v[10:11], v[22:23], v[112:113] op_sel_hi:[1,0]
	v_pk_mul_f32 v[8:9], v[20:21], v[112:113] op_sel_hi:[1,0]
	s_mov_b32 s5, s28
	v_cvt_pk_bf16_f32 v8, v8, v9
	v_cvt_pk_bf16_f32 v9, v10, v11
	v_cvt_pk_bf16_f32 v10, v12, v13
	v_cvt_pk_bf16_f32 v11, v14, v15
	global_store_dwordx4 v[16:17], v[8:11], off
	s_mov_b32 s4, s30
	s_mov_b64 s[6:7], s[34:35]
	v_pk_mul_f32 v[8:9], v[2:3], v[112:113] op_sel_hi:[1,0]
	v_pk_mul_f32 v[2:3], v[0:1], v[112:113] op_sel_hi:[1,0]
	v_cvt_pk_bf16_f32 v0, v4, v5
	v_cvt_pk_bf16_f32 v1, v6, v7
	v_cvt_pk_bf16_f32 v2, v2, v3
	v_cvt_pk_bf16_f32 v3, v8, v9
	global_store_dwordx4 v[16:17], v[0:3], off offset:256
	s_cbranch_vccz .LBB0_343
	s_waitcnt vmcnt(0)
	s_cmpk_gt_u32 s27, 0xff
	s_cbranch_scc1 .LBB0_350
	s_barrier

; #define PG8_STAGE(bufoff, gbase, voff) do { _Pragma("unroll") for (int _i = 0; _i < 2; ++_i) \
;     __builtin_amdgcn_global_load_lds((const unsigned*)((const char*)(gbase) + (voff)[_i]), (LAS unsigned*)(lds + (bufoff) + ldsw + _i * 8192), 16, 0, 0); } while (0)
; #define PG8_LDA(dst, b, h) do { _Pragma("unroll") for (int m = 0; m < 4; ++m) _Pragma("unroll") for (int k = 0; k < 2; ++k) dst[m][k] = *(const LAS bf16x8*)(lds + PG8_SA(b, h) + aoff + m * 2048 + k * 1024); } while (0)
; #define PG8_LDB(dst, b, h) do { _Pragma("unroll") for (int n = 0; n < 2; ++n) _Pragma("unroll") for (int k = 0; k < 2; ++k) dst[n][k] = *(const LAS bf16x8*)(lds + PG8_SB(b, h) + boff + n * 2048 + k * 1024); } while (0)
; #define PG8_MMA(ai, bj, At, Bt) do { __builtin_amdgcn_s_setprio(1); _Pragma("unroll") for (int m = 0; m < 4; ++m) _Pragma("unroll") for (int n = 0; n < 2; ++n) _Pragma("unroll") for (int k = 0; k < 2; ++k) \
;     acc[ai][bj][m][n] = __builtin_amdgcn_mfma_f32_16x16x32_bf16(Bt[n][k], At[m][k], acc[ai][bj][m][n], 0, 0, 0); __builtin_amdgcn_s_setprio(0); } while (0)
; #define PG8_WAIT_V(n) asm volatile("s_waitcnt vmcnt(" #n ")" ::: "memory")
; #define PG8_WAIT_L(n) asm volatile("s_waitcnt lgkmcnt(" #n ")" ::: "memory")
; #define PG8_BAR __builtin_amdgcn_s_barrier()
; #define PG8_SCHED __builtin_amdgcn_sched_barrier(0)
; template <class Epi, class Sched = StaticOrder>
; DI void gemm_phase(LAS unsigned char* lds, const Gemm g, const Sched& S, const Epi& E) {
;     ...
;     for (int t = 0; t < nt; t += 2) {
;       const bool last = (t == nt - 2);
;       const char* a1 = cA + (size_t)(t + 1) * kstep;
;       const char* a2 = last ? nA : cA + (size_t)(t + 2) * kstep; const char* b2 = last ? nB : cB + (size_t)(t + 2) * kstep;
;       const char* a3 = a2 + kstep; const char* b3 = b2 + kstep;
;       PG8_LDB(B0, 0, 0); PG8_SCHED; PG8_LDA(At, 0, 0); PG8_STAGE(PG8_SA(1, 1), a1 + hstep, voffA);
;       PG8_WAIT_L(8); PG8_BAR; PG8_WAIT_L(0); PG8_MMA(0, 0, At, B0); PG8_BAR; PG8_SCHED;
;       PG8_LDB(B1, 0, 1); PG8_STAGE(PG8_SB(0, 0), b2, voffB);
;       PG8_BAR; PG8_WAIT_L(0); PG8_MMA(0, 1, At, B1); PG8_BAR;
;       PG8_LDA(At, 0, 1); PG8_STAGE(PG8_SA(0, 0), a2, voffA);
;       PG8_BAR; PG8_WAIT_L(0); PG8_MMA(1, 0, At, B0); PG8_BAR; PG8_SCHED;
;       PG8_STAGE(PG8_SB(0, 1), b2 + hstep, voffB);
;       PG8_WAIT_V(6); PG8_BAR; PG8_MMA(1, 1, At, B1); PG8_BAR;
.LBB0_728:
	s_add_u32 s24, s22, 0xfff80080
	s_addc_u32 s25, s23, -1
	s_cmp_eq_u32 s53, 28
	s_cselect_b32 s27, s17, s25
	s_cselect_b32 s26, s43, s24
	s_cselect_b32 s25, s15, s52
	s_cselect_b32 s24, s44, s45
	s_add_i32 m0, s37, 0xc000
	ds_read_b128 v[144:147], v208
	ds_read_b128 v[148:151], v208 offset:1024
	ds_read_b128 v[152:155], v208 offset:2048
	ds_read_b128 v[156:159], v208 offset:3072
	ds_read_b128 v[160:163], v208 offset:4096
	ds_read_b128 v[164:167], v208 offset:5120
	ds_read_b128 v[168:171], v208 offset:6144
	ds_read_b128 v[172:175], v208 offset:7168
	global_load_lds_dwordx4 v184, s[22:23]
	s_add_i32 m0, s37, 0xe000
	s_nop 0
	global_load_lds_dwordx4 v186, s[22:23]
	s_waitcnt lgkmcnt(8)
	s_setprio 1
	s_barrier
	s_waitcnt lgkmcnt(0)
	v_mfma_f32_16x16x32_bf16 v[124:127], v[128:131], v[144:147], v[124:127]
	v_mfma_f32_16x16x32_bf16 v[120:123], v[136:139], v[144:147], v[120:123]
	v_mfma_f32_16x16x32_bf16 v[108:111], v[128:131], v[152:155], v[108:111]
	v_mfma_f32_16x16x32_bf16 v[104:107], v[136:139], v[152:155], v[104:107]
	v_mfma_f32_16x16x32_bf16 v[92:95], v[128:131], v[160:163], v[92:95]
	v_mfma_f32_16x16x32_bf16 v[88:91], v[136:139], v[160:163], v[88:91]
	v_mfma_f32_16x16x32_bf16 v[76:79], v[128:131], v[168:171], v[76:79]
	v_mfma_f32_16x16x32_bf16 v[72:75], v[136:139], v[168:171], v[72:75]
	v_mfma_f32_16x16x32_bf16 v[124:127], v[132:135], v[148:151], v[124:127]
	v_mfma_f32_16x16x32_bf16 v[120:123], v[140:143], v[148:151], v[120:123]
	v_mfma_f32_16x16x32_bf16 v[108:111], v[132:135], v[156:159], v[108:111]
	v_mfma_f32_16x16x32_bf16 v[104:107], v[140:143], v[156:159], v[104:107]
	v_mfma_f32_16x16x32_bf16 v[92:95], v[132:135], v[164:167], v[92:95]
	v_mfma_f32_16x16x32_bf16 v[88:91], v[140:143], v[164:167], v[88:91]
	v_mfma_f32_16x16x32_bf16 v[76:79], v[132:135], v[172:175], v[76:79]
	v_mfma_f32_16x16x32_bf16 v[72:75], v[140:143], v[172:175], v[72:75]
	s_barrier
	s_setprio 0
	s_add_i32 s54, s50, s35
	s_add_u32 s98, s24, 0x80
	s_addc_u32 s99, s25, 0
	s_add_u32 s100, s26, 0x80
	s_addc_u32 s101, s27, 0
	s_mov_b32 m0, s54
	ds_read_b128 v[192:195], v209
	ds_read_b128 v[196:199], v209 offset:1024
	ds_read_b128 v[200:203], v209 offset:2048
	ds_read_b128 v[212:215], v209 offset:3072
	global_load_lds_dwordx4 v180, s[24:25]
	s_add_i32 m0, s54, 0x2000
	s_nop 0
	global_load_lds_dwordx4 v176, s[24:25]
	s_setprio 1
	s_barrier
	s_waitcnt lgkmcnt(0)
	v_mfma_f32_16x16x32_bf16 v[116:119], v[192:195], v[144:147], v[116:119]
	v_mfma_f32_16x16x32_bf16 v[112:115], v[200:203], v[144:147], v[112:115]
	v_mfma_f32_16x16x32_bf16 v[100:103], v[192:195], v[152:155], v[100:103]
	v_mfma_f32_16x16x32_bf16 v[96:99], v[200:203], v[152:155], v[96:99]
	v_mfma_f32_16x16x32_bf16 v[84:87], v[192:195], v[160:163], v[84:87]
	v_mfma_f32_16x16x32_bf16 v[80:83], v[200:203], v[160:163], v[80:83]
	v_mfma_f32_16x16x32_bf16 v[68:71], v[192:195], v[168:171], v[68:71]
	v_mfma_f32_16x16x32_bf16 v[64:67], v[200:203], v[168:171], v[64:67]
	v_mfma_f32_16x16x32_bf16 v[116:119], v[196:199], v[148:151], v[116:119]
	v_mfma_f32_16x16x32_bf16 v[112:115], v[212:215], v[148:151], v[112:115]
	v_mfma_f32_16x16x32_bf16 v[100:103], v[196:199], v[156:159], v[100:103]
	v_mfma_f32_16x16x32_bf16 v[96:99], v[212:215], v[156:159], v[96:99]
	v_mfma_f32_16x16x32_bf16 v[84:87], v[196:199], v[164:167], v[84:87]
	v_mfma_f32_16x16x32_bf16 v[80:83], v[212:215], v[164:167], v[80:83]
	v_mfma_f32_16x16x32_bf16 v[68:71], v[196:199], v[172:175], v[68:71]
	v_mfma_f32_16x16x32_bf16 v[64:67], v[212:215], v[172:175], v[64:67]
	s_barrier
	s_setprio 0
	s_mov_b32 m0, s37
	ds_read_b128 v[144:147], v208 offset:16384
	ds_read_b128 v[148:151], v208 offset:17408
	ds_read_b128 v[152:155], v208 offset:18432
	ds_read_b128 v[156:159], v208 offset:19456
	ds_read_b128 v[160:163], v208 offset:20480
	ds_read_b128 v[164:167], v208 offset:21504
	ds_read_b128 v[168:171], v208 offset:22528
	ds_read_b128 v[172:175], v208 offset:23552
	global_load_lds_dwordx4 v182, s[26:27]
	s_mov_b32 m0, s38
	s_nop 0
	global_load_lds_dwordx4 v178, s[26:27]
	s_waitcnt vmcnt(10)
	s_setprio 1
	s_barrier
	s_waitcnt lgkmcnt(0)
	v_mfma_f32_16x16x32_bf16 v[60:63], v[128:131], v[144:147], v[60:63]
	v_mfma_f32_16x16x32_bf16 v[56:59], v[136:139], v[144:147], v[56:59]
	v_mfma_f32_16x16x32_bf16 v[44:47], v[128:131], v[152:155], v[44:47]
	v_mfma_f32_16x16x32_bf16 v[40:43], v[136:139], v[152:155], v[40:43]
	v_mfma_f32_16x16x32_bf16 v[28:31], v[128:131], v[160:163], v[28:31]
	v_mfma_f32_16x16x32_bf16 v[24:27], v[136:139], v[160:163], v[24:27]
	v_mfma_f32_16x16x32_bf16 v[12:15], v[128:131], v[168:171], v[12:15]
	v_mfma_f32_16x16x32_bf16 v[8:11], v[136:139], v[168:171], v[8:11]
	v_mfma_f32_16x16x32_bf16 v[60:63], v[132:135], v[148:151], v[60:63]
	v_mfma_f32_16x16x32_bf16 v[56:59], v[140:143], v[148:151], v[56:59]
	v_mfma_f32_16x16x32_bf16 v[44:47], v[132:135], v[156:159], v[44:47]
	v_mfma_f32_16x16x32_bf16 v[40:43], v[140:143], v[156:159], v[40:43]
	v_mfma_f32_16x16x32_bf16 v[28:31], v[132:135], v[164:167], v[28:31]
	v_mfma_f32_16x16x32_bf16 v[24:27], v[140:143], v[164:167], v[24:27]
	v_mfma_f32_16x16x32_bf16 v[12:15], v[132:135], v[172:175], v[12:15]
	v_mfma_f32_16x16x32_bf16 v[8:11], v[140:143], v[172:175], v[8:11]
	s_barrier
	s_setprio 0
	s_add_u32 s54, s24, 0x80000
	s_addc_u32 s55, s25, 0
	s_add_i32 s57, s51, s35
	s_mov_b32 m0, s57
	s_nop 0
	global_load_lds_dwordx4 v180, s[54:55]
	s_add_i32 m0, s57, 0x2000
	s_nop 0
	global_load_lds_dwordx4 v176, s[54:55]
	s_add_i32 s54, 0, 0x18000
	v_add_u32_e32 v140, s54, v205
	ds_read_b128 v[128:131], v140
	ds_read_b128 v[132:135], v140 offset:1024
	ds_read_b128 v[136:139], v140 offset:2048
	ds_read_b128 v[140:143], v140 offset:3072
	s_waitcnt vmcnt(6)
	s_setprio 1
	s_barrier
; #define PG8_STAGE(bufoff, gbase, voff) do { _Pragma("unroll") for (int _i = 0; _i < 2; ++_i) \
;     __builtin_amdgcn_global_load_lds((const unsigned*)((const char*)(gbase) + (voff)[_i]), (LAS unsigned*)(lds + (bufoff) + ldsw + _i * 8192), 16, 0, 0); } while (0)
; #define PG8_LDA(dst, b, h) do { _Pragma("unroll") for (int m = 0; m < 4; ++m) _Pragma("unroll") for (int k = 0; k < 2; ++k) dst[m][k] = *(const LAS bf16x8*)(lds + PG8_SA(b, h) + aoff + m * 2048 + k * 1024); } while (0)
; #define PG8_LDB(dst, b, h) do { _Pragma("unroll") for (int n = 0; n < 2; ++n) _Pragma("unroll") for (int k = 0; k < 2; ++k) dst[n][k] = *(const LAS bf16x8*)(lds + PG8_SB(b, h) + boff + n * 2048 + k * 1024); } while (0)
; #define PG8_MMA(ai, bj, At, Bt) do { __builtin_amdgcn_s_setprio(1); _Pragma("unroll") for (int m = 0; m < 4; ++m) _Pragma("unroll") for (int n = 0; n < 2; ++n) _Pragma("unroll") for (int k = 0; k < 2; ++k) \
;     acc[ai][bj][m][n] = __builtin_amdgcn_mfma_f32_16x16x32_bf16(Bt[n][k], At[m][k], acc[ai][bj][m][n], 0, 0, 0); __builtin_amdgcn_s_setprio(0); } while (0)
; #define PG8_WAIT_V(n) asm volatile("s_waitcnt vmcnt(" #n ")" ::: "memory")
; #define PG8_WAIT_L(n) asm volatile("s_waitcnt lgkmcnt(" #n ")" ::: "memory")
; #define PG8_BAR __builtin_amdgcn_s_barrier()
; #define PG8_SCHED __builtin_amdgcn_sched_barrier(0)
; template <class Epi, class Sched = StaticOrder>
; DI void gemm_phase(LAS unsigned char* lds, const Gemm g, const Sched& S, const Epi& E) {
;     ...
;       PG8_WAIT_V(6); PG8_BAR; PG8_MMA(1, 1, At, B1); PG8_BAR;
;       PG8_LDB(B0, 1, 0); PG8_SCHED; PG8_LDA(At, 1, 0); PG8_STAGE(PG8_SA(0, 1), a2 + hstep, voffA);
;       PG8_WAIT_L(8); PG8_BAR; PG8_WAIT_L(0); PG8_MMA(0, 0, At, B0); PG8_BAR; PG8_SCHED;
;       PG8_LDB(B1, 1, 1); PG8_STAGE(PG8_SB(1, 0), b3, voffB);
;       PG8_BAR; PG8_WAIT_L(0); PG8_MMA(0, 1, At, B1); PG8_BAR;
;       PG8_LDA(At, 1, 1); PG8_STAGE(PG8_SA(1, 0), a3, voffA);
;       PG8_BAR; PG8_WAIT_L(0); PG8_MMA(1, 0, At, B0); PG8_BAR; PG8_SCHED;
	v_mfma_f32_16x16x32_bf16 v[52:55], v[192:195], v[144:147], v[52:55]
	v_mfma_f32_16x16x32_bf16 v[48:51], v[200:203], v[144:147], v[48:51]
	v_mfma_f32_16x16x32_bf16 v[36:39], v[192:195], v[152:155], v[36:39]
	v_mfma_f32_16x16x32_bf16 v[32:35], v[200:203], v[152:155], v[32:35]
	v_mfma_f32_16x16x32_bf16 v[20:23], v[192:195], v[160:163], v[20:23]
	v_mfma_f32_16x16x32_bf16 v[16:19], v[200:203], v[160:163], v[16:19]
	v_mfma_f32_16x16x32_bf16 v[4:7], v[192:195], v[168:171], v[4:7]
	v_mfma_f32_16x16x32_bf16 v[0:3], v[200:203], v[168:171], v[0:3]
	v_mfma_f32_16x16x32_bf16 v[52:55], v[196:199], v[148:151], v[52:55]
	v_mfma_f32_16x16x32_bf16 v[48:51], v[212:215], v[148:151], v[48:51]
	v_mfma_f32_16x16x32_bf16 v[36:39], v[196:199], v[156:159], v[36:39]
	v_mfma_f32_16x16x32_bf16 v[32:35], v[212:215], v[156:159], v[32:35]
	v_mfma_f32_16x16x32_bf16 v[20:23], v[196:199], v[164:167], v[20:23]
	v_mfma_f32_16x16x32_bf16 v[16:19], v[212:215], v[164:167], v[16:19]
	v_mfma_f32_16x16x32_bf16 v[4:7], v[196:199], v[172:175], v[4:7]
	v_mfma_f32_16x16x32_bf16 v[0:3], v[212:215], v[172:175], v[0:3]
	s_barrier
	s_setprio 0
	s_add_u32 s26, s26, 0x80000
	s_addc_u32 s27, s27, 0
	s_mov_b32 m0, s39
	ds_read_b128 v[144:147], v208 offset:32768
	ds_read_b128 v[148:151], v208 offset:33792
	ds_read_b128 v[152:155], v208 offset:34816
	ds_read_b128 v[156:159], v208 offset:35840
	ds_read_b128 v[160:163], v208 offset:36864
	ds_read_b128 v[164:167], v208 offset:37888
	ds_read_b128 v[168:171], v208 offset:38912
	ds_read_b128 v[172:175], v208 offset:39936
	global_load_lds_dwordx4 v182, s[26:27]
	s_mov_b32 m0, s40
	s_nop 0
	global_load_lds_dwordx4 v178, s[26:27]
	s_waitcnt lgkmcnt(8)
	s_setprio 1
	s_barrier
	s_waitcnt lgkmcnt(0)
	v_mfma_f32_16x16x32_bf16 v[124:127], v[128:131], v[144:147], v[124:127]
	v_mfma_f32_16x16x32_bf16 v[120:123], v[136:139], v[144:147], v[120:123]
	v_mfma_f32_16x16x32_bf16 v[108:111], v[128:131], v[152:155], v[108:111]
	v_mfma_f32_16x16x32_bf16 v[104:107], v[136:139], v[152:155], v[104:107]
	v_mfma_f32_16x16x32_bf16 v[92:95], v[128:131], v[160:163], v[92:95]
	v_mfma_f32_16x16x32_bf16 v[88:91], v[136:139], v[160:163], v[88:91]
	v_mfma_f32_16x16x32_bf16 v[76:79], v[128:131], v[168:171], v[76:79]
	v_mfma_f32_16x16x32_bf16 v[72:75], v[136:139], v[168:171], v[72:75]
	v_mfma_f32_16x16x32_bf16 v[124:127], v[132:135], v[148:151], v[124:127]
	v_mfma_f32_16x16x32_bf16 v[120:123], v[140:143], v[148:151], v[120:123]
	v_mfma_f32_16x16x32_bf16 v[108:111], v[132:135], v[156:159], v[108:111]
	v_mfma_f32_16x16x32_bf16 v[104:107], v[140:143], v[156:159], v[104:107]
	v_mfma_f32_16x16x32_bf16 v[92:95], v[132:135], v[164:167], v[92:95]
	v_mfma_f32_16x16x32_bf16 v[88:91], v[140:143], v[164:167], v[88:91]
	v_mfma_f32_16x16x32_bf16 v[76:79], v[132:135], v[172:175], v[76:79]
	v_mfma_f32_16x16x32_bf16 v[72:75], v[140:143], v[172:175], v[72:75]
	s_barrier
	s_setprio 0
	s_add_i32 s26, 0, 0x1c000
	s_add_i32 s27, s54, s35
	v_add_u32_e32 v212, s26, v205
	s_mov_b32 m0, s27
	ds_read_b128 v[192:195], v212
	ds_read_b128 v[196:199], v212 offset:1024
	ds_read_b128 v[200:203], v212 offset:2048
	ds_read_b128 v[212:215], v212 offset:3072
	global_load_lds_dwordx4 v180, s[98:99]
	s_add_i32 m0, s27, 0x2000
	s_nop 0
	global_load_lds_dwordx4 v176, s[98:99]
	s_setprio 1
	s_barrier
	s_waitcnt lgkmcnt(0)
	v_mfma_f32_16x16x32_bf16 v[116:119], v[192:195], v[144:147], v[116:119]
	v_mfma_f32_16x16x32_bf16 v[112:115], v[200:203], v[144:147], v[112:115]
	v_mfma_f32_16x16x32_bf16 v[100:103], v[192:195], v[152:155], v[100:103]
	v_mfma_f32_16x16x32_bf16 v[96:99], v[200:203], v[152:155], v[96:99]
	v_mfma_f32_16x16x32_bf16 v[84:87], v[192:195], v[160:163], v[84:87]
	v_mfma_f32_16x16x32_bf16 v[80:83], v[200:203], v[160:163], v[80:83]
	v_mfma_f32_16x16x32_bf16 v[68:71], v[192:195], v[168:171], v[68:71]
	v_mfma_f32_16x16x32_bf16 v[64:67], v[200:203], v[168:171], v[64:67]
	v_mfma_f32_16x16x32_bf16 v[116:119], v[196:199], v[148:151], v[116:119]
	v_mfma_f32_16x16x32_bf16 v[112:115], v[212:215], v[148:151], v[112:115]
	v_mfma_f32_16x16x32_bf16 v[100:103], v[196:199], v[156:159], v[100:103]
	v_mfma_f32_16x16x32_bf16 v[96:99], v[212:215], v[156:159], v[96:99]
	v_mfma_f32_16x16x32_bf16 v[84:87], v[196:199], v[164:167], v[84:87]
	v_mfma_f32_16x16x32_bf16 v[80:83], v[212:215], v[164:167], v[80:83]
	v_mfma_f32_16x16x32_bf16 v[68:71], v[196:199], v[172:175], v[68:71]
	v_mfma_f32_16x16x32_bf16 v[64:67], v[212:215], v[172:175], v[64:67]
	s_barrier
	s_setprio 0
	s_mov_b32 m0, s46
	ds_read_b128 v[144:147], v208 offset:49152
	ds_read_b128 v[148:151], v208 offset:50176
	ds_read_b128 v[152:155], v208 offset:51200
	ds_read_b128 v[156:159], v208 offset:52224
	ds_read_b128 v[160:163], v208 offset:53248
	ds_read_b128 v[164:167], v208 offset:54272
	ds_read_b128 v[168:171], v208 offset:55296
	ds_read_b128 v[172:175], v208 offset:56320
	global_load_lds_dwordx4 v182, s[100:101]
	s_mov_b32 m0, s47
	s_nop 0
	global_load_lds_dwordx4 v178, s[100:101]
	s_waitcnt vmcnt(10)
	s_setprio 1
	s_barrier
	s_waitcnt lgkmcnt(0)
	v_mfma_f32_16x16x32_bf16 v[60:63], v[128:131], v[144:147], v[60:63]
	v_mfma_f32_16x16x32_bf16 v[56:59], v[136:139], v[144:147], v[56:59]
	v_mfma_f32_16x16x32_bf16 v[44:47], v[128:131], v[152:155], v[44:47]
	v_mfma_f32_16x16x32_bf16 v[40:43], v[136:139], v[152:155], v[40:43]
	v_mfma_f32_16x16x32_bf16 v[28:31], v[128:131], v[160:163], v[28:31]
	v_mfma_f32_16x16x32_bf16 v[24:27], v[136:139], v[160:163], v[24:27]
	v_mfma_f32_16x16x32_bf16 v[12:15], v[128:131], v[168:171], v[12:15]
	v_mfma_f32_16x16x32_bf16 v[8:11], v[136:139], v[168:171], v[8:11]
	v_mfma_f32_16x16x32_bf16 v[60:63], v[132:135], v[148:151], v[60:63]
	v_mfma_f32_16x16x32_bf16 v[56:59], v[140:143], v[148:151], v[56:59]
	v_mfma_f32_16x16x32_bf16 v[44:47], v[132:135], v[156:159], v[44:47]
	v_mfma_f32_16x16x32_bf16 v[40:43], v[140:143], v[156:159], v[40:43]
	v_mfma_f32_16x16x32_bf16 v[28:31], v[132:135], v[164:167], v[28:31]
	v_mfma_f32_16x16x32_bf16 v[24:27], v[140:143], v[164:167], v[24:27]
	v_mfma_f32_16x16x32_bf16 v[12:15], v[132:135], v[172:175], v[12:15]
	v_mfma_f32_16x16x32_bf16 v[8:11], v[140:143], v[172:175], v[8:11]
	s_barrier
; DI unsigned pack2(float lo, float hi) { f32x2 v = {lo, hi}; bf16v2 r = __builtin_convertvector(v, bf16v2); return __builtin_bit_cast(unsigned, r); }
; #define PG8_STAGE(bufoff, gbase, voff) do { _Pragma("unroll") for (int _i = 0; _i < 2; ++_i) \
;     __builtin_amdgcn_global_load_lds((const unsigned*)((const char*)(gbase) + (voff)[_i]), (LAS unsigned*)(lds + (bufoff) + ldsw + _i * 8192), 16, 0, 0); } while (0)
; #define PG8_WAIT_V(n) asm volatile("s_waitcnt vmcnt(" #n ")" ::: "memory")
; #define PG8_BAR __builtin_amdgcn_s_barrier()
;   DI void operator()(const f32x4 (&acc)[2][2][4][2], const Unit& u, int wr, int wc, int fr, int fq) const {
;     const int row0 = u.pm * BM + wr * 64 + fr, col0 = u.pn * BM + wc * 32 + 8 * fq;
; #pragma unroll
;     for (int ai = 0; ai < 2; ++ai) {
;       f32x4 bv[4][2][2];
; #pragma unroll
;       for (int m = 0; m < 4; ++m)
; #pragma unroll
;         for (int bj = 0; bj < 2; ++bj) {
;           const float* bp = base + (size_t)(row0 + ai * HALF + m * 16) * 2048 + col0 + bj * HALF;
;           bv[m][bj][0] = *(const f32x4*)bp; bv[m][bj][1] = *(const f32x4*)(bp + 4);
;         }
; #pragma unroll
;       for (int m = 0; m < 4; ++m) {
;         const int row = row0 + ai * HALF + m * 16;
;         const size_t off = (size_t)row * 2048 + col0;
;         float ss = 0.f;
; #pragma unroll
;         for (int bj = 0; bj < 2; ++bj) {
;           const f32x4 v0 = acc[ai][bj][m][0] + bv[m][bj][0], v1 = acc[ai][bj][m][1] + bv[m][bj][1];
;           *(f32x4*)(C + off + bj * HALF) = v0; *(f32x4*)(C + off + bj * HALF + 4) = v1;
;           if (xb) {
;             u32x4 w; w.x = pack2(v0[0], v0[1]); w.y = pack2(v0[2], v0[3]); w.z = pack2(v1[0], v1[1]); w.w = pack2(v1[2], v1[3]);
;             *(u32x4*)(xb + off + bj * HALF) = w;
;             ss += v0[0] * v0[0] + v0[1] * v0[1] + v0[2] * v0[2] + v0[3] * v0[3] + v1[0] * v1[0] + v1[1] * v1[1] + v1[2] * v1[2] + v1[3] * v1[3];
;           }
;         }
;         if (xb) {
;           ss += __shfl_xor(ss, 16); ss += __shfl_xor(ss, 32);
;           if (fq == 0) ssq[(size_t)row * 32 + u.pn * 4 + wc] = ss;
;         }
;       }
;     }
; template <class Epi, class Sched = StaticOrder>
; DI void gemm_phase(LAS unsigned char* lds, const Gemm g, const Sched& S, const Epi& E) {
;     ...
;       PG8_STAGE(PG8_SB(1, 1), b3 + hstep, voffB);
;       PG8_WAIT_V(6); PG8_BAR; PG8_MMA(1, 1, At, B1); PG8_BAR;
	s_setprio 0
	s_add_u32 s24, s24, 0x80080
	s_addc_u32 s25, s25, 0
	s_add_i32 s26, s26, s35
	s_mov_b32 m0, s26
	s_nop 0
	global_load_lds_dwordx4 v180, s[24:25]
	s_add_i32 m0, s26, 0x2000
	s_nop 0
	global_load_lds_dwordx4 v176, s[24:25]
	ds_read_b128 v[128:131], v207
	ds_read_b128 v[132:135], v207 offset:1024
	ds_read_b128 v[136:139], v207 offset:2048
	ds_read_b128 v[140:143], v207 offset:3072
	s_waitcnt vmcnt(6)
	s_setprio 1
	s_barrier
	v_mfma_f32_16x16x32_bf16 v[52:55], v[192:195], v[144:147], v[52:55]
	v_mfma_f32_16x16x32_bf16 v[48:51], v[200:203], v[144:147], v[48:51]
	v_mfma_f32_16x16x32_bf16 v[36:39], v[192:195], v[152:155], v[36:39]
	v_mfma_f32_16x16x32_bf16 v[32:35], v[200:203], v[152:155], v[32:35]
	v_mfma_f32_16x16x32_bf16 v[20:23], v[192:195], v[160:163], v[20:23]
	v_mfma_f32_16x16x32_bf16 v[16:19], v[200:203], v[160:163], v[16:19]
	v_mfma_f32_16x16x32_bf16 v[4:7], v[192:195], v[168:171], v[4:7]
	v_mfma_f32_16x16x32_bf16 v[0:3], v[200:203], v[168:171], v[0:3]
	v_mfma_f32_16x16x32_bf16 v[52:55], v[196:199], v[148:151], v[52:55]
	v_mfma_f32_16x16x32_bf16 v[48:51], v[212:215], v[148:151], v[48:51]
	v_mfma_f32_16x16x32_bf16 v[36:39], v[196:199], v[156:159], v[36:39]
	v_mfma_f32_16x16x32_bf16 v[32:35], v[212:215], v[156:159], v[32:35]
	v_mfma_f32_16x16x32_bf16 v[20:23], v[196:199], v[164:167], v[20:23]
	v_mfma_f32_16x16x32_bf16 v[16:19], v[212:215], v[164:167], v[16:19]
	v_mfma_f32_16x16x32_bf16 v[4:7], v[196:199], v[172:175], v[4:7]
	v_mfma_f32_16x16x32_bf16 v[0:3], v[212:215], v[172:175], v[0:3]
	s_add_i32 s53, s53, 2
	s_add_u32 s22, s22, 0x100
	s_addc_u32 s23, s23, 0
	s_add_u32 s45, s45, 0x100
	s_addc_u32 s52, s52, 0
	s_cmp_gt_u32 s53, 29
	s_barrier
	s_setprio 0
	s_cbranch_scc0 .LBB0_728
	s_waitcnt lgkmcnt(0)
	v_lshl_add_u32 v196, s12, 8, v204
	v_lshl_or_b32 v192, s42, 8, v206
	v_ashrrev_i32_e32 v193, 31, v192
	v_ashrrev_i32_e32 v197, 31, v196
	v_lshl_add_u64 v[194:195], v[192:193], 2, s[60:61]
	v_lshlrev_b64 v[128:129], 13, v[196:197]
	v_lshl_add_u64 v[128:129], v[194:195], 0, v[128:129]
	global_load_dwordx4 v[214:217], v[128:129], off
	global_load_dwordx4 v[218:221], v[128:129], off offset:16
	global_load_dwordx4 v[222:225], v[128:129], off offset:512
	global_load_dwordx4 v[226:229], v[128:129], off offset:528
	v_or_b32_e32 v202, 16, v196
	v_or_b32_e32 v200, 32, v196
	v_or_b32_e32 v198, 48, v196
	v_ashrrev_i32_e32 v203, 31, v202
	v_ashrrev_i32_e32 v201, 31, v200
	v_ashrrev_i32_e32 v199, 31, v198
	v_lshlrev_b64 v[128:129], 13, v[202:203]
	v_lshlrev_b64 v[130:131], 13, v[200:201]
	v_lshlrev_b64 v[132:133], 13, v[198:199]
	v_lshl_add_u64 v[128:129], v[194:195], 0, v[128:129]
	v_lshl_add_u64 v[130:131], v[194:195], 0, v[130:131]
	v_lshl_add_u64 v[132:133], v[194:195], 0, v[132:133]
	global_load_dwordx4 v[168:171], v[128:129], off offset:16
	global_load_dwordx4 v[172:175], v[128:129], off
	global_load_dwordx4 v[160:163], v[128:129], off offset:528
	global_load_dwordx4 v[164:167], v[128:129], off offset:512
	global_load_dwordx4 v[152:155], v[130:131], off offset:16
	global_load_dwordx4 v[156:159], v[130:131], off
	global_load_dwordx4 v[144:147], v[130:131], off offset:528
	global_load_dwordx4 v[148:151], v[130:131], off offset:512
	global_load_dwordx4 v[136:139], v[132:133], off offset:16
	global_load_dwordx4 v[140:143], v[132:133], off
	s_nop 0
	global_load_dwordx4 v[128:131], v[132:133], off offset:528
	s_nop 0
	global_load_dwordx4 v[132:135], v[132:133], off offset:512
	v_and_b32_e32 v212, 64, v211
	v_xor_b32_e32 v230, 16, v211
	v_add_u32_e32 v232, 64, v212
	v_xor_b32_e32 v231, 32, v211
	v_cmp_lt_i32_e32 vcc, v230, v232
	v_lshlrev_b64 v[212:213], 11, v[196:197]
	v_readlane_b32 s64, v243, 3
	v_cndmask_b32_e32 v233, v211, v230, vcc
	v_cmp_lt_i32_e32 vcc, v231, v232
	v_readlane_b32 s78, v243, 17
	v_readlane_b32 s79, v243, 18
	v_cndmask_b32_e32 v234, v211, v231, vcc
	v_lshl_add_u64 v[230:231], v[212:213], 0, v[192:193]
	v_lshlrev_b32_e32 v212, 2, v233
	v_lshl_add_u64 v[232:233], v[230:231], 2, s[78:79]
	v_lshl_add_u64 v[230:231], v[230:231], 1, s[2:3]
	s_lshl_b32 s22, s42, 2
	s_ashr_i32 s23, s22, 31
	v_readlane_b32 s65, v243, 4
	v_readlane_b32 s66, v243, 5
	v_readlane_b32 s67, v243, 6
	v_readlane_b32 s68, v243, 7
	v_readlane_b32 s69, v243, 8
	v_readlane_b32 s70, v243, 9
	v_readlane_b32 s71, v243, 10
	v_readlane_b32 s72, v243, 11
	v_readlane_b32 s73, v243, 12
	v_readlane_b32 s74, v243, 13
	v_readlane_b32 s75, v243, 14
	v_readlane_b32 s76, v243, 15
	v_readlane_b32 s77, v243, 16
	s_waitcnt vmcnt(0)
	v_pk_add_f32 v[126:127], v[126:127], v[216:217]
	v_pk_add_f32 v[124:125], v[124:125], v[214:215]
	v_pk_add_f32 v[116:117], v[116:117], v[222:223]
	v_pk_add_f32 v[122:123], v[122:123], v[220:221]
	v_pk_add_f32 v[120:121], v[120:121], v[218:219]
	v_pk_add_f32 v[214:215], v[112:113], v[226:227]
	global_store_dwordx4 v[232:233], v[124:127], off
	global_store_dwordx4 v[232:233], v[120:123], off offset:16
	v_cvt_pk_bf16_f32 v112, v124, v125
	v_mul_f32_e32 v125, v125, v125
	v_mul_f32_e32 v213, v117, v117
	v_pk_add_f32 v[118:119], v[118:119], v[224:225]
	v_fmac_f32_e32 v125, v124, v124
	v_fmac_f32_e32 v213, v116, v116
	v_fmac_f32_e32 v125, v126, v126
	v_fmac_f32_e32 v213, v118, v118
	v_fmac_f32_e32 v125, v127, v127
	v_fmac_f32_e32 v213, v119, v119
	v_fmac_f32_e32 v125, v120, v120
	v_fmac_f32_e32 v213, v214, v214
	v_pk_add_f32 v[216:217], v[114:115], v[228:229]
	v_fmac_f32_e32 v125, v121, v121
	v_fmac_f32_e32 v213, v215, v215
	v_fmac_f32_e32 v125, v122, v122
	v_fmac_f32_e32 v213, v216, v216
	v_fmac_f32_e32 v125, v123, v123
	v_fmac_f32_e32 v213, v217, v217
	v_cvt_pk_bf16_f32 v114, v120, v121
	v_add_f32_e32 v120, v125, v213
	ds_bpermute_b32 v121, v212, v120
	v_cvt_pk_bf16_f32 v113, v126, v127
	v_cvt_pk_bf16_f32 v115, v122, v123
	global_store_dwordx4 v[230:231], v[112:115], off
	global_store_dwordx4 v[232:233], v[116:119], off offset:512
	global_store_dwordx4 v[232:233], v[214:217], off offset:528
	v_cvt_pk_bf16_f32 v122, v116, v117
	s_waitcnt lgkmcnt(0)
	v_add_f32_e32 v112, v120, v121
	v_lshlrev_b32_e32 v120, 2, v234
	ds_bpermute_b32 v113, v120, v112
	v_cvt_pk_bf16_f32 v123, v118, v119
	v_cvt_pk_bf16_f32 v124, v214, v215
	v_cvt_pk_bf16_f32 v125, v216, v217
	global_store_dwordx4 v[230:231], v[122:125], off offset:256
	s_and_saveexec_b64 s[24:25], s[0:1]
	s_cbranch_execz .LBB0_731
	s_waitcnt lgkmcnt(0)
	v_add_f32_e32 v114, v112, v113
	v_lshlrev_b64 v[112:113], 7, v[196:197]
	v_lshl_add_u64 v[112:113], s[8:9], 0, v[112:113]
	v_lshl_add_u64 v[112:113], s[22:23], 2, v[112:113]
	s_lshl_b32 s12, s41, 2
	v_lshl_add_u64 v[112:113], v[112:113], 0, s[12:13]
	global_store_dword v[112:113], v114, off

; #define PG8_STAGE(bufoff, gbase, voff) do { _Pragma("unroll") for (int _i = 0; _i < 2; ++_i) \
;     __builtin_amdgcn_global_load_lds((const unsigned*)((const char*)(gbase) + (voff)[_i]), (LAS unsigned*)(lds + (bufoff) + ldsw + _i * 8192), 16, 0, 0); } while (0)
; #define PG8_LDA(dst, b, h) do { _Pragma("unroll") for (int m = 0; m < 4; ++m) _Pragma("unroll") for (int k = 0; k < 2; ++k) dst[m][k] = *(const LAS bf16x8*)(lds + PG8_SA(b, h) + aoff + m * 2048 + k * 1024); } while (0)
; #define PG8_LDB(dst, b, h) do { _Pragma("unroll") for (int n = 0; n < 2; ++n) _Pragma("unroll") for (int k = 0; k < 2; ++k) dst[n][k] = *(const LAS bf16x8*)(lds + PG8_SB(b, h) + boff + n * 2048 + k * 1024); } while (0)
; #define PG8_MMA(ai, bj, At, Bt) do { __builtin_amdgcn_s_setprio(1); _Pragma("unroll") for (int m = 0; m < 4; ++m) _Pragma("unroll") for (int n = 0; n < 2; ++n) _Pragma("unroll") for (int k = 0; k < 2; ++k) \
;     acc[ai][bj][m][n] = __builtin_amdgcn_mfma_f32_16x16x32_bf16(Bt[n][k], At[m][k], acc[ai][bj][m][n], 0, 0, 0); __builtin_amdgcn_s_setprio(0); } while (0)
; #define PG8_WAIT_V(n) asm volatile("s_waitcnt vmcnt(" #n ")" ::: "memory")
; #define PG8_WAIT_L(n) asm volatile("s_waitcnt lgkmcnt(" #n ")" ::: "memory")
; #define PG8_BAR __builtin_amdgcn_s_barrier()
; #define PG8_SCHED __builtin_amdgcn_sched_barrier(0)
; template <class Epi, class Sched = StaticOrder>
; DI void gemm_phase(LAS unsigned char* lds, const Gemm g, const Sched& S, const Epi& E) {
;     ...
;     for (int t = 0; t < nt; t += 2) {
;       const bool last = (t == nt - 2);
;       const char* a1 = cA + (size_t)(t + 1) * kstep;
;       const char* a2 = last ? nA : cA + (size_t)(t + 2) * kstep; const char* b2 = last ? nB : cB + (size_t)(t + 2) * kstep;
;       const char* a3 = a2 + kstep; const char* b3 = b2 + kstep;
;       PG8_LDB(B0, 0, 0); PG8_SCHED; PG8_LDA(At, 0, 0); PG8_STAGE(PG8_SA(1, 1), a1 + hstep, voffA);
;       PG8_WAIT_L(8); PG8_BAR; PG8_WAIT_L(0); PG8_MMA(0, 0, At, B0); PG8_BAR; PG8_SCHED;
;       PG8_LDB(B1, 0, 1); PG8_STAGE(PG8_SB(0, 0), b2, voffB);
;       PG8_BAR; PG8_WAIT_L(0); PG8_MMA(0, 1, At, B1); PG8_BAR;
;       PG8_LDA(At, 0, 1); PG8_STAGE(PG8_SA(0, 0), a2, voffA);
;       PG8_BAR; PG8_WAIT_L(0); PG8_MMA(1, 0, At, B0); PG8_BAR; PG8_SCHED;
;       PG8_STAGE(PG8_SB(0, 1), b2 + hstep, voffB);
;       PG8_WAIT_V(6); PG8_BAR; PG8_MMA(1, 1, At, B1); PG8_BAR;
.LBB0_811:
	s_add_u32 s46, s14, 0xfff80080
	s_addc_u32 s47, s15, -1
	s_cmp_eq_u32 s52, 28
	s_cselect_b32 s49, s37, s47
	s_cselect_b32 s48, s42, s46
	s_cselect_b32 s47, s35, s45
	s_cselect_b32 s46, s43, s44
	s_add_i32 m0, s62, 0xc000
	ds_read_b128 v[80:83], v202
	ds_read_b128 v[84:87], v202 offset:1024
	ds_read_b128 v[92:95], v202 offset:2048
	ds_read_b128 v[96:99], v202 offset:3072
	ds_read_b128 v[180:183], v202 offset:4096
	ds_read_b128 v[184:187], v202 offset:5120
	ds_read_b128 v[188:191], v202 offset:6144
	ds_read_b128 v[192:195], v202 offset:7168
	global_load_lds_dwordx4 v170, s[14:15]
	s_add_i32 m0, s62, 0xe000
	s_nop 0
	global_load_lds_dwordx4 v172, s[14:15]
	s_waitcnt lgkmcnt(8)
	s_setprio 1
	s_barrier
	s_waitcnt lgkmcnt(0)
	v_mfma_f32_16x16x32_bf16 v[156:159], v[64:67], v[80:83], v[156:159]
	v_mfma_f32_16x16x32_bf16 v[144:147], v[72:75], v[80:83], v[144:147]
	v_mfma_f32_16x16x32_bf16 v[140:143], v[64:67], v[92:95], v[140:143]
	v_mfma_f32_16x16x32_bf16 v[132:135], v[72:75], v[92:95], v[132:135]
	v_mfma_f32_16x16x32_bf16 v[124:127], v[64:67], v[180:183], v[124:127]
	v_mfma_f32_16x16x32_bf16 v[116:119], v[72:75], v[180:183], v[116:119]
	v_mfma_f32_16x16x32_bf16 v[112:115], v[64:67], v[188:191], v[112:115]
	v_mfma_f32_16x16x32_bf16 v[108:111], v[72:75], v[188:191], v[108:111]
	v_mfma_f32_16x16x32_bf16 v[156:159], v[68:71], v[84:87], v[156:159]
	v_mfma_f32_16x16x32_bf16 v[144:147], v[76:79], v[84:87], v[144:147]
	v_mfma_f32_16x16x32_bf16 v[140:143], v[68:71], v[96:99], v[140:143]
	v_mfma_f32_16x16x32_bf16 v[132:135], v[76:79], v[96:99], v[132:135]
	v_mfma_f32_16x16x32_bf16 v[124:127], v[68:71], v[184:187], v[124:127]
	v_mfma_f32_16x16x32_bf16 v[116:119], v[76:79], v[184:187], v[116:119]
	v_mfma_f32_16x16x32_bf16 v[112:115], v[68:71], v[192:195], v[112:115]
	v_mfma_f32_16x16x32_bf16 v[108:111], v[76:79], v[192:195], v[108:111]
	s_barrier
	s_setprio 0
	s_add_i32 s53, s72, s60
	s_add_u32 s98, s46, 0x80
	s_addc_u32 s99, s47, 0
	s_add_u32 s100, s48, 0x80
	s_addc_u32 s101, s49, 0
	s_mov_b32 m0, s53
	ds_read_b128 v[206:209], v203
	ds_read_b128 v[212:215], v203 offset:1024
	ds_read_b128 v[216:219], v203 offset:2048
	ds_read_b128 v[220:223], v203 offset:3072
	global_load_lds_dwordx4 v164, s[46:47]
	s_add_i32 m0, s53, 0x2000
	s_nop 0
	global_load_lds_dwordx4 v160, s[46:47]
	s_setprio 1
	s_barrier
	s_waitcnt lgkmcnt(0)
	v_mfma_f32_16x16x32_bf16 v[152:155], v[206:209], v[80:83], v[152:155]
	v_mfma_f32_16x16x32_bf16 v[80:83], v[216:219], v[80:83], v[148:151]
	v_mfma_f32_16x16x32_bf16 v[152:155], v[212:215], v[84:87], v[152:155]
	v_mfma_f32_16x16x32_bf16 v[80:83], v[220:223], v[84:87], v[80:83]
	v_mfma_f32_16x16x32_bf16 v[84:87], v[206:209], v[92:95], v[136:139]
	v_mfma_f32_16x16x32_bf16 v[92:95], v[216:219], v[92:95], v[128:131]
	v_mfma_f32_16x16x32_bf16 v[104:107], v[216:219], v[180:183], v[104:107]
	v_mfma_f32_16x16x32_bf16 v[100:103], v[206:209], v[188:191], v[100:103]
	v_mfma_f32_16x16x32_bf16 v[88:91], v[216:219], v[188:191], v[88:91]
	v_mfma_f32_16x16x32_bf16 v[84:87], v[212:215], v[96:99], v[84:87]
	v_mfma_f32_16x16x32_bf16 v[92:95], v[220:223], v[96:99], v[92:95]
	v_mfma_f32_16x16x32_bf16 v[96:99], v[206:209], v[180:183], v[120:123]
	v_mfma_f32_16x16x32_bf16 v[104:107], v[220:223], v[184:187], v[104:107]
	v_mfma_f32_16x16x32_bf16 v[100:103], v[212:215], v[192:195], v[100:103]
	v_mfma_f32_16x16x32_bf16 v[88:91], v[220:223], v[192:195], v[88:91]
	v_mfma_f32_16x16x32_bf16 v[96:99], v[212:215], v[184:187], v[96:99]
	s_barrier
	s_setprio 0
	s_mov_b32 m0, s62
	ds_read_b128 v[120:123], v202 offset:16384
	ds_read_b128 v[128:131], v202 offset:17408
	ds_read_b128 v[136:139], v202 offset:18432
	ds_read_b128 v[148:151], v202 offset:19456
	ds_read_b128 v[180:183], v202 offset:20480
	ds_read_b128 v[184:187], v202 offset:21504
	ds_read_b128 v[188:191], v202 offset:22528
	ds_read_b128 v[192:195], v202 offset:23552
	global_load_lds_dwordx4 v166, s[48:49]
	s_mov_b32 m0, s63
	s_nop 0
	global_load_lds_dwordx4 v162, s[48:49]
	s_waitcnt vmcnt(10)
	s_setprio 1
	s_barrier
	s_waitcnt lgkmcnt(0)
	v_mfma_f32_16x16x32_bf16 v[60:63], v[64:67], v[120:123], v[60:63]
	v_mfma_f32_16x16x32_bf16 v[48:51], v[72:75], v[120:123], v[48:51]
	v_mfma_f32_16x16x32_bf16 v[44:47], v[64:67], v[136:139], v[44:47]
	v_mfma_f32_16x16x32_bf16 v[36:39], v[72:75], v[136:139], v[36:39]
	v_mfma_f32_16x16x32_bf16 v[28:31], v[64:67], v[180:183], v[28:31]
	v_mfma_f32_16x16x32_bf16 v[20:23], v[72:75], v[180:183], v[20:23]
	v_mfma_f32_16x16x32_bf16 v[16:19], v[64:67], v[188:191], v[16:19]
	v_mfma_f32_16x16x32_bf16 v[12:15], v[72:75], v[188:191], v[12:15]
	v_mfma_f32_16x16x32_bf16 v[60:63], v[68:71], v[128:131], v[60:63]
	v_mfma_f32_16x16x32_bf16 v[48:51], v[76:79], v[128:131], v[48:51]
	v_mfma_f32_16x16x32_bf16 v[44:47], v[68:71], v[148:151], v[44:47]
	v_mfma_f32_16x16x32_bf16 v[36:39], v[76:79], v[148:151], v[36:39]
	v_mfma_f32_16x16x32_bf16 v[28:31], v[68:71], v[184:187], v[28:31]
	v_mfma_f32_16x16x32_bf16 v[20:23], v[76:79], v[184:187], v[20:23]
	v_mfma_f32_16x16x32_bf16 v[16:19], v[68:71], v[192:195], v[16:19]
	v_mfma_f32_16x16x32_bf16 v[12:15], v[76:79], v[192:195], v[12:15]
	s_barrier
	s_setprio 0
	s_add_u32 s54, s46, 0x80000
	s_addc_u32 s55, s47, 0
	s_add_i32 s53, s73, s60
	s_mov_b32 m0, s53
	s_nop 0
	global_load_lds_dwordx4 v164, s[54:55]
	s_add_i32 m0, s53, 0x2000
	s_nop 0
	global_load_lds_dwordx4 v160, s[54:55]
	s_add_i32 s53, 0, 0x18000
	v_add_u32_e32 v76, s53, v198
	ds_read_b128 v[64:67], v76
	ds_read_b128 v[68:71], v76 offset:1024
	ds_read_b128 v[72:75], v76 offset:2048
	ds_read_b128 v[76:79], v76 offset:3072
	s_waitcnt vmcnt(6)
	s_setprio 1
	s_barrier
; #define PG8_STAGE(bufoff, gbase, voff) do { _Pragma("unroll") for (int _i = 0; _i < 2; ++_i) \
;     __builtin_amdgcn_global_load_lds((const unsigned*)((const char*)(gbase) + (voff)[_i]), (LAS unsigned*)(lds + (bufoff) + ldsw + _i * 8192), 16, 0, 0); } while (0)
; #define PG8_LDA(dst, b, h) do { _Pragma("unroll") for (int m = 0; m < 4; ++m) _Pragma("unroll") for (int k = 0; k < 2; ++k) dst[m][k] = *(const LAS bf16x8*)(lds + PG8_SA(b, h) + aoff + m * 2048 + k * 1024); } while (0)
; #define PG8_LDB(dst, b, h) do { _Pragma("unroll") for (int n = 0; n < 2; ++n) _Pragma("unroll") for (int k = 0; k < 2; ++k) dst[n][k] = *(const LAS bf16x8*)(lds + PG8_SB(b, h) + boff + n * 2048 + k * 1024); } while (0)
; #define PG8_MMA(ai, bj, At, Bt) do { __builtin_amdgcn_s_setprio(1); _Pragma("unroll") for (int m = 0; m < 4; ++m) _Pragma("unroll") for (int n = 0; n < 2; ++n) _Pragma("unroll") for (int k = 0; k < 2; ++k) \
;     acc[ai][bj][m][n] = __builtin_amdgcn_mfma_f32_16x16x32_bf16(Bt[n][k], At[m][k], acc[ai][bj][m][n], 0, 0, 0); __builtin_amdgcn_s_setprio(0); } while (0)
; #define PG8_WAIT_V(n) asm volatile("s_waitcnt vmcnt(" #n ")" ::: "memory")
; #define PG8_WAIT_L(n) asm volatile("s_waitcnt lgkmcnt(" #n ")" ::: "memory")
; #define PG8_BAR __builtin_amdgcn_s_barrier()
; #define PG8_SCHED __builtin_amdgcn_sched_barrier(0)
; template <class Epi, class Sched = StaticOrder>
; DI void gemm_phase(LAS unsigned char* lds, const Gemm g, const Sched& S, const Epi& E) {
;     ...
;       PG8_WAIT_V(6); PG8_BAR; PG8_MMA(1, 1, At, B1); PG8_BAR;
;       PG8_LDB(B0, 1, 0); PG8_SCHED; PG8_LDA(At, 1, 0); PG8_STAGE(PG8_SA(0, 1), a2 + hstep, voffA);
;       PG8_WAIT_L(8); PG8_BAR; PG8_WAIT_L(0); PG8_MMA(0, 0, At, B0); PG8_BAR; PG8_SCHED;
;       PG8_LDB(B1, 1, 1); PG8_STAGE(PG8_SB(1, 0), b3, voffB);
;       PG8_BAR; PG8_WAIT_L(0); PG8_MMA(0, 1, At, B1); PG8_BAR;
;       PG8_LDA(At, 1, 1); PG8_STAGE(PG8_SA(1, 0), a3, voffA);
;       PG8_BAR; PG8_WAIT_L(0); PG8_MMA(1, 0, At, B0); PG8_BAR; PG8_SCHED;
	v_mfma_f32_16x16x32_bf16 v[56:59], v[206:209], v[120:123], v[56:59]
	v_mfma_f32_16x16x32_bf16 v[52:55], v[216:219], v[120:123], v[52:55]
	v_mfma_f32_16x16x32_bf16 v[40:43], v[206:209], v[136:139], v[40:43]
	v_mfma_f32_16x16x32_bf16 v[32:35], v[216:219], v[136:139], v[32:35]
	v_mfma_f32_16x16x32_bf16 v[24:27], v[206:209], v[180:183], v[24:27]
	v_mfma_f32_16x16x32_bf16 v[8:11], v[216:219], v[180:183], v[8:11]
	v_mfma_f32_16x16x32_bf16 v[4:7], v[206:209], v[188:191], v[4:7]
	v_mfma_f32_16x16x32_bf16 v[0:3], v[216:219], v[188:191], v[0:3]
	v_mfma_f32_16x16x32_bf16 v[56:59], v[212:215], v[128:131], v[56:59]
	v_mfma_f32_16x16x32_bf16 v[52:55], v[220:223], v[128:131], v[52:55]
	v_mfma_f32_16x16x32_bf16 v[40:43], v[212:215], v[148:151], v[40:43]
	v_mfma_f32_16x16x32_bf16 v[32:35], v[220:223], v[148:151], v[32:35]
	v_mfma_f32_16x16x32_bf16 v[24:27], v[212:215], v[184:187], v[24:27]
	v_mfma_f32_16x16x32_bf16 v[8:11], v[220:223], v[184:187], v[8:11]
	v_mfma_f32_16x16x32_bf16 v[4:7], v[212:215], v[192:195], v[4:7]
	v_mfma_f32_16x16x32_bf16 v[0:3], v[220:223], v[192:195], v[0:3]
	s_barrier
	s_setprio 0
	s_add_u32 s48, s48, 0x80000
	s_addc_u32 s49, s49, 0
	s_mov_b32 m0, s64
	ds_read_b128 v[120:123], v202 offset:32768
	ds_read_b128 v[128:131], v202 offset:33792
	ds_read_b128 v[180:183], v202 offset:34816
	ds_read_b128 v[184:187], v202 offset:35840
	ds_read_b128 v[188:191], v202 offset:36864
	ds_read_b128 v[192:195], v202 offset:37888
	ds_read_b128 v[206:209], v202 offset:38912
	ds_read_b128 v[212:215], v202 offset:39936
	global_load_lds_dwordx4 v166, s[48:49]
	s_mov_b32 m0, s65
	s_nop 0
	global_load_lds_dwordx4 v162, s[48:49]
	s_waitcnt lgkmcnt(8)
	s_setprio 1
	s_barrier
	s_waitcnt lgkmcnt(0)
	v_mfma_f32_16x16x32_bf16 v[136:139], v[64:67], v[120:123], v[156:159]
	v_mfma_f32_16x16x32_bf16 v[156:159], v[68:71], v[128:131], v[136:139]
	v_mfma_f32_16x16x32_bf16 v[136:139], v[72:75], v[120:123], v[144:147]
	v_mfma_f32_16x16x32_bf16 v[144:147], v[76:79], v[128:131], v[136:139]
	v_mfma_f32_16x16x32_bf16 v[136:139], v[64:67], v[180:183], v[140:143]
	v_mfma_f32_16x16x32_bf16 v[132:135], v[72:75], v[180:183], v[132:135]
	v_mfma_f32_16x16x32_bf16 v[124:127], v[64:67], v[188:191], v[124:127]
	v_mfma_f32_16x16x32_bf16 v[116:119], v[72:75], v[188:191], v[116:119]
	v_mfma_f32_16x16x32_bf16 v[112:115], v[64:67], v[206:209], v[112:115]
	v_mfma_f32_16x16x32_bf16 v[108:111], v[72:75], v[206:209], v[108:111]
	v_mfma_f32_16x16x32_bf16 v[140:143], v[68:71], v[184:187], v[136:139]
	v_mfma_f32_16x16x32_bf16 v[132:135], v[76:79], v[184:187], v[132:135]
	v_mfma_f32_16x16x32_bf16 v[124:127], v[68:71], v[192:195], v[124:127]
	v_mfma_f32_16x16x32_bf16 v[116:119], v[76:79], v[192:195], v[116:119]
	v_mfma_f32_16x16x32_bf16 v[112:115], v[68:71], v[212:215], v[112:115]
	v_mfma_f32_16x16x32_bf16 v[108:111], v[76:79], v[212:215], v[108:111]
	s_barrier
	s_setprio 0
	s_add_i32 s48, 0, 0x1c000
	v_add_u32_e32 v136, s48, v198
	s_add_i32 s49, s53, s60
	ds_read_b128 v[216:219], v136
	ds_read_b128 v[220:223], v136 offset:1024
	ds_read_b128 v[224:227], v136 offset:2048
	ds_read_b128 v[228:231], v136 offset:3072
	s_mov_b32 m0, s49
	s_nop 0
	global_load_lds_dwordx4 v164, s[98:99]
	s_add_i32 m0, s49, 0x2000
	s_nop 0
	global_load_lds_dwordx4 v160, s[98:99]
	s_setprio 1
	s_barrier
	s_waitcnt lgkmcnt(0)
	v_mfma_f32_16x16x32_bf16 v[80:83], v[224:227], v[120:123], v[80:83]
	v_mfma_f32_16x16x32_bf16 v[136:139], v[216:219], v[120:123], v[152:155]
	v_mfma_f32_16x16x32_bf16 v[148:151], v[228:231], v[128:131], v[80:83]
	v_mfma_f32_16x16x32_bf16 v[80:83], v[216:219], v[180:183], v[84:87]
	v_mfma_f32_16x16x32_bf16 v[152:155], v[220:223], v[128:131], v[136:139]
	v_mfma_f32_16x16x32_bf16 v[136:139], v[220:223], v[184:187], v[80:83]
	v_mfma_f32_16x16x32_bf16 v[80:83], v[224:227], v[180:183], v[92:95]
	v_mfma_f32_16x16x32_bf16 v[128:131], v[228:231], v[184:187], v[80:83]
	v_mfma_f32_16x16x32_bf16 v[80:83], v[216:219], v[188:191], v[96:99]
	v_mfma_f32_16x16x32_bf16 v[120:123], v[220:223], v[192:195], v[80:83]
	v_mfma_f32_16x16x32_bf16 v[80:83], v[224:227], v[188:191], v[104:107]
	v_mfma_f32_16x16x32_bf16 v[104:107], v[228:231], v[192:195], v[80:83]
	v_mfma_f32_16x16x32_bf16 v[80:83], v[216:219], v[206:209], v[100:103]
	v_mfma_f32_16x16x32_bf16 v[100:103], v[220:223], v[212:215], v[80:83]
	v_mfma_f32_16x16x32_bf16 v[80:83], v[224:227], v[206:209], v[88:91]
	v_mfma_f32_16x16x32_bf16 v[88:91], v[228:231], v[212:215], v[80:83]
	s_barrier
	s_setprio 0
	s_mov_b32 m0, s67
	s_nop 2
	ds_read_b128 v[80:83], v202 offset:49152
	ds_read_b128 v[84:87], v202 offset:50176
	ds_read_b128 v[92:95], v202 offset:51200
	ds_read_b128 v[96:99], v202 offset:52224
	ds_read_b128 v[180:183], v202 offset:53248
	ds_read_b128 v[184:187], v202 offset:54272
	ds_read_b128 v[188:191], v202 offset:55296
	ds_read_b128 v[192:195], v202 offset:56320
	global_load_lds_dwordx4 v166, s[100:101]
	s_mov_b32 m0, s68
	s_nop 0
	global_load_lds_dwordx4 v162, s[100:101]
	s_waitcnt vmcnt(10)
	s_setprio 1
	s_barrier
	s_waitcnt lgkmcnt(0)
	v_mfma_f32_16x16x32_bf16 v[60:63], v[64:67], v[80:83], v[60:63]
	v_mfma_f32_16x16x32_bf16 v[48:51], v[72:75], v[80:83], v[48:51]
	v_mfma_f32_16x16x32_bf16 v[44:47], v[64:67], v[92:95], v[44:47]
	v_mfma_f32_16x16x32_bf16 v[36:39], v[72:75], v[92:95], v[36:39]
	v_mfma_f32_16x16x32_bf16 v[28:31], v[64:67], v[180:183], v[28:31]
	v_mfma_f32_16x16x32_bf16 v[20:23], v[72:75], v[180:183], v[20:23]
	v_mfma_f32_16x16x32_bf16 v[16:19], v[64:67], v[188:191], v[16:19]
	v_mfma_f32_16x16x32_bf16 v[12:15], v[72:75], v[188:191], v[12:15]
	v_mfma_f32_16x16x32_bf16 v[60:63], v[68:71], v[84:87], v[60:63]
	v_mfma_f32_16x16x32_bf16 v[48:51], v[76:79], v[84:87], v[48:51]
	v_mfma_f32_16x16x32_bf16 v[44:47], v[68:71], v[96:99], v[44:47]
	v_mfma_f32_16x16x32_bf16 v[36:39], v[76:79], v[96:99], v[36:39]
	v_mfma_f32_16x16x32_bf16 v[28:31], v[68:71], v[184:187], v[28:31]
	v_mfma_f32_16x16x32_bf16 v[20:23], v[76:79], v[184:187], v[20:23]
	v_mfma_f32_16x16x32_bf16 v[16:19], v[68:71], v[192:195], v[16:19]
	v_mfma_f32_16x16x32_bf16 v[12:15], v[76:79], v[192:195], v[12:15]
	s_barrier
; #define PG8_STAGE(bufoff, gbase, voff) do { _Pragma("unroll") for (int _i = 0; _i < 2; ++_i) \
;     __builtin_amdgcn_global_load_lds((const unsigned*)((const char*)(gbase) + (voff)[_i]), (LAS unsigned*)(lds + (bufoff) + ldsw + _i * 8192), 16, 0, 0); } while (0)
; #define PG8_MMA(ai, bj, At, Bt) do { __builtin_amdgcn_s_setprio(1); _Pragma("unroll") for (int m = 0; m < 4; ++m) _Pragma("unroll") for (int n = 0; n < 2; ++n) _Pragma("unroll") for (int k = 0; k < 2; ++k) \
;     acc[ai][bj][m][n] = __builtin_amdgcn_mfma_f32_16x16x32_bf16(Bt[n][k], At[m][k], acc[ai][bj][m][n], 0, 0, 0); __builtin_amdgcn_s_setprio(0); } while (0)
; #define PG8_WAIT_V(n) asm volatile("s_waitcnt vmcnt(" #n ")" ::: "memory")
; #define PG8_BAR __builtin_amdgcn_s_barrier()
; DI float row_rstd(const float* ssq, int row, int fq) {
;   const f32x4 a = *(const f32x4*)(ssq + (size_t)row * 32 + fq * 8), b = *(const f32x4*)(ssq + (size_t)row * 32 + fq * 8 + 4);
;   float sm = ((a[0] + a[1]) + (a[2] + a[3])) + ((b[0] + b[1]) + (b[2] + b[3]));
;   sm += __shfl_xor(sm, 16); sm += __shfl_xor(sm, 32);
;   return rsqrtf(sm * (1.0f / 2048.f) + 1e-6f);
; }
;   DI void operator()(const f32x4 (&acc)[2][2][4][2], const Unit& u, int wr, int wc, int fr, int fq) const {
;     const int col = u.pn * 128 + wc * 32 + 8 * fq;
;     float w0[8], w1[8], w2[8], bb[8];
; #pragma unroll
;     for (int e = 0; e < 8; ++e) { w0[e] = cw[col + e]; w1[e] = cw[5632 + col + e]; w2[e] = cw[2 * 5632 + col + e]; bb[e] = cb[col + e]; }
; #pragma unroll
;     for (int ai = 0; ai < 2; ++ai) {
;       const int row0 = u.pm * BM + ai * HALF + wr * 64, span = row0 >> 6;
;       float rsv[4];
; #pragma unroll
;       for (int m = 0; m < 4; ++m) rsv[m] = row_rstd(ssq, row0 + 16 * m + fr, fq);
; template <class Epi, class Sched = StaticOrder>
; DI void gemm_phase(LAS unsigned char* lds, const Gemm g, const Sched& S, const Epi& E) {
;     ...
;       PG8_STAGE(PG8_SB(1, 1), b3 + hstep, voffB);
;       PG8_WAIT_V(6); PG8_BAR; PG8_MMA(1, 1, At, B1); PG8_BAR;
	s_setprio 0
	s_add_u32 s46, s46, 0x80080
	s_addc_u32 s47, s47, 0
	s_add_i32 s48, s48, s60
	s_mov_b32 m0, s48
	s_nop 0
	global_load_lds_dwordx4 v164, s[46:47]
	s_add_i32 m0, s48, 0x2000
	s_nop 0
	global_load_lds_dwordx4 v160, s[46:47]
	ds_read_b128 v[64:67], v201
	ds_read_b128 v[68:71], v201 offset:1024
	ds_read_b128 v[72:75], v201 offset:2048
	ds_read_b128 v[76:79], v201 offset:3072
	s_waitcnt vmcnt(6)
	s_setprio 1
	s_barrier
	v_mfma_f32_16x16x32_bf16 v[56:59], v[216:219], v[80:83], v[56:59]
	v_mfma_f32_16x16x32_bf16 v[52:55], v[224:227], v[80:83], v[52:55]
	v_mfma_f32_16x16x32_bf16 v[40:43], v[216:219], v[92:95], v[40:43]
	v_mfma_f32_16x16x32_bf16 v[32:35], v[224:227], v[92:95], v[32:35]
	v_mfma_f32_16x16x32_bf16 v[24:27], v[216:219], v[180:183], v[24:27]
	v_mfma_f32_16x16x32_bf16 v[8:11], v[224:227], v[180:183], v[8:11]
	v_mfma_f32_16x16x32_bf16 v[4:7], v[216:219], v[188:191], v[4:7]
	v_mfma_f32_16x16x32_bf16 v[0:3], v[224:227], v[188:191], v[0:3]
	v_mfma_f32_16x16x32_bf16 v[56:59], v[220:223], v[84:87], v[56:59]
	v_mfma_f32_16x16x32_bf16 v[52:55], v[228:231], v[84:87], v[52:55]
	v_mfma_f32_16x16x32_bf16 v[40:43], v[220:223], v[96:99], v[40:43]
	v_mfma_f32_16x16x32_bf16 v[32:35], v[228:231], v[96:99], v[32:35]
	v_mfma_f32_16x16x32_bf16 v[24:27], v[220:223], v[184:187], v[24:27]
	v_mfma_f32_16x16x32_bf16 v[8:11], v[228:231], v[184:187], v[8:11]
	v_mfma_f32_16x16x32_bf16 v[4:7], v[220:223], v[192:195], v[4:7]
	v_mfma_f32_16x16x32_bf16 v[0:3], v[228:231], v[192:195], v[0:3]
	s_add_i32 s52, s52, 2
	s_add_u32 s14, s14, 0x100
	s_addc_u32 s15, s15, 0
	s_add_u32 s44, s44, 0x100
	s_addc_u32 s45, s45, 0
	s_cmp_gt_u32 s52, 29
	s_barrier
	s_setprio 0
	s_cbranch_scc0 .LBB0_811
	s_waitcnt lgkmcnt(0)
	s_lshl_b32 s35, s12, 8
	s_add_i32 s35, s35, s66
	v_or_b32_e32 v190, s35, v179
	v_ashrrev_i32_e32 v191, 31, v190
	v_lshlrev_b64 v[64:65], 7, v[190:191]
	v_or_b32_e32 v188, 16, v190
	v_lshl_add_u64 v[64:65], v[168:169], 0, v[64:65]
	v_ashrrev_i32_e32 v189, 31, v188
	global_load_dwordx4 v[192:195], v[64:65], off
	global_load_dwordx4 v[206:209], v[64:65], off offset:16
	v_lshlrev_b64 v[64:65], 7, v[188:189]
	v_lshl_add_u64 v[64:65], v[168:169], 0, v[64:65]
	global_load_dwordx4 v[212:215], v[64:65], off
	global_load_dwordx4 v[216:219], v[64:65], off offset:16
	v_or_b32_e32 v186, 32, v190
	v_ashrrev_i32_e32 v187, 31, v186
	v_lshlrev_b64 v[64:65], 7, v[186:187]
	v_or_b32_e32 v184, 48, v190
	v_lshl_add_u64 v[64:65], v[168:169], 0, v[64:65]
	v_ashrrev_i32_e32 v185, 31, v184
	global_load_dwordx4 v[220:223], v[64:65], off
	global_load_dwordx4 v[224:227], v[64:65], off offset:16
	v_lshlrev_b64 v[64:65], 7, v[184:185]
	v_lshl_add_u64 v[64:65], v[168:169], 0, v[64:65]
	global_load_dwordx4 v[228:231], v[64:65], off
	global_load_dwordx4 v[232:235], v[64:65], off offset:16
	v_lshl_or_b32 v180, s13, 7, v200
	v_and_b32_e32 v65, 64, v204
	v_xor_b32_e32 v64, 16, v204
	v_ashrrev_i32_e32 v181, 31, v180
	v_add_u32_e32 v65, 64, v65
	v_readlane_b32 s44, v243, 3
	v_xor_b32_e32 v66, 32, v204
	v_lshlrev_b64 v[182:183], 2, v[180:181]
	v_cmp_lt_i32_e32 vcc, v64, v65
	v_readlane_b32 s52, v243, 11
	v_readlane_b32 s53, v243, 12
	v_cndmask_b32_e32 v64, v204, v64, vcc
	v_cmp_lt_i32_e32 vcc, v66, v65
	v_lshl_add_u64 v[92:93], s[52:53], 0, v[182:183]
	v_readlane_b32 s54, v243, 13
	v_cndmask_b32_e32 v65, v204, v66, vcc
	v_add_co_u32_e32 v94, vcc, 0x5000, v92
	v_readlane_b32 s55, v243, 14
	s_nop 0
	v_addc_co_u32_e32 v95, vcc, 0, v93, vcc
	v_add_co_u32_e32 v96, vcc, 0xb000, v92
	v_lshl_add_u64 v[72:73], s[54:55], 0, v[182:183]
	v_lshl_add_u64 v[74:75], v[92:93], 0, s[26:27]
	v_lshl_add_u64 v[76:77], v[92:93], 0, s[28:29]
	v_addc_co_u32_e32 v97, vcc, 0, v93, vcc
	v_lshlrev_b32_e32 v187, 2, v64
	v_lshlrev_b32_e32 v185, 2, v65
	global_load_dwordx4 v[64:67], v[92:93], off offset:16
	global_load_dwordx4 v[80:83], v[92:93], off
	global_load_dwordx4 v[68:71], v[72:73], off offset:16
	global_load_dwordx4 v[84:87], v[72:73], off
	s_nop 0
	global_load_dwordx4 v[72:75], v[74:75], off offset:16
	s_nop 0
	global_load_dwordx4 v[76:79], v[76:77], off offset:16
	s_nop 0
	global_load_dwordx4 v[92:95], v[94:95], off offset:2048
	s_nop 0
	global_load_dwordx4 v[96:99], v[96:97], off
	v_mov_b32_e32 v211, 0
	v_mov_b32_e32 v205, 0
	v_readlane_b32 s45, v243, 4
	v_readlane_b32 s46, v243, 5
	v_readlane_b32 s47, v243, 6
	v_readlane_b32 s48, v243, 7
	v_readlane_b32 s49, v243, 8
	v_readlane_b32 s50, v243, 9
	v_readlane_b32 s51, v243, 10
	v_readlane_b32 s56, v243, 15
	v_readlane_b32 s57, v243, 16
	v_readlane_b32 s58, v243, 17
	v_readlane_b32 s59, v243, 18
	s_waitcnt vmcnt(0)
	v_mov_b32_e32 v196, v192
	v_mov_b32_e32 v197, v206
	v_mov_b32_e32 v206, v193
	v_mov_b32_e32 v192, v194
	v_mov_b32_e32 v193, v208
	v_mov_b32_e32 v208, v195
	v_pk_add_f32 v[194:195], v[196:197], v[206:207]
	v_pk_add_f32 v[192:193], v[192:193], v[208:209]
	v_mov_b32_e32 v196, v212
	v_mov_b32_e32 v197, v216
	v_mov_b32_e32 v216, v213
	v_mov_b32_e32 v206, v214
	v_mov_b32_e32 v207, v218
	v_mov_b32_e32 v218, v215
	v_pk_add_f32 v[192:193], v[194:195], v[192:193]
	v_pk_add_f32 v[194:195], v[196:197], v[216:217]
	v_pk_add_f32 v[196:197], v[206:207], v[218:219]
	v_mov_b32_e32 v208, v220
	v_pk_add_f32 v[194:195], v[194:195], v[196:197]
	v_mov_b32_e32 v197, v192
	v_mov_b32_e32 v196, v194
	v_mov_b32_e32 v192, v195
	v_pk_add_f32 v[192:193], v[196:197], v[192:193]
	ds_bpermute_b32 v195, v187, v193
	ds_bpermute_b32 v194, v187, v192
	v_mov_b32_e32 v209, v224
	v_mov_b32_e32 v224, v221
	v_mov_b32_e32 v212, v222
	v_mov_b32_e32 v213, v226
	s_waitcnt lgkmcnt(0)
; DI unsigned pack2(float lo, float hi) { f32x2 v = {lo, hi}; bf16v2 r = __builtin_convertvector(v, bf16v2); return __builtin_bit_cast(unsigned, r); }
; DI float silu_f(float x) { return x * sigmoid_f(x); }
; DI float dpp_ror1(float v) { return __int_as_float(__builtin_amdgcn_update_dpp(0, __float_as_int(v), 0x121, 0xf, 0xf, false)); }
; DI float row_rstd(const float* ssq, int row, int fq) {
;   const f32x4 a = *(const f32x4*)(ssq + (size_t)row * 32 + fq * 8), b = *(const f32x4*)(ssq + (size_t)row * 32 + fq * 8 + 4);
;   float sm = ((a[0] + a[1]) + (a[2] + a[3])) + ((b[0] + b[1]) + (b[2] + b[3]));
;   sm += __shfl_xor(sm, 16); sm += __shfl_xor(sm, 32);
;   return rsqrtf(sm * (1.0f / 2048.f) + 1e-6f);
; }
;   DI void operator()(const f32x4 (&acc)[2][2][4][2], const Unit& u, int wr, int wc, int fr, int fq) const {
;     ...
;       float p1[8], p2[8];
; #pragma unroll
;       for (int e = 0; e < 8; ++e) { p1[e] = 0.f; p2[e] = 0.f; }
; #pragma unroll
;       for (int m = 0; m < 4; ++m) {
;         float g[8], uu[8], a[8];
;         const float rs = rsv[m];
; #pragma unroll
;         for (int e = 0; e < 4; ++e) { g[e] = acc[ai][0][m][0][e] * rs; g[4 + e] = acc[ai][0][m][1][e] * rs; uu[e] = acc[ai][1][m][0][e] * rs; uu[4 + e] = acc[ai][1][m][1][e] * rs; }
; #pragma unroll
;         for (int e = 0; e < 8; ++e) {
;           const float x1 = dpp_ror1(g[e]), x2 = dpp_ror2(g[e]);
;           const float pr1 = (fr == 0) ? p1[e] : x1, pr2 = (fr < 2) ? p2[e] : x2;
;           a[e] = w2[e] * g[e] + w1[e] * pr1 + w0[e] * pr2 + bb[e];
;           p1[e] = x1; p2[e] = x2;
;         }
;         if (m == 0 && fr < 2) {
;           float* ha = headA + (size_t)(span * 2 + fr) * 5632 + col; float* hu = headU + (size_t)(span * 2 + fr) * 5632 + col;
;           *(f32x4*)ha = (f32x4){a[0], a[1], a[2], a[3]}; *(f32x4*)(ha + 4) = (f32x4){a[4], a[5], a[6], a[7]};
;           *(f32x4*)hu = (f32x4){uu[0], uu[1], uu[2], uu[3]}; *(f32x4*)(hu + 4) = (f32x4){uu[4], uu[5], uu[6], uu[7]};
;         } else {
;           u32x4 w;
;           w.x = pack2(silu_f(a[0]) * uu[0], silu_f(a[1]) * uu[1]);
;           w.y = pack2(silu_f(a[2]) * uu[2], silu_f(a[3]) * uu[3]);
;           w.z = pack2(silu_f(a[4]) * uu[4], silu_f(a[5]) * uu[5]);
;           w.w = pack2(silu_f(a[6]) * uu[6], silu_f(a[7]) * uu[7]);
;           *(u32x4*)(H + (size_t)(row0 + 16 * m + fr) * 5632 + col) = w;
;         }
	v_pk_add_f32 v[192:193], v[192:193], v[194:195]
	ds_bpermute_b32 v195, v185, v193
	ds_bpermute_b32 v194, v185, v192
	v_mov_b32_e32 v226, v223
	v_mov_b32_e32 v196, v228
	v_mov_b32_e32 v197, v232
	v_mov_b32_e32 v232, v229
	s_waitcnt lgkmcnt(0)
	v_pk_add_f32 v[192:193], v[192:193], v[194:195]
	v_mov_b32_e32 v206, v230
	v_pk_fma_f32 v[192:193], v[192:193], s[30:31], v[178:179] op_sel_hi:[1,0,0]
	v_mov_b32_e32 v207, v234
	v_mul_f32_e32 v189, 0x4b800000, v193
	v_cmp_gt_f32_e64 s[12:13], s74, v193
	v_mov_b32_e32 v234, v231
	v_pk_add_f32 v[208:209], v[208:209], v[224:225]
	v_cndmask_b32_e64 v189, v193, v189, s[12:13]
	v_rsq_f32_e32 v189, v189
	v_pk_add_f32 v[212:213], v[212:213], v[226:227]
	v_pk_add_f32 v[196:197], v[196:197], v[232:233]
	v_pk_add_f32 v[194:195], v[206:207], v[234:235]
	v_mul_f32_e32 v191, 0x45800000, v189
	v_cndmask_b32_e64 v220, v189, v191, s[12:13]
	v_pk_add_f32 v[208:209], v[208:209], v[212:213]
	v_pk_add_f32 v[194:195], v[196:197], v[194:195]
	v_pk_mul_f32 v[156:157], v[156:157], v[220:221] op_sel_hi:[1,0]
	v_mov_b32_e32 v216, 0
	v_mov_b32_e32 v218, 0
	v_mov_b32_e32 v196, v194
	v_mov_b32_e32 v197, v208
	v_mov_b32_e32 v208, v195
	v_mov_b32_dpp v216, v156 row_ror:1 row_mask:0xf bank_mask:0xf
	v_mov_b32_dpp v218, v157 row_ror:1 row_mask:0xf bank_mask:0xf
	v_pk_add_f32 v[194:195], v[196:197], v[208:209]
	v_cndmask_b32_e64 v207, v218, 0, s[0:1]
	v_cndmask_b32_e64 v206, v216, 0, s[0:1]
	v_pk_mul_f32 v[158:159], v[158:159], v[220:221] op_sel_hi:[1,0]
	v_mov_b32_e32 v212, 0
	v_mov_b32_e32 v214, 0
	ds_bpermute_b32 v197, v187, v195
	ds_bpermute_b32 v196, v187, v194
	v_mov_b32_e32 v215, 0
	v_mov_b32_e32 v217, 0
	v_pk_mul_f32 v[206:207], v[92:93], v[206:207]
	v_mov_b32_dpp v212, v158 row_ror:1 row_mask:0xf bank_mask:0xf
	v_mov_b32_dpp v214, v159 row_ror:1 row_mask:0xf bank_mask:0xf
	v_mov_b32_dpp v215, v156 row_ror:2 row_mask:0xf bank_mask:0xf
	v_mov_b32_dpp v217, v157 row_ror:2 row_mask:0xf bank_mask:0xf
	v_pk_fma_f32 v[156:157], v[96:97], v[156:157], v[206:207]
	v_mov_b32_e32 v213, 0
	v_cndmask_b32_e64 v207, v214, 0, s[0:1]
	v_cndmask_b32_e64 v206, v212, 0, s[0:1]
	v_cndmask_b32_e64 v209, v217, 0, s[4:5]
	v_cndmask_b32_e64 v208, v215, 0, s[4:5]
	v_mov_b32_dpp v211, v158 row_ror:2 row_mask:0xf bank_mask:0xf
	v_mov_b32_dpp v213, v159 row_ror:2 row_mask:0xf bank_mask:0xf
	v_pk_mul_f32 v[206:207], v[94:95], v[206:207]
	v_pk_fma_f32 v[156:157], v[80:81], v[208:209], v[156:157]
	v_cndmask_b32_e64 v209, v213, 0, s[4:5]
	v_cndmask_b32_e64 v208, v211, 0, s[4:5]
	v_pk_fma_f32 v[158:159], v[98:99], v[158:159], v[206:207]
	v_pk_mul_f32 v[144:145], v[144:145], v[220:221] op_sel_hi:[1,0]
	v_pk_fma_f32 v[158:159], v[82:83], v[208:209], v[158:159]
	v_mov_b32_e32 v207, 0
	v_mov_b32_e32 v209, 0
	v_pk_mul_f32 v[146:147], v[146:147], v[220:221] op_sel_hi:[1,0]
	v_mov_b32_e32 v191, 0
	s_waitcnt lgkmcnt(0)
	v_pk_add_f32 v[194:195], v[194:195], v[196:197]
	v_mov_b32_dpp v207, v144 row_ror:1 row_mask:0xf bank_mask:0xf
	v_mov_b32_dpp v209, v145 row_ror:1 row_mask:0xf bank_mask:0xf
	v_mov_b32_dpp v191, v146 row_ror:1 row_mask:0xf bank_mask:0xf
	v_mov_b32_dpp v205, v147 row_ror:1 row_mask:0xf bank_mask:0xf
	ds_bpermute_b32 v197, v185, v195
	ds_bpermute_b32 v196, v185, v194
	v_pk_mul_f32 v[152:153], v[152:153], v[220:221] op_sel_hi:[1,0]
	v_pk_mul_f32 v[148:149], v[148:149], v[220:221] op_sel_hi:[1,0]
	v_pk_mul_f32 v[154:155], v[154:155], v[220:221] op_sel_hi:[1,0]
	v_pk_mul_f32 v[150:151], v[150:151], v[220:221] op_sel_hi:[1,0]
	v_mov_b32_e32 v206, 0
	v_mov_b32_e32 v208, 0
	v_cndmask_b32_e64 v223, v209, 0, s[0:1]
	v_cndmask_b32_e64 v222, v207, 0, s[0:1]
	v_mov_b32_e32 v189, 0
	v_mov_b32_e32 v193, 0
	v_cndmask_b32_e64 v221, v205, 0, s[0:1]
	v_cndmask_b32_e64 v220, v191, 0, s[0:1]
	v_mov_b32_dpp v206, v144 row_ror:2 row_mask:0xf bank_mask:0xf
	v_mov_b32_dpp v208, v145 row_ror:2 row_mask:0xf bank_mask:0xf
	v_pk_mul_f32 v[222:223], v[72:73], v[222:223]
	v_mov_b32_dpp v189, v146 row_ror:2 row_mask:0xf bank_mask:0xf
	v_mov_b32_dpp v193, v147 row_ror:2 row_mask:0xf bank_mask:0xf
	v_pk_mul_f32 v[220:221], v[74:75], v[220:221]
	v_cndmask_b32_e64 v225, v208, 0, s[4:5]
	v_cndmask_b32_e64 v224, v206, 0, s[4:5]
	v_pk_fma_f32 v[144:145], v[76:77], v[144:145], v[222:223]
	v_cndmask_b32_e64 v223, v193, 0, s[4:5]
	v_cndmask_b32_e64 v222, v189, 0, s[4:5]
	v_pk_fma_f32 v[146:147], v[78:79], v[146:147], v[220:221]
	v_pk_fma_f32 v[144:145], v[64:65], v[224:225], v[144:145]
	v_pk_fma_f32 v[146:147], v[66:67], v[222:223], v[146:147]
	v_cmp_gt_f32_e32 vcc, s74, v192
	v_pk_add_f32 v[156:157], v[84:85], v[156:157]
	v_pk_add_f32 v[158:159], v[86:87], v[158:159]
	v_pk_add_f32 v[144:145], v[68:69], v[144:145]
	v_pk_add_f32 v[146:147], v[70:71], v[146:147]
	s_and_saveexec_b64 s[12:13], s[10:11]
	s_xor_b64 s[12:13], exec, s[12:13]
	s_cbranch_execz .LBB0_814
	v_mul_f32_e32 v219, 0xbfb8aa3b, v156
	v_exp_f32_e32 v219, v219
	v_mul_f32_e32 v220, 0xbfb8aa3b, v157
	v_exp_f32_e32 v220, v220
	v_mul_f32_e32 v222, 0xbfb8aa3b, v159
	v_add_f32_e32 v219, 1.0, v219
	v_exp_f32_e32 v223, v222
	v_add_f32_e32 v221, 1.0, v220
	v_rcp_f32_e32 v220, v219
	v_mul_f32_e32 v219, 0xbfb8aa3b, v158
	v_exp_f32_e32 v219, v219
	v_rcp_f32_e32 v221, v221
	v_add_f32_e32 v219, 1.0, v219
	v_rcp_f32_e32 v222, v219
	v_add_f32_e32 v219, 1.0, v223
	v_rcp_f32_e32 v223, v219
	v_pk_mul_f32 v[156:157], v[156:157], v[220:221]
	s_nop 0
	v_pk_mul_f32 v[152:153], v[152:153], v[156:157]
	v_pk_mul_f32 v[156:157], v[158:159], v[222:223]
	v_cvt_pk_bf16_f32 v152, v152, v153
	v_mul_f32_e32 v153, 0xbfb8aa3b, v144
	v_pk_mul_f32 v[154:155], v[154:155], v[156:157]
	v_exp_f32_e32 v156, v153
	v_mul_f32_e32 v153, 0xbfb8aa3b, v145
	v_exp_f32_e32 v157, v153
	v_cvt_pk_bf16_f32 v153, v154, v155
	v_add_f32_e32 v154, 1.0, v156
	v_mul_f32_e32 v156, 0xbfb8aa3b, v146
	v_add_f32_e32 v155, 1.0, v157
	v_mul_f32_e32 v157, 0xbfb8aa3b, v147
	v_exp_f32_e32 v156, v156
	v_exp_f32_e32 v157, v157
	v_rcp_f32_e32 v154, v154
	v_rcp_f32_e32 v155, v155
	v_add_f32_e32 v156, 1.0, v156
	v_add_f32_e32 v157, 1.0, v157
	v_rcp_f32_e32 v156, v156
	v_rcp_f32_e32 v157, v157
	v_pk_mul_f32 v[144:145], v[144:145], v[154:155]
	s_nop 0
	v_pk_mul_f32 v[144:145], v[148:149], v[144:145]
	s_nop 0
	v_cvt_pk_bf16_f32 v154, v144, v145
	v_pk_mul_f32 v[144:145], v[146:147], v[156:157]
	s_nop 0
	v_pk_mul_f32 v[144:145], v[150:151], v[144:145]
	s_nop 0
	v_cvt_pk_bf16_f32 v155, v144, v145
	v_mov_b64_e32 v[144:145], s[16:17]
	v_mad_i64_i32 v[144:145], s[14:15], v190, s75, v[144:145]
	v_lshl_add_u64 v[144:145], v[180:181], 1, v[144:145]
	global_store_dwordx4 v[144:145], v[152:155], off

; #define PG8_STAGE(bufoff, gbase, voff) do { _Pragma("unroll") for (int _i = 0; _i < 2; ++_i) \
;     __builtin_amdgcn_global_load_lds((const unsigned*)((const char*)(gbase) + (voff)[_i]), (LAS unsigned*)(lds + (bufoff) + ldsw + _i * 8192), 16, 0, 0); } while (0)
; #define PG8_LDA(dst, b, h) do { _Pragma("unroll") for (int m = 0; m < 4; ++m) _Pragma("unroll") for (int k = 0; k < 2; ++k) dst[m][k] = *(const LAS bf16x8*)(lds + PG8_SA(b, h) + aoff + m * 2048 + k * 1024); } while (0)
; #define PG8_LDB(dst, b, h) do { _Pragma("unroll") for (int n = 0; n < 2; ++n) _Pragma("unroll") for (int k = 0; k < 2; ++k) dst[n][k] = *(const LAS bf16x8*)(lds + PG8_SB(b, h) + boff + n * 2048 + k * 1024); } while (0)
; #define PG8_MMA(ai, bj, At, Bt) do { __builtin_amdgcn_s_setprio(1); _Pragma("unroll") for (int m = 0; m < 4; ++m) _Pragma("unroll") for (int n = 0; n < 2; ++n) _Pragma("unroll") for (int k = 0; k < 2; ++k) \
;     acc[ai][bj][m][n] = __builtin_amdgcn_mfma_f32_16x16x32_bf16(Bt[n][k], At[m][k], acc[ai][bj][m][n], 0, 0, 0); __builtin_amdgcn_s_setprio(0); } while (0)
; #define PG8_WAIT_V(n) asm volatile("s_waitcnt vmcnt(" #n ")" ::: "memory")
; #define PG8_WAIT_L(n) asm volatile("s_waitcnt lgkmcnt(" #n ")" ::: "memory")
; #define PG8_BAR __builtin_amdgcn_s_barrier()
; #define PG8_SCHED __builtin_amdgcn_sched_barrier(0)
; template <class Epi, class Sched = StaticOrder>
; DI void gemm_phase(LAS unsigned char* lds, const Gemm g, const Sched& S, const Epi& E) {
;     ...
;     for (int t = 0; t < nt; t += 2) {
;       const bool last = (t == nt - 2);
;       const char* a1 = cA + (size_t)(t + 1) * kstep;
;       const char* a2 = last ? nA : cA + (size_t)(t + 2) * kstep; const char* b2 = last ? nB : cB + (size_t)(t + 2) * kstep;
;       const char* a3 = a2 + kstep; const char* b3 = b2 + kstep;
;       PG8_LDB(B0, 0, 0); PG8_SCHED; PG8_LDA(At, 0, 0); PG8_STAGE(PG8_SA(1, 1), a1 + hstep, voffA);
;       PG8_WAIT_L(8); PG8_BAR; PG8_WAIT_L(0); PG8_MMA(0, 0, At, B0); PG8_BAR; PG8_SCHED;
;       PG8_LDB(B1, 0, 1); PG8_STAGE(PG8_SB(0, 0), b2, voffB);
;       PG8_BAR; PG8_WAIT_L(0); PG8_MMA(0, 1, At, B1); PG8_BAR;
;       PG8_LDA(At, 0, 1); PG8_STAGE(PG8_SA(0, 0), a2, voffA);
;       PG8_BAR; PG8_WAIT_L(0); PG8_MMA(1, 0, At, B0); PG8_BAR; PG8_SCHED;
;       PG8_STAGE(PG8_SB(0, 1), b2 + hstep, voffB);
;       PG8_WAIT_V(6); PG8_BAR; PG8_MMA(1, 1, At, B1); PG8_BAR;
.LBB0_961:
	s_add_u32 s20, s18, 0xffea0080
	s_addc_u32 s21, s19, -1
	s_cmpk_eq_i32 s44, 0x54
	s_cselect_b32 s23, s5, s21
	s_cselect_b32 s22, s4, s20
	s_cselect_b32 s21, s7, s43
	s_cselect_b32 s20, s6, s42
	s_add_i32 m0, s31, 0xc000
	ds_read_b128 v[144:147], v215
	ds_read_b128 v[148:151], v215 offset:1024
	ds_read_b128 v[152:155], v215 offset:2048
	ds_read_b128 v[156:159], v215 offset:3072
	ds_read_b128 v[160:163], v215 offset:4096
	ds_read_b128 v[164:167], v215 offset:5120
	ds_read_b128 v[168:171], v215 offset:6144
	ds_read_b128 v[172:175], v215 offset:7168
	global_load_lds_dwordx4 v184, s[18:19]
	s_add_i32 m0, s31, 0xe000
	s_nop 0
	global_load_lds_dwordx4 v186, s[18:19]
	s_waitcnt lgkmcnt(8)
	s_setprio 1
	s_barrier
	s_waitcnt lgkmcnt(0)
	v_mfma_f32_16x16x32_bf16 v[124:127], v[128:131], v[144:147], v[124:127]
	v_mfma_f32_16x16x32_bf16 v[120:123], v[136:139], v[144:147], v[120:123]
	v_mfma_f32_16x16x32_bf16 v[108:111], v[128:131], v[152:155], v[108:111]
	v_mfma_f32_16x16x32_bf16 v[104:107], v[136:139], v[152:155], v[104:107]
	v_mfma_f32_16x16x32_bf16 v[92:95], v[128:131], v[160:163], v[92:95]
	v_mfma_f32_16x16x32_bf16 v[88:91], v[136:139], v[160:163], v[88:91]
	v_mfma_f32_16x16x32_bf16 v[76:79], v[128:131], v[168:171], v[76:79]
	v_mfma_f32_16x16x32_bf16 v[72:75], v[136:139], v[168:171], v[72:75]
	v_mfma_f32_16x16x32_bf16 v[124:127], v[132:135], v[148:151], v[124:127]
	v_mfma_f32_16x16x32_bf16 v[120:123], v[140:143], v[148:151], v[120:123]
	v_mfma_f32_16x16x32_bf16 v[108:111], v[132:135], v[156:159], v[108:111]
	v_mfma_f32_16x16x32_bf16 v[104:107], v[140:143], v[156:159], v[104:107]
	v_mfma_f32_16x16x32_bf16 v[92:95], v[132:135], v[164:167], v[92:95]
	v_mfma_f32_16x16x32_bf16 v[88:91], v[140:143], v[164:167], v[88:91]
	v_mfma_f32_16x16x32_bf16 v[76:79], v[132:135], v[172:175], v[76:79]
	v_mfma_f32_16x16x32_bf16 v[72:75], v[140:143], v[172:175], v[72:75]
	s_barrier
	s_setprio 0
	s_add_i32 s45, s46, s30
	s_add_u32 s98, s20, 0x80
	s_addc_u32 s99, s21, 0
	s_add_u32 s100, s22, 0x80
	s_addc_u32 s101, s23, 0
	s_mov_b32 m0, s45
	ds_read_b128 v[192:195], v216
	ds_read_b128 v[196:199], v216 offset:1024
	ds_read_b128 v[200:203], v216 offset:2048
	ds_read_b128 v[204:207], v216 offset:3072
	global_load_lds_dwordx4 v178, s[20:21]
	s_add_i32 m0, s45, 0x2000
	s_nop 0
	global_load_lds_dwordx4 v182, s[20:21]
	s_setprio 1
	s_barrier
	s_waitcnt lgkmcnt(0)
	v_mfma_f32_16x16x32_bf16 v[116:119], v[192:195], v[144:147], v[116:119]
	v_mfma_f32_16x16x32_bf16 v[112:115], v[200:203], v[144:147], v[112:115]
	v_mfma_f32_16x16x32_bf16 v[100:103], v[192:195], v[152:155], v[100:103]
	v_mfma_f32_16x16x32_bf16 v[96:99], v[200:203], v[152:155], v[96:99]
	v_mfma_f32_16x16x32_bf16 v[84:87], v[192:195], v[160:163], v[84:87]
	v_mfma_f32_16x16x32_bf16 v[80:83], v[200:203], v[160:163], v[80:83]
	v_mfma_f32_16x16x32_bf16 v[68:71], v[192:195], v[168:171], v[68:71]
	v_mfma_f32_16x16x32_bf16 v[64:67], v[200:203], v[168:171], v[64:67]
	v_mfma_f32_16x16x32_bf16 v[116:119], v[196:199], v[148:151], v[116:119]
	v_mfma_f32_16x16x32_bf16 v[112:115], v[204:207], v[148:151], v[112:115]
	v_mfma_f32_16x16x32_bf16 v[100:103], v[196:199], v[156:159], v[100:103]
	v_mfma_f32_16x16x32_bf16 v[96:99], v[204:207], v[156:159], v[96:99]
	v_mfma_f32_16x16x32_bf16 v[84:87], v[196:199], v[164:167], v[84:87]
	v_mfma_f32_16x16x32_bf16 v[80:83], v[204:207], v[164:167], v[80:83]
	v_mfma_f32_16x16x32_bf16 v[68:71], v[196:199], v[172:175], v[68:71]
	v_mfma_f32_16x16x32_bf16 v[64:67], v[204:207], v[172:175], v[64:67]
	s_barrier
	s_setprio 0
	s_mov_b32 m0, s31
	ds_read_b128 v[144:147], v215 offset:16384
	ds_read_b128 v[148:151], v215 offset:17408
	ds_read_b128 v[152:155], v215 offset:18432
	ds_read_b128 v[156:159], v215 offset:19456
	ds_read_b128 v[160:163], v215 offset:20480
	ds_read_b128 v[164:167], v215 offset:21504
	ds_read_b128 v[168:171], v215 offset:22528
	ds_read_b128 v[172:175], v215 offset:23552
	global_load_lds_dwordx4 v176, s[22:23]
	s_mov_b32 m0, s33
	s_nop 0
	global_load_lds_dwordx4 v180, s[22:23]
	s_waitcnt vmcnt(10)
	s_setprio 1
	s_barrier
	s_waitcnt lgkmcnt(0)
	v_mfma_f32_16x16x32_bf16 v[60:63], v[128:131], v[144:147], v[60:63]
	v_mfma_f32_16x16x32_bf16 v[56:59], v[136:139], v[144:147], v[56:59]
	v_mfma_f32_16x16x32_bf16 v[44:47], v[128:131], v[152:155], v[44:47]
	v_mfma_f32_16x16x32_bf16 v[40:43], v[136:139], v[152:155], v[40:43]
	v_mfma_f32_16x16x32_bf16 v[28:31], v[128:131], v[160:163], v[28:31]
	v_mfma_f32_16x16x32_bf16 v[24:27], v[136:139], v[160:163], v[24:27]
	v_mfma_f32_16x16x32_bf16 v[12:15], v[128:131], v[168:171], v[12:15]
	v_mfma_f32_16x16x32_bf16 v[8:11], v[136:139], v[168:171], v[8:11]
	v_mfma_f32_16x16x32_bf16 v[60:63], v[132:135], v[148:151], v[60:63]
	v_mfma_f32_16x16x32_bf16 v[56:59], v[140:143], v[148:151], v[56:59]
	v_mfma_f32_16x16x32_bf16 v[44:47], v[132:135], v[156:159], v[44:47]
	v_mfma_f32_16x16x32_bf16 v[40:43], v[140:143], v[156:159], v[40:43]
	v_mfma_f32_16x16x32_bf16 v[28:31], v[132:135], v[164:167], v[28:31]
	v_mfma_f32_16x16x32_bf16 v[24:27], v[140:143], v[164:167], v[24:27]
	v_mfma_f32_16x16x32_bf16 v[12:15], v[132:135], v[172:175], v[12:15]
	v_mfma_f32_16x16x32_bf16 v[8:11], v[140:143], v[172:175], v[8:11]
	s_barrier
	s_setprio 0
	s_add_u32 s52, s20, 0x160000
	s_addc_u32 s53, s21, 0
	s_add_i32 s45, s47, s30
	s_mov_b32 m0, s45
	s_nop 0
	global_load_lds_dwordx4 v178, s[52:53]
	s_add_i32 m0, s45, 0x2000
	s_nop 0
	global_load_lds_dwordx4 v182, s[52:53]
	s_add_i32 s45, 0, 0x18000
	v_add_u32_e32 v140, s45, v212
	ds_read_b128 v[128:131], v140
	ds_read_b128 v[132:135], v140 offset:1024
	ds_read_b128 v[136:139], v140 offset:2048
	ds_read_b128 v[140:143], v140 offset:3072
	s_waitcnt vmcnt(6)
	s_setprio 1
	s_barrier
; #define PG8_STAGE(bufoff, gbase, voff) do { _Pragma("unroll") for (int _i = 0; _i < 2; ++_i) \
;     __builtin_amdgcn_global_load_lds((const unsigned*)((const char*)(gbase) + (voff)[_i]), (LAS unsigned*)(lds + (bufoff) + ldsw + _i * 8192), 16, 0, 0); } while (0)
; #define PG8_LDA(dst, b, h) do { _Pragma("unroll") for (int m = 0; m < 4; ++m) _Pragma("unroll") for (int k = 0; k < 2; ++k) dst[m][k] = *(const LAS bf16x8*)(lds + PG8_SA(b, h) + aoff + m * 2048 + k * 1024); } while (0)
; #define PG8_LDB(dst, b, h) do { _Pragma("unroll") for (int n = 0; n < 2; ++n) _Pragma("unroll") for (int k = 0; k < 2; ++k) dst[n][k] = *(const LAS bf16x8*)(lds + PG8_SB(b, h) + boff + n * 2048 + k * 1024); } while (0)
; #define PG8_MMA(ai, bj, At, Bt) do { __builtin_amdgcn_s_setprio(1); _Pragma("unroll") for (int m = 0; m < 4; ++m) _Pragma("unroll") for (int n = 0; n < 2; ++n) _Pragma("unroll") for (int k = 0; k < 2; ++k) \
;     acc[ai][bj][m][n] = __builtin_amdgcn_mfma_f32_16x16x32_bf16(Bt[n][k], At[m][k], acc[ai][bj][m][n], 0, 0, 0); __builtin_amdgcn_s_setprio(0); } while (0)
; #define PG8_WAIT_V(n) asm volatile("s_waitcnt vmcnt(" #n ")" ::: "memory")
; #define PG8_WAIT_L(n) asm volatile("s_waitcnt lgkmcnt(" #n ")" ::: "memory")
; #define PG8_BAR __builtin_amdgcn_s_barrier()
; #define PG8_SCHED __builtin_amdgcn_sched_barrier(0)
; template <class Epi, class Sched = StaticOrder>
; DI void gemm_phase(LAS unsigned char* lds, const Gemm g, const Sched& S, const Epi& E) {
;     ...
;       PG8_WAIT_V(6); PG8_BAR; PG8_MMA(1, 1, At, B1); PG8_BAR;
;       PG8_LDB(B0, 1, 0); PG8_SCHED; PG8_LDA(At, 1, 0); PG8_STAGE(PG8_SA(0, 1), a2 + hstep, voffA);
;       PG8_WAIT_L(8); PG8_BAR; PG8_WAIT_L(0); PG8_MMA(0, 0, At, B0); PG8_BAR; PG8_SCHED;
;       PG8_LDB(B1, 1, 1); PG8_STAGE(PG8_SB(1, 0), b3, voffB);
;       PG8_BAR; PG8_WAIT_L(0); PG8_MMA(0, 1, At, B1); PG8_BAR;
;       PG8_LDA(At, 1, 1); PG8_STAGE(PG8_SA(1, 0), a3, voffA);
;       PG8_BAR; PG8_WAIT_L(0); PG8_MMA(1, 0, At, B0); PG8_BAR; PG8_SCHED;
	v_mfma_f32_16x16x32_bf16 v[52:55], v[192:195], v[144:147], v[52:55]
	v_mfma_f32_16x16x32_bf16 v[48:51], v[200:203], v[144:147], v[48:51]
	v_mfma_f32_16x16x32_bf16 v[36:39], v[192:195], v[152:155], v[36:39]
	v_mfma_f32_16x16x32_bf16 v[32:35], v[200:203], v[152:155], v[32:35]
	v_mfma_f32_16x16x32_bf16 v[20:23], v[192:195], v[160:163], v[20:23]
	v_mfma_f32_16x16x32_bf16 v[16:19], v[200:203], v[160:163], v[16:19]
	v_mfma_f32_16x16x32_bf16 v[4:7], v[192:195], v[168:171], v[4:7]
	v_mfma_f32_16x16x32_bf16 v[0:3], v[200:203], v[168:171], v[0:3]
	v_mfma_f32_16x16x32_bf16 v[52:55], v[196:199], v[148:151], v[52:55]
	v_mfma_f32_16x16x32_bf16 v[48:51], v[204:207], v[148:151], v[48:51]
	v_mfma_f32_16x16x32_bf16 v[36:39], v[196:199], v[156:159], v[36:39]
	v_mfma_f32_16x16x32_bf16 v[32:35], v[204:207], v[156:159], v[32:35]
	v_mfma_f32_16x16x32_bf16 v[20:23], v[196:199], v[164:167], v[20:23]
	v_mfma_f32_16x16x32_bf16 v[16:19], v[204:207], v[164:167], v[16:19]
	v_mfma_f32_16x16x32_bf16 v[4:7], v[196:199], v[172:175], v[4:7]
	v_mfma_f32_16x16x32_bf16 v[0:3], v[204:207], v[172:175], v[0:3]
	s_barrier
	s_setprio 0
	s_add_u32 s22, s22, 0x160000
	s_addc_u32 s23, s23, 0
	s_mov_b32 m0, s34
	ds_read_b128 v[144:147], v215 offset:32768
	ds_read_b128 v[148:151], v215 offset:33792
	ds_read_b128 v[152:155], v215 offset:34816
	ds_read_b128 v[156:159], v215 offset:35840
	ds_read_b128 v[160:163], v215 offset:36864
	ds_read_b128 v[164:167], v215 offset:37888
	ds_read_b128 v[168:171], v215 offset:38912
	ds_read_b128 v[172:175], v215 offset:39936
	global_load_lds_dwordx4 v176, s[22:23]
	s_mov_b32 m0, s35
	s_nop 0
	global_load_lds_dwordx4 v180, s[22:23]
	s_waitcnt lgkmcnt(8)
	s_setprio 1
	s_barrier
	s_waitcnt lgkmcnt(0)
	v_mfma_f32_16x16x32_bf16 v[124:127], v[128:131], v[144:147], v[124:127]
	v_mfma_f32_16x16x32_bf16 v[120:123], v[136:139], v[144:147], v[120:123]
	v_mfma_f32_16x16x32_bf16 v[108:111], v[128:131], v[152:155], v[108:111]
	v_mfma_f32_16x16x32_bf16 v[104:107], v[136:139], v[152:155], v[104:107]
	v_mfma_f32_16x16x32_bf16 v[92:95], v[128:131], v[160:163], v[92:95]
	v_mfma_f32_16x16x32_bf16 v[88:91], v[136:139], v[160:163], v[88:91]
	v_mfma_f32_16x16x32_bf16 v[76:79], v[128:131], v[168:171], v[76:79]
	v_mfma_f32_16x16x32_bf16 v[72:75], v[136:139], v[168:171], v[72:75]
	v_mfma_f32_16x16x32_bf16 v[124:127], v[132:135], v[148:151], v[124:127]
	v_mfma_f32_16x16x32_bf16 v[120:123], v[140:143], v[148:151], v[120:123]
	v_mfma_f32_16x16x32_bf16 v[108:111], v[132:135], v[156:159], v[108:111]
	v_mfma_f32_16x16x32_bf16 v[104:107], v[140:143], v[156:159], v[104:107]
	v_mfma_f32_16x16x32_bf16 v[92:95], v[132:135], v[164:167], v[92:95]
	v_mfma_f32_16x16x32_bf16 v[88:91], v[140:143], v[164:167], v[88:91]
	v_mfma_f32_16x16x32_bf16 v[76:79], v[132:135], v[172:175], v[76:79]
	v_mfma_f32_16x16x32_bf16 v[72:75], v[140:143], v[172:175], v[72:75]
	s_barrier
	s_setprio 0
	s_add_i32 s22, 0, 0x1c000
	s_add_i32 s23, s45, s30
	v_add_u32_e32 v204, s22, v212
	s_mov_b32 m0, s23
	ds_read_b128 v[192:195], v204
	ds_read_b128 v[196:199], v204 offset:1024
	ds_read_b128 v[200:203], v204 offset:2048
	ds_read_b128 v[204:207], v204 offset:3072
	global_load_lds_dwordx4 v178, s[98:99]
	s_add_i32 m0, s23, 0x2000
	s_nop 0
	global_load_lds_dwordx4 v182, s[98:99]
	s_setprio 1
	s_barrier
	s_waitcnt lgkmcnt(0)
	v_mfma_f32_16x16x32_bf16 v[116:119], v[192:195], v[144:147], v[116:119]
	v_mfma_f32_16x16x32_bf16 v[112:115], v[200:203], v[144:147], v[112:115]
	v_mfma_f32_16x16x32_bf16 v[100:103], v[192:195], v[152:155], v[100:103]
	v_mfma_f32_16x16x32_bf16 v[96:99], v[200:203], v[152:155], v[96:99]
	v_mfma_f32_16x16x32_bf16 v[84:87], v[192:195], v[160:163], v[84:87]
	v_mfma_f32_16x16x32_bf16 v[80:83], v[200:203], v[160:163], v[80:83]
	v_mfma_f32_16x16x32_bf16 v[68:71], v[192:195], v[168:171], v[68:71]
	v_mfma_f32_16x16x32_bf16 v[64:67], v[200:203], v[168:171], v[64:67]
	v_mfma_f32_16x16x32_bf16 v[116:119], v[196:199], v[148:151], v[116:119]
	v_mfma_f32_16x16x32_bf16 v[112:115], v[204:207], v[148:151], v[112:115]
	v_mfma_f32_16x16x32_bf16 v[100:103], v[196:199], v[156:159], v[100:103]
	v_mfma_f32_16x16x32_bf16 v[96:99], v[204:207], v[156:159], v[96:99]
	v_mfma_f32_16x16x32_bf16 v[84:87], v[196:199], v[164:167], v[84:87]
	v_mfma_f32_16x16x32_bf16 v[80:83], v[204:207], v[164:167], v[80:83]
	v_mfma_f32_16x16x32_bf16 v[68:71], v[196:199], v[172:175], v[68:71]
	v_mfma_f32_16x16x32_bf16 v[64:67], v[204:207], v[172:175], v[64:67]
	s_barrier
	s_setprio 0
	s_mov_b32 m0, s37
	ds_read_b128 v[144:147], v215 offset:49152
	ds_read_b128 v[148:151], v215 offset:50176
	ds_read_b128 v[152:155], v215 offset:51200
	ds_read_b128 v[156:159], v215 offset:52224
	ds_read_b128 v[160:163], v215 offset:53248
	ds_read_b128 v[164:167], v215 offset:54272
	ds_read_b128 v[168:171], v215 offset:55296
	ds_read_b128 v[172:175], v215 offset:56320
	global_load_lds_dwordx4 v176, s[100:101]
	s_mov_b32 m0, s38
	s_nop 0
	global_load_lds_dwordx4 v180, s[100:101]
	s_waitcnt vmcnt(10)
	s_setprio 1
	s_barrier
	s_waitcnt lgkmcnt(0)
	v_mfma_f32_16x16x32_bf16 v[60:63], v[128:131], v[144:147], v[60:63]
	v_mfma_f32_16x16x32_bf16 v[56:59], v[136:139], v[144:147], v[56:59]
	v_mfma_f32_16x16x32_bf16 v[44:47], v[128:131], v[152:155], v[44:47]
	v_mfma_f32_16x16x32_bf16 v[40:43], v[136:139], v[152:155], v[40:43]
	v_mfma_f32_16x16x32_bf16 v[28:31], v[128:131], v[160:163], v[28:31]
	v_mfma_f32_16x16x32_bf16 v[24:27], v[136:139], v[160:163], v[24:27]
	v_mfma_f32_16x16x32_bf16 v[12:15], v[128:131], v[168:171], v[12:15]
	v_mfma_f32_16x16x32_bf16 v[8:11], v[136:139], v[168:171], v[8:11]
	v_mfma_f32_16x16x32_bf16 v[60:63], v[132:135], v[148:151], v[60:63]
	v_mfma_f32_16x16x32_bf16 v[56:59], v[140:143], v[148:151], v[56:59]
	v_mfma_f32_16x16x32_bf16 v[44:47], v[132:135], v[156:159], v[44:47]
	v_mfma_f32_16x16x32_bf16 v[40:43], v[140:143], v[156:159], v[40:43]
	v_mfma_f32_16x16x32_bf16 v[28:31], v[132:135], v[164:167], v[28:31]
	v_mfma_f32_16x16x32_bf16 v[24:27], v[140:143], v[164:167], v[24:27]
	v_mfma_f32_16x16x32_bf16 v[12:15], v[132:135], v[172:175], v[12:15]
	v_mfma_f32_16x16x32_bf16 v[8:11], v[140:143], v[172:175], v[8:11]
	s_barrier
; DI unsigned pack2(float lo, float hi) { f32x2 v = {lo, hi}; bf16v2 r = __builtin_convertvector(v, bf16v2); return __builtin_bit_cast(unsigned, r); }
; #define PG8_STAGE(bufoff, gbase, voff) do { _Pragma("unroll") for (int _i = 0; _i < 2; ++_i) \
;     __builtin_amdgcn_global_load_lds((const unsigned*)((const char*)(gbase) + (voff)[_i]), (LAS unsigned*)(lds + (bufoff) + ldsw + _i * 8192), 16, 0, 0); } while (0)
; #define PG8_WAIT_V(n) asm volatile("s_waitcnt vmcnt(" #n ")" ::: "memory")
; #define PG8_BAR __builtin_amdgcn_s_barrier()
;   DI void operator()(const f32x4 (&acc)[2][2][4][2], const Unit& u, int wr, int wc, int fr, int fq) const {
;     const int row0 = u.pm * BM + wr * 64 + fr, col0 = u.pn * BM + wc * 32 + 8 * fq;
; #pragma unroll
;     for (int ai = 0; ai < 2; ++ai) {
;       f32x4 bv[4][2][2];
; #pragma unroll
;       for (int m = 0; m < 4; ++m)
; #pragma unroll
;         for (int bj = 0; bj < 2; ++bj) {
;           const float* bp = base + (size_t)(row0 + ai * HALF + m * 16) * 2048 + col0 + bj * HALF;
;           bv[m][bj][0] = *(const f32x4*)bp; bv[m][bj][1] = *(const f32x4*)(bp + 4);
;         }
; #pragma unroll
;       for (int m = 0; m < 4; ++m) {
;         const int row = row0 + ai * HALF + m * 16;
;         const size_t off = (size_t)row * 2048 + col0;
;         float ss = 0.f;
; #pragma unroll
;         for (int bj = 0; bj < 2; ++bj) {
;           const f32x4 v0 = acc[ai][bj][m][0] + bv[m][bj][0], v1 = acc[ai][bj][m][1] + bv[m][bj][1];
;           *(f32x4*)(C + off + bj * HALF) = v0; *(f32x4*)(C + off + bj * HALF + 4) = v1;
;           if (xb) {
;             u32x4 w; w.x = pack2(v0[0], v0[1]); w.y = pack2(v0[2], v0[3]); w.z = pack2(v1[0], v1[1]); w.w = pack2(v1[2], v1[3]);
;             *(u32x4*)(xb + off + bj * HALF) = w;
;             ss += v0[0] * v0[0] + v0[1] * v0[1] + v0[2] * v0[2] + v0[3] * v0[3] + v1[0] * v1[0] + v1[1] * v1[1] + v1[2] * v1[2] + v1[3] * v1[3];
;           }
;         }
;         if (xb) {
;           ss += __shfl_xor(ss, 16); ss += __shfl_xor(ss, 32);
;           if (fq == 0) ssq[(size_t)row * 32 + u.pn * 4 + wc] = ss;
;         }
;       }
;     }
; template <class Epi, class Sched = StaticOrder>
; DI void gemm_phase(LAS unsigned char* lds, const Gemm g, const Sched& S, const Epi& E) {
;     ...
;       PG8_STAGE(PG8_SB(1, 1), b3 + hstep, voffB);
;       PG8_WAIT_V(6); PG8_BAR; PG8_MMA(1, 1, At, B1); PG8_BAR;
	s_setprio 0
	s_add_u32 s20, s20, 0x160080
	s_addc_u32 s21, s21, 0
	s_add_i32 s22, s22, s30
	s_mov_b32 m0, s22
	s_nop 0
	global_load_lds_dwordx4 v178, s[20:21]
	s_add_i32 m0, s22, 0x2000
	s_nop 0
	global_load_lds_dwordx4 v182, s[20:21]
	ds_read_b128 v[128:131], v214
	ds_read_b128 v[132:135], v214 offset:1024
	ds_read_b128 v[136:139], v214 offset:2048
	ds_read_b128 v[140:143], v214 offset:3072
	s_waitcnt vmcnt(6)
	s_setprio 1
	s_barrier
	v_mfma_f32_16x16x32_bf16 v[52:55], v[192:195], v[144:147], v[52:55]
	v_mfma_f32_16x16x32_bf16 v[48:51], v[200:203], v[144:147], v[48:51]
	v_mfma_f32_16x16x32_bf16 v[36:39], v[192:195], v[152:155], v[36:39]
	v_mfma_f32_16x16x32_bf16 v[32:35], v[200:203], v[152:155], v[32:35]
	v_mfma_f32_16x16x32_bf16 v[20:23], v[192:195], v[160:163], v[20:23]
	v_mfma_f32_16x16x32_bf16 v[16:19], v[200:203], v[160:163], v[16:19]
	v_mfma_f32_16x16x32_bf16 v[4:7], v[192:195], v[168:171], v[4:7]
	v_mfma_f32_16x16x32_bf16 v[0:3], v[200:203], v[168:171], v[0:3]
	v_mfma_f32_16x16x32_bf16 v[52:55], v[196:199], v[148:151], v[52:55]
	v_mfma_f32_16x16x32_bf16 v[48:51], v[204:207], v[148:151], v[48:51]
	v_mfma_f32_16x16x32_bf16 v[36:39], v[196:199], v[156:159], v[36:39]
	v_mfma_f32_16x16x32_bf16 v[32:35], v[204:207], v[156:159], v[32:35]
	v_mfma_f32_16x16x32_bf16 v[20:23], v[196:199], v[164:167], v[20:23]
	v_mfma_f32_16x16x32_bf16 v[16:19], v[204:207], v[164:167], v[16:19]
	v_mfma_f32_16x16x32_bf16 v[4:7], v[196:199], v[172:175], v[4:7]
	v_mfma_f32_16x16x32_bf16 v[0:3], v[204:207], v[172:175], v[0:3]
	s_add_i32 s44, s44, 2
	s_add_u32 s18, s18, 0x100
	s_addc_u32 s19, s19, 0
	s_add_u32 s42, s42, 0x100
	s_addc_u32 s43, s43, 0
	s_cmpk_gt_u32 s44, 0x55
	s_barrier
	s_setprio 0
	s_cbranch_scc0 .LBB0_961
	s_waitcnt lgkmcnt(0)
	v_lshl_add_u32 v194, s51, 8, v211
	v_lshl_or_b32 v192, s2, 8, v213
	v_readlane_b32 s52, v243, 3
	v_ashrrev_i32_e32 v193, 31, v192
	v_readlane_b32 s66, v243, 17
	v_readlane_b32 s67, v243, 18
	v_ashrrev_i32_e32 v195, 31, v194
	v_lshlrev_b64 v[128:129], 13, v[194:195]
	v_lshl_add_u64 v[196:197], v[192:193], 2, s[66:67]
	v_lshl_add_u64 v[236:237], v[196:197], 0, v[128:129]
	global_load_dwordx4 v[220:223], v[236:237], off
	global_load_dwordx4 v[224:227], v[236:237], off offset:16
	global_load_dwordx4 v[228:231], v[236:237], off offset:512
	global_load_dwordx4 v[232:235], v[236:237], off offset:528
	v_or_b32_e32 v206, 16, v194
	v_or_b32_e32 v202, 32, v194
	v_or_b32_e32 v198, 48, v194
	v_ashrrev_i32_e32 v207, 31, v206
	v_ashrrev_i32_e32 v203, 31, v202
	v_ashrrev_i32_e32 v199, 31, v198
	v_lshlrev_b64 v[128:129], 13, v[206:207]
	v_lshlrev_b64 v[130:131], 13, v[202:203]
	v_lshlrev_b64 v[132:133], 13, v[198:199]
	v_lshl_add_u64 v[208:209], v[196:197], 0, v[128:129]
	v_lshl_add_u64 v[204:205], v[196:197], 0, v[130:131]
	v_lshl_add_u64 v[200:201], v[196:197], 0, v[132:133]
	global_load_dwordx4 v[168:171], v[208:209], off offset:16
	global_load_dwordx4 v[172:175], v[208:209], off
	global_load_dwordx4 v[160:163], v[208:209], off offset:528
	global_load_dwordx4 v[164:167], v[208:209], off offset:512
	global_load_dwordx4 v[152:155], v[204:205], off offset:16
	global_load_dwordx4 v[156:159], v[204:205], off
	global_load_dwordx4 v[144:147], v[204:205], off offset:528
	global_load_dwordx4 v[148:151], v[204:205], off offset:512
	global_load_dwordx4 v[136:139], v[200:201], off offset:16
	global_load_dwordx4 v[140:143], v[200:201], off
	global_load_dwordx4 v[128:131], v[200:201], off offset:528
	global_load_dwordx4 v[132:135], v[200:201], off offset:512
	v_and_b32_e32 v218, 64, v217
	v_xor_b32_e32 v238, 16, v217
	v_add_u32_e32 v240, 64, v218
	v_xor_b32_e32 v239, 32, v217
	v_cmp_lt_i32_e32 vcc, v238, v240
	v_lshlrev_b64 v[218:219], 11, v[194:195]
	s_lshl_b32 s18, s2, 2
	v_cndmask_b32_e32 v241, v217, v238, vcc
	v_cmp_lt_i32_e32 vcc, v239, v240
	s_ashr_i32 s19, s18, 31
	v_readlane_b32 s53, v243, 4
	v_cndmask_b32_e32 v240, v217, v239, vcc
	v_lshl_add_u64 v[238:239], v[218:219], 0, v[192:193]
	v_lshlrev_b32_e32 v218, 2, v241
	v_lshl_add_u64 v[238:239], v[238:239], 1, s[12:13]
	v_readlane_b32 s54, v243, 5
	v_readlane_b32 s55, v243, 6
	v_readlane_b32 s56, v243, 7
	v_readlane_b32 s57, v243, 8
	v_readlane_b32 s58, v243, 9
	v_readlane_b32 s59, v243, 10
	v_readlane_b32 s60, v243, 11
	v_readlane_b32 s61, v243, 12
	v_readlane_b32 s62, v243, 13
	v_readlane_b32 s63, v243, 14
	v_readlane_b32 s64, v243, 15
	v_readlane_b32 s65, v243, 16
	s_waitcnt vmcnt(0)
	v_pk_add_f32 v[126:127], v[126:127], v[222:223]
	v_pk_add_f32 v[124:125], v[124:125], v[220:221]
	v_pk_add_f32 v[116:117], v[116:117], v[228:229]
	v_pk_add_f32 v[122:123], v[122:123], v[226:227]
	v_pk_add_f32 v[120:121], v[120:121], v[224:225]
	v_pk_add_f32 v[220:221], v[112:113], v[232:233]
	global_store_dwordx4 v[236:237], v[124:127], off
	global_store_dwordx4 v[236:237], v[120:123], off offset:16
	v_cvt_pk_bf16_f32 v112, v124, v125
	v_mul_f32_e32 v125, v125, v125
	v_mul_f32_e32 v219, v117, v117
	v_pk_add_f32 v[118:119], v[118:119], v[230:231]
	v_fmac_f32_e32 v125, v124, v124
	v_fmac_f32_e32 v219, v116, v116
	v_fmac_f32_e32 v125, v126, v126
	v_fmac_f32_e32 v219, v118, v118
	v_fmac_f32_e32 v125, v127, v127
	v_fmac_f32_e32 v219, v119, v119
	v_fmac_f32_e32 v125, v120, v120
	v_fmac_f32_e32 v219, v220, v220
	v_pk_add_f32 v[222:223], v[114:115], v[234:235]
	v_fmac_f32_e32 v125, v121, v121
	v_fmac_f32_e32 v219, v221, v221
	v_fmac_f32_e32 v125, v122, v122
	v_fmac_f32_e32 v219, v222, v222
	v_fmac_f32_e32 v125, v123, v123
	v_fmac_f32_e32 v219, v223, v223
	v_cvt_pk_bf16_f32 v114, v120, v121
	v_add_f32_e32 v121, v125, v219
	v_cvt_pk_bf16_f32 v115, v122, v123
	ds_bpermute_b32 v122, v218, v121
	v_cvt_pk_bf16_f32 v113, v126, v127
	global_store_dwordx4 v[238:239], v[112:115], off
	global_store_dwordx4 v[236:237], v[116:119], off offset:512
	global_store_dwordx4 v[236:237], v[220:223], off offset:528
	v_lshlrev_b32_e32 v126, 2, v240
	v_cvt_pk_bf16_f32 v120, v116, v117
	s_waitcnt lgkmcnt(0)
	v_add_f32_e32 v112, v121, v122
	ds_bpermute_b32 v113, v126, v112
	v_cvt_pk_bf16_f32 v121, v118, v119
	v_cvt_pk_bf16_f32 v122, v220, v221
	v_cvt_pk_bf16_f32 v123, v222, v223
	global_store_dwordx4 v[238:239], v[120:123], off offset:256
	s_and_saveexec_b64 s[20:21], s[0:1]
	s_cbranch_execz .LBB0_964
	s_waitcnt lgkmcnt(0)
	v_add_f32_e32 v114, v112, v113
	v_lshlrev_b64 v[112:113], 7, v[194:195]
	v_lshl_add_u64 v[112:113], s[14:15], 0, v[112:113]
	v_lshl_add_u64 v[112:113], s[18:19], 2, v[112:113]
	s_lshl_b32 s2, s36, 2
	v_lshl_add_u64 v[112:113], v[112:113], 0, s[2:3]
	global_store_dword v[112:113], v114, off

; #define PG8_STAGE(bufoff, gbase, voff) do { _Pragma("unroll") for (int _i = 0; _i < 2; ++_i) \
;     __builtin_amdgcn_global_load_lds((const unsigned*)((const char*)(gbase) + (voff)[_i]), (LAS unsigned*)(lds + (bufoff) + ldsw + _i * 8192), 16, 0, 0); } while (0)
; #define PG8_LDA(dst, b, h) do { _Pragma("unroll") for (int m = 0; m < 4; ++m) _Pragma("unroll") for (int k = 0; k < 2; ++k) dst[m][k] = *(const LAS bf16x8*)(lds + PG8_SA(b, h) + aoff + m * 2048 + k * 1024); } while (0)
; #define PG8_LDB(dst, b, h) do { _Pragma("unroll") for (int n = 0; n < 2; ++n) _Pragma("unroll") for (int k = 0; k < 2; ++k) dst[n][k] = *(const LAS bf16x8*)(lds + PG8_SB(b, h) + boff + n * 2048 + k * 1024); } while (0)
; #define PG8_MMA(ai, bj, At, Bt) do { __builtin_amdgcn_s_setprio(1); _Pragma("unroll") for (int m = 0; m < 4; ++m) _Pragma("unroll") for (int n = 0; n < 2; ++n) _Pragma("unroll") for (int k = 0; k < 2; ++k) \
;     acc[ai][bj][m][n] = __builtin_amdgcn_mfma_f32_16x16x32_bf16(Bt[n][k], At[m][k], acc[ai][bj][m][n], 0, 0, 0); __builtin_amdgcn_s_setprio(0); } while (0)
; #define PG8_WAIT_V(n) asm volatile("s_waitcnt vmcnt(" #n ")" ::: "memory")
; #define PG8_WAIT_L(n) asm volatile("s_waitcnt lgkmcnt(" #n ")" ::: "memory")
; #define PG8_BAR __builtin_amdgcn_s_barrier()
; #define PG8_SCHED __builtin_amdgcn_sched_barrier(0)
; template <class Epi, class Sched = StaticOrder>
; DI void gemm_phase(LAS unsigned char* lds, const Gemm g, const Sched& S, const Epi& E) {
;     ...
;     for (int t = 0; t < nt; t += 2) {
;       const bool last = (t == nt - 2);
;       const char* a1 = cA + (size_t)(t + 1) * kstep;
;       const char* a2 = last ? nA : cA + (size_t)(t + 2) * kstep; const char* b2 = last ? nB : cB + (size_t)(t + 2) * kstep;
;       const char* a3 = a2 + kstep; const char* b3 = b2 + kstep;
;       PG8_LDB(B0, 0, 0); PG8_SCHED; PG8_LDA(At, 0, 0); PG8_STAGE(PG8_SA(1, 1), a1 + hstep, voffA);
;       PG8_WAIT_L(8); PG8_BAR; PG8_WAIT_L(0); PG8_MMA(0, 0, At, B0); PG8_BAR; PG8_SCHED;
;       PG8_LDB(B1, 0, 1); PG8_STAGE(PG8_SB(0, 0), b2, voffB);
;       PG8_BAR; PG8_WAIT_L(0); PG8_MMA(0, 1, At, B1); PG8_BAR;
;       PG8_LDA(At, 0, 1); PG8_STAGE(PG8_SA(0, 0), a2, voffA);
;       PG8_BAR; PG8_WAIT_L(0); PG8_MMA(1, 0, At, B0); PG8_BAR; PG8_SCHED;
;       PG8_STAGE(PG8_SB(0, 1), b2 + hstep, voffB);
;       PG8_WAIT_V(6); PG8_BAR; PG8_MMA(1, 1, At, B1); PG8_BAR;
.LBB0_1052:
	s_add_u32 s12, s10, 0xfff80080
	s_addc_u32 s13, s11, -1
	s_cmp_eq_u32 s52, 28
	s_cselect_b32 s65, s41, s13
	s_cselect_b32 s64, s42, s12
	s_cselect_b32 s13, s43, s49
	s_cselect_b32 s12, s44, s45
	s_add_i32 m0, s61, 0xc000
	ds_read_b128 v[144:147], v204
	ds_read_b128 v[148:151], v204 offset:1024
	ds_read_b128 v[152:155], v204 offset:2048
	ds_read_b128 v[156:159], v204 offset:3072
	ds_read_b128 v[178:181], v204 offset:4096
	ds_read_b128 v[182:185], v204 offset:5120
	ds_read_b128 v[186:189], v204 offset:6144
	ds_read_b128 v[190:193], v204 offset:7168
	global_load_lds_dwordx4 v172, s[10:11]
	s_add_i32 m0, s61, 0xe000
	s_nop 0
	global_load_lds_dwordx4 v174, s[10:11]
	s_waitcnt lgkmcnt(8)
	s_setprio 1
	s_barrier
	s_waitcnt lgkmcnt(0)
	v_mfma_f32_16x16x32_bf16 v[124:127], v[128:131], v[144:147], v[124:127]
	v_mfma_f32_16x16x32_bf16 v[120:123], v[136:139], v[144:147], v[120:123]
	v_mfma_f32_16x16x32_bf16 v[116:119], v[128:131], v[152:155], v[116:119]
	v_mfma_f32_16x16x32_bf16 v[104:107], v[136:139], v[152:155], v[104:107]
	v_mfma_f32_16x16x32_bf16 v[92:95], v[128:131], v[178:181], v[92:95]
	v_mfma_f32_16x16x32_bf16 v[88:91], v[136:139], v[178:181], v[88:91]
	v_mfma_f32_16x16x32_bf16 v[84:87], v[128:131], v[186:189], v[84:87]
	v_mfma_f32_16x16x32_bf16 v[72:75], v[136:139], v[186:189], v[72:75]
	v_mfma_f32_16x16x32_bf16 v[124:127], v[132:135], v[148:151], v[124:127]
	v_mfma_f32_16x16x32_bf16 v[120:123], v[140:143], v[148:151], v[120:123]
	v_mfma_f32_16x16x32_bf16 v[116:119], v[132:135], v[156:159], v[116:119]
	v_mfma_f32_16x16x32_bf16 v[104:107], v[140:143], v[156:159], v[104:107]
	v_mfma_f32_16x16x32_bf16 v[92:95], v[132:135], v[182:185], v[92:95]
	v_mfma_f32_16x16x32_bf16 v[88:91], v[140:143], v[182:185], v[88:91]
	v_mfma_f32_16x16x32_bf16 v[84:87], v[132:135], v[190:193], v[84:87]
	v_mfma_f32_16x16x32_bf16 v[72:75], v[140:143], v[190:193], v[72:75]
	s_barrier
	s_setprio 0
	s_add_i32 s53, s80, s70
	s_add_u32 s98, s12, 0x80
	s_addc_u32 s99, s13, 0
	s_add_u32 s100, s64, 0x80
	s_addc_u32 s101, s65, 0
	s_mov_b32 m0, s53
	ds_read_b128 v[194:197], v205
	ds_read_b128 v[212:215], v205 offset:1024
	ds_read_b128 v[216:219], v205 offset:2048
	ds_read_b128 v[220:223], v205 offset:3072
	global_load_lds_dwordx4 v162, s[12:13]
	s_add_i32 m0, s53, 0x2000
	s_nop 0
	global_load_lds_dwordx4 v166, s[12:13]
	s_setprio 1
	s_barrier
	s_waitcnt lgkmcnt(0)
	v_mfma_f32_16x16x32_bf16 v[112:115], v[194:197], v[144:147], v[112:115]
	v_mfma_f32_16x16x32_bf16 v[108:111], v[216:219], v[144:147], v[108:111]
	v_mfma_f32_16x16x32_bf16 v[100:103], v[194:197], v[152:155], v[100:103]
	v_mfma_f32_16x16x32_bf16 v[96:99], v[216:219], v[152:155], v[96:99]
	v_mfma_f32_16x16x32_bf16 v[80:83], v[194:197], v[178:181], v[80:83]
	v_mfma_f32_16x16x32_bf16 v[76:79], v[216:219], v[178:181], v[76:79]
	v_mfma_f32_16x16x32_bf16 v[68:71], v[194:197], v[186:189], v[68:71]
	v_mfma_f32_16x16x32_bf16 v[64:67], v[216:219], v[186:189], v[64:67]
	v_mfma_f32_16x16x32_bf16 v[112:115], v[212:215], v[148:151], v[112:115]
	v_mfma_f32_16x16x32_bf16 v[108:111], v[220:223], v[148:151], v[108:111]
	v_mfma_f32_16x16x32_bf16 v[100:103], v[212:215], v[156:159], v[100:103]
	v_mfma_f32_16x16x32_bf16 v[96:99], v[220:223], v[156:159], v[96:99]
	v_mfma_f32_16x16x32_bf16 v[80:83], v[212:215], v[182:185], v[80:83]
	v_mfma_f32_16x16x32_bf16 v[76:79], v[220:223], v[182:185], v[76:79]
	v_mfma_f32_16x16x32_bf16 v[68:71], v[212:215], v[190:193], v[68:71]
	v_mfma_f32_16x16x32_bf16 v[64:67], v[220:223], v[190:193], v[64:67]
	s_barrier
	s_setprio 0
	s_mov_b32 m0, s61
	ds_read_b128 v[144:147], v204 offset:16384
	ds_read_b128 v[148:151], v204 offset:17408
	ds_read_b128 v[152:155], v204 offset:18432
	ds_read_b128 v[156:159], v204 offset:19456
	ds_read_b128 v[178:181], v204 offset:20480
	ds_read_b128 v[182:185], v204 offset:21504
	ds_read_b128 v[186:189], v204 offset:22528
	ds_read_b128 v[190:193], v204 offset:23552
	global_load_lds_dwordx4 v160, s[64:65]
	s_mov_b32 m0, s63
	s_nop 0
	global_load_lds_dwordx4 v164, s[64:65]
	s_waitcnt vmcnt(10)
	s_setprio 1
	s_barrier
	s_waitcnt lgkmcnt(0)
	v_mfma_f32_16x16x32_bf16 v[60:63], v[128:131], v[144:147], v[60:63]
	v_mfma_f32_16x16x32_bf16 v[56:59], v[136:139], v[144:147], v[56:59]
	v_mfma_f32_16x16x32_bf16 v[48:51], v[128:131], v[152:155], v[48:51]
	v_mfma_f32_16x16x32_bf16 v[40:43], v[136:139], v[152:155], v[40:43]
	v_mfma_f32_16x16x32_bf16 v[28:31], v[128:131], v[178:181], v[28:31]
	v_mfma_f32_16x16x32_bf16 v[24:27], v[136:139], v[178:181], v[24:27]
	v_mfma_f32_16x16x32_bf16 v[12:15], v[128:131], v[186:189], v[12:15]
	v_mfma_f32_16x16x32_bf16 v[8:11], v[136:139], v[186:189], v[8:11]
	v_mfma_f32_16x16x32_bf16 v[60:63], v[132:135], v[148:151], v[60:63]
	v_mfma_f32_16x16x32_bf16 v[56:59], v[140:143], v[148:151], v[56:59]
	v_mfma_f32_16x16x32_bf16 v[48:51], v[132:135], v[156:159], v[48:51]
	v_mfma_f32_16x16x32_bf16 v[40:43], v[140:143], v[156:159], v[40:43]
	v_mfma_f32_16x16x32_bf16 v[28:31], v[132:135], v[182:185], v[28:31]
	v_mfma_f32_16x16x32_bf16 v[24:27], v[140:143], v[182:185], v[24:27]
	v_mfma_f32_16x16x32_bf16 v[12:15], v[132:135], v[190:193], v[12:15]
	v_mfma_f32_16x16x32_bf16 v[8:11], v[140:143], v[190:193], v[8:11]
	s_barrier
	s_setprio 0
	s_add_u32 s54, s12, 0x80000
	s_addc_u32 s55, s13, 0
	s_add_i32 s53, s81, s70
	s_mov_b32 m0, s53
	s_nop 0
	global_load_lds_dwordx4 v162, s[54:55]
	s_add_i32 m0, s53, 0x2000
	s_nop 0
	global_load_lds_dwordx4 v166, s[54:55]
	s_add_i32 s53, 0, 0x18000
	v_add_u32_e32 v140, s53, v199
	ds_read_b128 v[128:131], v140
	ds_read_b128 v[132:135], v140 offset:1024
	ds_read_b128 v[136:139], v140 offset:2048
	ds_read_b128 v[140:143], v140 offset:3072
	s_waitcnt vmcnt(6)
	s_setprio 1
	s_barrier
; #define PG8_STAGE(bufoff, gbase, voff) do { _Pragma("unroll") for (int _i = 0; _i < 2; ++_i) \
;     __builtin_amdgcn_global_load_lds((const unsigned*)((const char*)(gbase) + (voff)[_i]), (LAS unsigned*)(lds + (bufoff) + ldsw + _i * 8192), 16, 0, 0); } while (0)
; #define PG8_LDA(dst, b, h) do { _Pragma("unroll") for (int m = 0; m < 4; ++m) _Pragma("unroll") for (int k = 0; k < 2; ++k) dst[m][k] = *(const LAS bf16x8*)(lds + PG8_SA(b, h) + aoff + m * 2048 + k * 1024); } while (0)
; #define PG8_LDB(dst, b, h) do { _Pragma("unroll") for (int n = 0; n < 2; ++n) _Pragma("unroll") for (int k = 0; k < 2; ++k) dst[n][k] = *(const LAS bf16x8*)(lds + PG8_SB(b, h) + boff + n * 2048 + k * 1024); } while (0)
; #define PG8_MMA(ai, bj, At, Bt) do { __builtin_amdgcn_s_setprio(1); _Pragma("unroll") for (int m = 0; m < 4; ++m) _Pragma("unroll") for (int n = 0; n < 2; ++n) _Pragma("unroll") for (int k = 0; k < 2; ++k) \
;     acc[ai][bj][m][n] = __builtin_amdgcn_mfma_f32_16x16x32_bf16(Bt[n][k], At[m][k], acc[ai][bj][m][n], 0, 0, 0); __builtin_amdgcn_s_setprio(0); } while (0)
; #define PG8_WAIT_V(n) asm volatile("s_waitcnt vmcnt(" #n ")" ::: "memory")
; #define PG8_WAIT_L(n) asm volatile("s_waitcnt lgkmcnt(" #n ")" ::: "memory")
; #define PG8_BAR __builtin_amdgcn_s_barrier()
; #define PG8_SCHED __builtin_amdgcn_sched_barrier(0)
; template <class Epi, class Sched = StaticOrder>
; DI void gemm_phase(LAS unsigned char* lds, const Gemm g, const Sched& S, const Epi& E) {
;     ...
;       PG8_WAIT_V(6); PG8_BAR; PG8_MMA(1, 1, At, B1); PG8_BAR;
;       PG8_LDB(B0, 1, 0); PG8_SCHED; PG8_LDA(At, 1, 0); PG8_STAGE(PG8_SA(0, 1), a2 + hstep, voffA);
;       PG8_WAIT_L(8); PG8_BAR; PG8_WAIT_L(0); PG8_MMA(0, 0, At, B0); PG8_BAR; PG8_SCHED;
;       PG8_LDB(B1, 1, 1); PG8_STAGE(PG8_SB(1, 0), b3, voffB);
;       PG8_BAR; PG8_WAIT_L(0); PG8_MMA(0, 1, At, B1); PG8_BAR;
;       PG8_LDA(At, 1, 1); PG8_STAGE(PG8_SA(1, 0), a3, voffA);
;       PG8_BAR; PG8_WAIT_L(0); PG8_MMA(1, 0, At, B0); PG8_BAR; PG8_SCHED;
	v_mfma_f32_16x16x32_bf16 v[52:55], v[194:197], v[144:147], v[52:55]
	v_mfma_f32_16x16x32_bf16 v[44:47], v[216:219], v[144:147], v[44:47]
	v_mfma_f32_16x16x32_bf16 v[36:39], v[194:197], v[152:155], v[36:39]
	v_mfma_f32_16x16x32_bf16 v[32:35], v[216:219], v[152:155], v[32:35]
	v_mfma_f32_16x16x32_bf16 v[20:23], v[194:197], v[178:181], v[20:23]
	v_mfma_f32_16x16x32_bf16 v[16:19], v[216:219], v[178:181], v[16:19]
	v_mfma_f32_16x16x32_bf16 v[4:7], v[194:197], v[186:189], v[4:7]
	v_mfma_f32_16x16x32_bf16 v[0:3], v[216:219], v[186:189], v[0:3]
	v_mfma_f32_16x16x32_bf16 v[52:55], v[212:215], v[148:151], v[52:55]
	v_mfma_f32_16x16x32_bf16 v[44:47], v[220:223], v[148:151], v[44:47]
	v_mfma_f32_16x16x32_bf16 v[36:39], v[212:215], v[156:159], v[36:39]
	v_mfma_f32_16x16x32_bf16 v[32:35], v[220:223], v[156:159], v[32:35]
	v_mfma_f32_16x16x32_bf16 v[20:23], v[212:215], v[182:185], v[20:23]
	v_mfma_f32_16x16x32_bf16 v[16:19], v[220:223], v[182:185], v[16:19]
	v_mfma_f32_16x16x32_bf16 v[4:7], v[212:215], v[190:193], v[4:7]
	v_mfma_f32_16x16x32_bf16 v[0:3], v[220:223], v[190:193], v[0:3]
	s_barrier
	s_setprio 0
	s_add_u32 s54, s64, 0x80000
	s_addc_u32 s55, s65, 0
	s_mov_b32 m0, s71
	ds_read_b128 v[144:147], v204 offset:32768
	ds_read_b128 v[148:151], v204 offset:33792
	ds_read_b128 v[152:155], v204 offset:34816
	ds_read_b128 v[156:159], v204 offset:35840
	ds_read_b128 v[178:181], v204 offset:36864
	ds_read_b128 v[182:185], v204 offset:37888
	ds_read_b128 v[186:189], v204 offset:38912
	ds_read_b128 v[190:193], v204 offset:39936
	global_load_lds_dwordx4 v160, s[54:55]
	s_mov_b32 m0, s72
	s_nop 0
	global_load_lds_dwordx4 v164, s[54:55]
	s_waitcnt lgkmcnt(8)
	s_setprio 1
	s_barrier
	s_waitcnt lgkmcnt(0)
	v_mfma_f32_16x16x32_bf16 v[124:127], v[128:131], v[144:147], v[124:127]
	v_mfma_f32_16x16x32_bf16 v[120:123], v[136:139], v[144:147], v[120:123]
	v_mfma_f32_16x16x32_bf16 v[116:119], v[128:131], v[152:155], v[116:119]
	v_mfma_f32_16x16x32_bf16 v[104:107], v[136:139], v[152:155], v[104:107]
	v_mfma_f32_16x16x32_bf16 v[92:95], v[128:131], v[178:181], v[92:95]
	v_mfma_f32_16x16x32_bf16 v[88:91], v[136:139], v[178:181], v[88:91]
	v_mfma_f32_16x16x32_bf16 v[84:87], v[128:131], v[186:189], v[84:87]
	v_mfma_f32_16x16x32_bf16 v[72:75], v[136:139], v[186:189], v[72:75]
	v_mfma_f32_16x16x32_bf16 v[124:127], v[132:135], v[148:151], v[124:127]
	v_mfma_f32_16x16x32_bf16 v[120:123], v[140:143], v[148:151], v[120:123]
	v_mfma_f32_16x16x32_bf16 v[116:119], v[132:135], v[156:159], v[116:119]
	v_mfma_f32_16x16x32_bf16 v[104:107], v[140:143], v[156:159], v[104:107]
	v_mfma_f32_16x16x32_bf16 v[92:95], v[132:135], v[182:185], v[92:95]
	v_mfma_f32_16x16x32_bf16 v[88:91], v[140:143], v[182:185], v[88:91]
	v_mfma_f32_16x16x32_bf16 v[84:87], v[132:135], v[190:193], v[84:87]
	v_mfma_f32_16x16x32_bf16 v[72:75], v[140:143], v[190:193], v[72:75]
	s_barrier
	s_setprio 0
	s_add_i32 s54, 0, 0x1c000
	s_add_i32 s53, s53, s70
	v_add_u32_e32 v168, s54, v199
	s_mov_b32 m0, s53
	ds_read_b128 v[194:197], v168
	ds_read_b128 v[212:215], v168 offset:1024
	ds_read_b128 v[216:219], v168 offset:2048
	ds_read_b128 v[220:223], v168 offset:3072
	global_load_lds_dwordx4 v162, s[98:99]
	s_add_i32 m0, s53, 0x2000
	s_nop 0
	global_load_lds_dwordx4 v166, s[98:99]
	s_setprio 1
	s_barrier
	s_waitcnt lgkmcnt(0)
	v_mfma_f32_16x16x32_bf16 v[112:115], v[194:197], v[144:147], v[112:115]
	v_mfma_f32_16x16x32_bf16 v[108:111], v[216:219], v[144:147], v[108:111]
	v_mfma_f32_16x16x32_bf16 v[100:103], v[194:197], v[152:155], v[100:103]
	v_mfma_f32_16x16x32_bf16 v[96:99], v[216:219], v[152:155], v[96:99]
	v_mfma_f32_16x16x32_bf16 v[80:83], v[194:197], v[178:181], v[80:83]
	v_mfma_f32_16x16x32_bf16 v[76:79], v[216:219], v[178:181], v[76:79]
	v_mfma_f32_16x16x32_bf16 v[68:71], v[194:197], v[186:189], v[68:71]
	v_mfma_f32_16x16x32_bf16 v[64:67], v[216:219], v[186:189], v[64:67]
	v_mfma_f32_16x16x32_bf16 v[112:115], v[212:215], v[148:151], v[112:115]
	v_mfma_f32_16x16x32_bf16 v[108:111], v[220:223], v[148:151], v[108:111]
	v_mfma_f32_16x16x32_bf16 v[100:103], v[212:215], v[156:159], v[100:103]
	v_mfma_f32_16x16x32_bf16 v[96:99], v[220:223], v[156:159], v[96:99]
	v_mfma_f32_16x16x32_bf16 v[80:83], v[212:215], v[182:185], v[80:83]
	v_mfma_f32_16x16x32_bf16 v[76:79], v[220:223], v[182:185], v[76:79]
	v_mfma_f32_16x16x32_bf16 v[68:71], v[212:215], v[190:193], v[68:71]
	v_mfma_f32_16x16x32_bf16 v[64:67], v[220:223], v[190:193], v[64:67]
	s_barrier
	s_setprio 0
	s_mov_b32 m0, s76
	ds_read_b128 v[144:147], v204 offset:49152
	ds_read_b128 v[148:151], v204 offset:50176
	ds_read_b128 v[152:155], v204 offset:51200
	ds_read_b128 v[156:159], v204 offset:52224
	ds_read_b128 v[178:181], v204 offset:53248
	ds_read_b128 v[182:185], v204 offset:54272
	ds_read_b128 v[186:189], v204 offset:55296
	ds_read_b128 v[190:193], v204 offset:56320
	global_load_lds_dwordx4 v160, s[100:101]
	s_mov_b32 m0, s77
	s_nop 0
	global_load_lds_dwordx4 v164, s[100:101]
	s_waitcnt vmcnt(10)
	s_setprio 1
	s_barrier
	s_waitcnt lgkmcnt(0)
	v_mfma_f32_16x16x32_bf16 v[60:63], v[128:131], v[144:147], v[60:63]
	v_mfma_f32_16x16x32_bf16 v[56:59], v[136:139], v[144:147], v[56:59]
	v_mfma_f32_16x16x32_bf16 v[48:51], v[128:131], v[152:155], v[48:51]
	v_mfma_f32_16x16x32_bf16 v[40:43], v[136:139], v[152:155], v[40:43]
	v_mfma_f32_16x16x32_bf16 v[28:31], v[128:131], v[178:181], v[28:31]
	v_mfma_f32_16x16x32_bf16 v[24:27], v[136:139], v[178:181], v[24:27]
	v_mfma_f32_16x16x32_bf16 v[12:15], v[128:131], v[186:189], v[12:15]
	v_mfma_f32_16x16x32_bf16 v[8:11], v[136:139], v[186:189], v[8:11]
	v_mfma_f32_16x16x32_bf16 v[60:63], v[132:135], v[148:151], v[60:63]
	v_mfma_f32_16x16x32_bf16 v[56:59], v[140:143], v[148:151], v[56:59]
	v_mfma_f32_16x16x32_bf16 v[48:51], v[132:135], v[156:159], v[48:51]
	v_mfma_f32_16x16x32_bf16 v[40:43], v[140:143], v[156:159], v[40:43]
	v_mfma_f32_16x16x32_bf16 v[28:31], v[132:135], v[182:185], v[28:31]
	v_mfma_f32_16x16x32_bf16 v[24:27], v[140:143], v[182:185], v[24:27]
	v_mfma_f32_16x16x32_bf16 v[12:15], v[132:135], v[190:193], v[12:15]
	v_mfma_f32_16x16x32_bf16 v[8:11], v[140:143], v[190:193], v[8:11]
	s_barrier
; #define PG8_STAGE(bufoff, gbase, voff) do { _Pragma("unroll") for (int _i = 0; _i < 2; ++_i) \
;     __builtin_amdgcn_global_load_lds((const unsigned*)((const char*)(gbase) + (voff)[_i]), (LAS unsigned*)(lds + (bufoff) + ldsw + _i * 8192), 16, 0, 0); } while (0)
; #define PG8_MMA(ai, bj, At, Bt) do { __builtin_amdgcn_s_setprio(1); _Pragma("unroll") for (int m = 0; m < 4; ++m) _Pragma("unroll") for (int n = 0; n < 2; ++n) _Pragma("unroll") for (int k = 0; k < 2; ++k) \
;     acc[ai][bj][m][n] = __builtin_amdgcn_mfma_f32_16x16x32_bf16(Bt[n][k], At[m][k], acc[ai][bj][m][n], 0, 0, 0); __builtin_amdgcn_s_setprio(0); } while (0)
; #define PG8_WAIT_V(n) asm volatile("s_waitcnt vmcnt(" #n ")" ::: "memory")
; #define PG8_BAR __builtin_amdgcn_s_barrier()
;   DI void operator()(const f32x4 (&acc)[2][2][4][2], const Unit& u, int wr, int wc, int fr, int fq) const {
;     if (u.pn >= 16) {
;       const int row0 = u.pm * BM + wr * 64 + fr, col0 = (u.pn - 16) * BM + wc * 32 + 8 * fq;
;     ...
;     const int col = u.pn * 128 + wc * 32 + 8 * fq;
;     float w0[8], w1[8], w2[8];
; #pragma unroll
;     for (int e = 0; e < 8; ++e) { w0[e] = cw[col + e]; w1[e] = cw[2048 + col + e]; w2[e] = cw[4096 + col + e]; }
; #pragma unroll
;     for (int ai = 0; ai < 2; ++ai) {
;       const int row0 = u.pm * BM + ai * HALF + wr * 64, span = row0 >> 6;
;       float rsv[4];
; #pragma unroll
;       for (int m = 0; m < 4; ++m) rsv[m] = row_rstd(ssq, row0 + 16 * m + fr, fq);
; template <class Epi, class Sched = StaticOrder>
; DI void gemm_phase(LAS unsigned char* lds, const Gemm g, const Sched& S, const Epi& E) {
;     ...
;       PG8_STAGE(PG8_SB(1, 1), b3 + hstep, voffB);
;       PG8_WAIT_V(6); PG8_BAR; PG8_MMA(1, 1, At, B1); PG8_BAR;
	s_setprio 0
	s_add_u32 s12, s12, 0x80080
	s_addc_u32 s13, s13, 0
	s_add_i32 s53, s54, s70
	s_mov_b32 m0, s53
	s_nop 0
	global_load_lds_dwordx4 v162, s[12:13]
	s_add_i32 m0, s53, 0x2000
	s_nop 0
	global_load_lds_dwordx4 v166, s[12:13]
	ds_read_b128 v[128:131], v203
	ds_read_b128 v[132:135], v203 offset:1024
	ds_read_b128 v[136:139], v203 offset:2048
	ds_read_b128 v[140:143], v203 offset:3072
	s_waitcnt vmcnt(6)
	s_setprio 1
	s_barrier
	v_mfma_f32_16x16x32_bf16 v[52:55], v[194:197], v[144:147], v[52:55]
	v_mfma_f32_16x16x32_bf16 v[44:47], v[216:219], v[144:147], v[44:47]
	v_mfma_f32_16x16x32_bf16 v[36:39], v[194:197], v[152:155], v[36:39]
	v_mfma_f32_16x16x32_bf16 v[32:35], v[216:219], v[152:155], v[32:35]
	v_mfma_f32_16x16x32_bf16 v[20:23], v[194:197], v[178:181], v[20:23]
	v_mfma_f32_16x16x32_bf16 v[16:19], v[216:219], v[178:181], v[16:19]
	v_mfma_f32_16x16x32_bf16 v[4:7], v[194:197], v[186:189], v[4:7]
	v_mfma_f32_16x16x32_bf16 v[0:3], v[216:219], v[186:189], v[0:3]
	v_mfma_f32_16x16x32_bf16 v[52:55], v[212:215], v[148:151], v[52:55]
	v_mfma_f32_16x16x32_bf16 v[44:47], v[220:223], v[148:151], v[44:47]
	v_mfma_f32_16x16x32_bf16 v[36:39], v[212:215], v[156:159], v[36:39]
	v_mfma_f32_16x16x32_bf16 v[32:35], v[220:223], v[156:159], v[32:35]
	v_mfma_f32_16x16x32_bf16 v[20:23], v[212:215], v[182:185], v[20:23]
	v_mfma_f32_16x16x32_bf16 v[16:19], v[220:223], v[182:185], v[16:19]
	v_mfma_f32_16x16x32_bf16 v[4:7], v[212:215], v[190:193], v[4:7]
	v_mfma_f32_16x16x32_bf16 v[0:3], v[220:223], v[190:193], v[0:3]
	s_add_i32 s52, s52, 2
	s_add_u32 s10, s10, 0x100
	s_addc_u32 s11, s11, 0
	s_add_u32 s45, s45, 0x100
	s_addc_u32 s49, s49, 0
	s_cmp_gt_u32 s52, 29
	s_barrier
	s_setprio 0
	s_cbranch_scc0 .LBB0_1052
	s_waitcnt lgkmcnt(0)
	s_cmp_lt_i32 s62, 16
	s_mov_b64 s[10:11], -1
	s_cbranch_scc0 .LBB0_1067
	s_lshl_b32 s41, s60, 8
	s_add_i32 s41, s41, s75
	v_or_b32_e32 v186, s41, v177
	v_ashrrev_i32_e32 v187, 31, v186
	v_lshlrev_b64 v[128:129], 7, v[186:187]
	v_or_b32_e32 v180, 16, v186
	v_lshl_add_u64 v[128:129], v[170:171], 0, v[128:129]
	v_ashrrev_i32_e32 v181, 31, v180
	global_load_dwordx4 v[152:155], v[128:129], off
	global_load_dwordx4 v[156:159], v[128:129], off offset:16
	v_lshlrev_b64 v[128:129], 7, v[180:181]
	v_lshl_add_u64 v[128:129], v[170:171], 0, v[128:129]
	global_load_dwordx4 v[188:191], v[128:129], off
	global_load_dwordx4 v[192:195], v[128:129], off offset:16
	v_or_b32_e32 v184, 32, v186
	v_ashrrev_i32_e32 v185, 31, v184
	v_lshlrev_b64 v[128:129], 7, v[184:185]
	v_or_b32_e32 v182, 48, v186
	v_lshl_add_u64 v[128:129], v[170:171], 0, v[128:129]
	v_ashrrev_i32_e32 v183, 31, v182
	global_load_dwordx4 v[212:215], v[128:129], off
	global_load_dwordx4 v[216:219], v[128:129], off offset:16
	v_lshlrev_b64 v[128:129], 7, v[182:183]
	v_lshl_add_u64 v[128:129], v[170:171], 0, v[128:129]
	global_load_dwordx4 v[220:223], v[128:129], off
	global_load_dwordx4 v[224:227], v[128:129], off offset:16
	v_and_b32_e32 v129, 64, v206
	v_lshl_or_b32 v178, s62, 7, v200
	v_xor_b32_e32 v128, 16, v206
	v_add_u32_e32 v129, 64, v129
	v_readlane_b32 s44, v243, 3
	v_xor_b32_e32 v130, 32, v206
	v_ashrrev_i32_e32 v179, 31, v178
	v_readlane_b32 s45, v243, 4
	v_cmp_lt_i32_e32 vcc, v128, v129
	s_movk_i32 s10, 0x2000
	v_lshl_add_u64 v[144:145], v[178:179], 2, s[44:45]
	v_cndmask_b32_e32 v134, v206, v128, vcc
	v_cmp_lt_i32_e32 vcc, v130, v129
	v_lshl_add_u64 v[132:133], v[144:145], 0, s[26:27]
	v_lshl_add_u64 v[136:137], v[144:145], 0, s[28:29]
	v_cndmask_b32_e32 v135, v206, v130, vcc
	v_add_co_u32_e32 v146, vcc, s10, v144
	global_load_dwordx4 v[128:131], v[144:145], off offset:16
	global_load_dwordx4 v[140:143], v[144:145], off
	v_addc_co_u32_e32 v147, vcc, 0, v145, vcc
	v_add_co_u32_e32 v148, vcc, s74, v144
	v_lshlrev_b32_e32 v196, 2, v134
	s_nop 0
	v_addc_co_u32_e32 v149, vcc, 0, v145, vcc
	v_lshlrev_b32_e32 v207, 2, v135
	global_load_dwordx4 v[132:135], v[132:133], off offset:16
	s_nop 0
	global_load_dwordx4 v[136:139], v[136:137], off offset:16
	s_nop 0
	global_load_dwordx4 v[144:147], v[146:147], off
	s_nop 0
	global_load_dwordx4 v[148:151], v[148:149], off
	v_mov_b32_e32 v197, 0
	v_mov_b32_e32 v211, 0
	v_readlane_b32 s46, v243, 5
	v_readlane_b32 s47, v243, 6
	v_readlane_b32 s48, v243, 7
	v_readlane_b32 s49, v243, 8
	v_readlane_b32 s50, v243, 9
	v_readlane_b32 s51, v243, 10
	v_readlane_b32 s52, v243, 11
	v_readlane_b32 s53, v243, 12
	v_readlane_b32 s54, v243, 13
	v_readlane_b32 s55, v243, 14
	v_readlane_b32 s56, v243, 15
	v_readlane_b32 s57, v243, 16
	v_readlane_b32 s58, v243, 17
	v_readlane_b32 s59, v243, 18
	s_waitcnt vmcnt(0)
	v_mov_b32_e32 v208, v152
	v_mov_b32_e32 v209, v156
	v_mov_b32_e32 v156, v153
	v_mov_b32_e32 v152, v154
	v_mov_b32_e32 v153, v158
	v_mov_b32_e32 v158, v155
	v_pk_add_f32 v[154:155], v[208:209], v[156:157]
	v_pk_add_f32 v[152:153], v[152:153], v[158:159]
	v_mov_b32_e32 v156, v188
	v_mov_b32_e32 v157, v192
	v_mov_b32_e32 v192, v189
	v_mov_b32_e32 v158, v190
	v_mov_b32_e32 v159, v194
	v_mov_b32_e32 v194, v191
	v_pk_add_f32 v[152:153], v[154:155], v[152:153]
	v_pk_add_f32 v[154:155], v[156:157], v[192:193]
	v_pk_add_f32 v[156:157], v[158:159], v[194:195]
	v_mov_b32_e32 v188, v212
	v_pk_add_f32 v[154:155], v[154:155], v[156:157]
	v_mov_b32_e32 v157, v152
	v_mov_b32_e32 v156, v154
	v_mov_b32_e32 v152, v155
	v_pk_add_f32 v[152:153], v[156:157], v[152:153]
	ds_bpermute_b32 v155, v196, v153
	ds_bpermute_b32 v154, v196, v152
	v_mov_b32_e32 v189, v216
	v_mov_b32_e32 v216, v213
	v_mov_b32_e32 v190, v214
	v_mov_b32_e32 v191, v218
	s_waitcnt lgkmcnt(0)
; DI unsigned pack2(float lo, float hi) { f32x2 v = {lo, hi}; bf16v2 r = __builtin_convertvector(v, bf16v2); return __builtin_bit_cast(unsigned, r); }
; DI float dpp_ror1(float v) { return __int_as_float(__builtin_amdgcn_update_dpp(0, __float_as_int(v), 0x121, 0xf, 0xf, false)); }
; DI float dpp_ror2(float v) { return __int_as_float(__builtin_amdgcn_update_dpp(0, __float_as_int(v), 0x122, 0xf, 0xf, false)); }
; DI float row_rstd(const float* ssq, int row, int fq) {
;   const f32x4 a = *(const f32x4*)(ssq + (size_t)row * 32 + fq * 8), b = *(const f32x4*)(ssq + (size_t)row * 32 + fq * 8 + 4);
;   float sm = ((a[0] + a[1]) + (a[2] + a[3])) + ((b[0] + b[1]) + (b[2] + b[3]));
;   sm += __shfl_xor(sm, 16); sm += __shfl_xor(sm, 32);
;   return rsqrtf(sm * (1.0f / 2048.f) + 1e-6f);
; }
;   DI void operator()(const f32x4 (&acc)[2][2][4][2], const Unit& u, int wr, int wc, int fr, int fq) const {
;     ...
;       float p1[8], p2[8];
; #pragma unroll
;       for (int e = 0; e < 8; ++e) { p1[e] = 0.f; p2[e] = 0.f; }
; #pragma unroll
;       for (int m = 0; m < 4; ++m) {
;         float g[8], a[8];
;         const float rs1 = rsv[m], rs2 = rs1 * rs1;
; #pragma unroll
;         for (int e = 0; e < 4; ++e) { g[e] = acc[ai][0][m][0][e] * acc[ai][1][m][0][e] * rs2; g[4 + e] = acc[ai][0][m][1][e] * acc[ai][1][m][1][e] * rs2; }
; #pragma unroll
;         for (int e = 0; e < 8; ++e) {
;           const float x1 = dpp_ror1(g[e]), x2 = dpp_ror2(g[e]);
;           const float pr1 = (fr == 0) ? p1[e] : x1, pr2 = (fr < 2) ? p2[e] : x2;
;           a[e] = w2[e] * g[e] + w1[e] * pr1 + w0[e] * pr2;
;           p1[e] = x1; p2[e] = x2;
;         }
;         if (m == 0 && fr < 2) {
;           float* hc = headC + (size_t)(span * 2 + fr) * 2048 + col;
;           *(f32x4*)hc = (f32x4){a[0], a[1], a[2], a[3]}; *(f32x4*)(hc + 4) = (f32x4){a[4], a[5], a[6], a[7]};
;         } else {
;           u32x4 w; w.x = pack2(a[0] * rs1, a[1] * rs1); w.y = pack2(a[2] * rs1, a[3] * rs1); w.z = pack2(a[4] * rs1, a[5] * rs1); w.w = pack2(a[6] * rs1, a[7] * rs1);
;           *(u32x4*)(C + (size_t)(row0 + 16 * m + fr) * 2048 + col) = w;
;         }
	v_pk_add_f32 v[152:153], v[152:153], v[154:155]
	ds_bpermute_b32 v155, v207, v153
	ds_bpermute_b32 v154, v207, v152
	v_mov_b32_e32 v218, v215
	v_mov_b32_e32 v208, v220
	v_mov_b32_e32 v209, v224
	v_mov_b32_e32 v224, v221
	v_mov_b32_e32 v212, v222
	v_mov_b32_e32 v213, v226
	v_mov_b32_e32 v226, v223
	v_pk_add_f32 v[156:157], v[188:189], v[216:217]
	v_pk_add_f32 v[158:159], v[190:191], v[218:219]
	v_pk_add_f32 v[188:189], v[208:209], v[224:225]
	v_pk_add_f32 v[190:191], v[212:213], v[226:227]
	s_waitcnt lgkmcnt(0)
	v_pk_add_f32 v[152:153], v[152:153], v[154:155]
	v_pk_add_f32 v[156:157], v[156:157], v[158:159]
	v_pk_add_f32 v[158:159], v[188:189], v[190:191]
	v_pk_fma_f32 v[188:189], v[152:153], s[30:31], v[176:177] op_sel_hi:[1,0,0]
	v_mov_b32_e32 v153, v156
	v_mul_f32_e32 v152, 0x4b800000, v189
	v_cmp_gt_f32_e64 s[10:11], s84, v189
	v_mov_b32_e32 v156, v159
	v_mov_b32_e32 v194, v123
	v_cndmask_b32_e64 v152, v189, v152, s[10:11]
	v_rsq_f32_e32 v168, v152
	v_mov_b32_e32 v152, v158
	v_pk_add_f32 v[152:153], v[152:153], v[156:157]
	ds_bpermute_b32 v155, v196, v153
	ds_bpermute_b32 v154, v196, v152
	v_mul_f32_e32 v156, 0x45800000, v168
	v_cndmask_b32_e64 v195, v168, v156, s[10:11]
	v_mov_b32_e32 v217, 0
	v_mul_f32_e32 v156, v125, v113
	s_waitcnt lgkmcnt(0)
	v_pk_add_f32 v[190:191], v[152:153], v[154:155]
	v_mov_b32_e32 v152, v111
	v_mov_b32_e32 v153, v195
	v_mul_f32_e32 v154, v124, v112
	v_pk_mul_f32 v[152:153], v[194:195], v[152:153]
	v_mul_f32_e32 v155, v120, v108
	v_mul_f32_e32 v154, v154, v153
	v_pk_mul_f32 v[222:223], v[152:153], v[152:153] op_sel:[0,1] op_sel_hi:[1,0]
	v_mov_b32_e32 v213, 0
	v_mov_b32_dpp v217, v154 row_ror:1 row_mask:0xf bank_mask:0xf
	v_cndmask_b32_e64 v152, v217, 0, s[0:1]
	v_mul_f32_e32 v157, v121, v109
	v_mul_f32_e32 v158, v126, v114
	v_mul_f32_e32 v159, v122, v110
	v_mul_f32_e32 v168, v127, v115
	v_mul_f32_e32 v194, v155, v153
	v_mul_f32_e32 v155, v156, v153
	v_mov_b32_dpp v213, v154 row_ror:2 row_mask:0xf bank_mask:0xf
	v_mov_b32_e32 v221, 0
	v_mul_f32_e32 v152, v144, v152
	v_mul_f32_e32 v208, v157, v153
	v_mul_f32_e32 v156, v158, v153
	v_mul_f32_e32 v159, v159, v153
	v_mul_f32_e32 v157, v168, v153
	v_mov_b32_dpp v221, v155 row_ror:1 row_mask:0xf bank_mask:0xf
	v_cndmask_b32_e64 v153, v213, 0, s[8:9]
	v_fmac_f32_e32 v152, v148, v154
	v_mov_b32_e32 v219, 0
	v_fmac_f32_e32 v152, v140, v153
	v_cndmask_b32_e64 v153, v221, 0, s[0:1]
	v_mov_b32_dpp v219, v155 row_ror:2 row_mask:0xf bank_mask:0xf
	v_mul_f32_e32 v153, v145, v153
	v_mov_b32_e32 v216, 0
	v_cndmask_b32_e64 v154, v219, 0, s[8:9]
	v_fmac_f32_e32 v153, v149, v155
	v_mov_b32_dpp v216, v156 row_ror:1 row_mask:0xf bank_mask:0xf
	v_fmac_f32_e32 v153, v141, v154
	v_mov_b32_e32 v212, 0
	v_cndmask_b32_e64 v154, v216, 0, s[0:1]
	v_mov_b32_e32 v220, 0
	v_mov_b32_dpp v212, v156 row_ror:2 row_mask:0xf bank_mask:0xf
	v_mul_f32_e32 v154, v146, v154
	v_mov_b32_dpp v220, v157 row_ror:1 row_mask:0xf bank_mask:0xf
	v_cndmask_b32_e64 v155, v212, 0, s[8:9]
	v_fmac_f32_e32 v154, v150, v156
	v_mov_b32_e32 v218, 0
	v_fmac_f32_e32 v154, v142, v155
	v_cndmask_b32_e64 v155, v220, 0, s[0:1]
	v_mov_b32_dpp v218, v157 row_ror:2 row_mask:0xf bank_mask:0xf
	v_mul_f32_e32 v155, v147, v155
	v_cndmask_b32_e64 v156, v218, 0, s[8:9]
	v_fmac_f32_e32 v155, v151, v157
	v_mov_b32_dpp v197, v194 row_ror:1 row_mask:0xf bank_mask:0xf
	v_fmac_f32_e32 v155, v143, v156
	v_mov_b32_e32 v189, 0
	v_cndmask_b32_e64 v156, v197, 0, s[0:1]
	v_mov_b32_e32 v214, 0
	v_mov_b32_dpp v189, v194 row_ror:2 row_mask:0xf bank_mask:0xf
	v_mul_f32_e32 v156, v132, v156
	v_mov_b32_dpp v214, v208 row_ror:1 row_mask:0xf bank_mask:0xf
	v_cndmask_b32_e64 v157, v189, 0, s[8:9]
	v_fmac_f32_e32 v156, v136, v194
	v_fmac_f32_e32 v156, v128, v157
	v_cndmask_b32_e64 v157, v214, 0, s[0:1]
	v_mov_b32_e32 v209, 0
	v_mul_f32_e32 v157, v133, v157
	v_fmac_f32_e32 v157, v137, v208
	v_mov_b32_dpp v209, v208 row_ror:2 row_mask:0xf bank_mask:0xf
	v_mov_b32_e32 v208, 0
	v_cndmask_b32_e64 v158, v209, 0, s[8:9]
	v_fmac_f32_e32 v157, v129, v158
	v_mov_b32_dpp v208, v159 row_ror:1 row_mask:0xf bank_mask:0xf
	v_mov_b32_e32 v194, 0
	v_cndmask_b32_e64 v158, v208, 0, s[0:1]
	ds_bpermute_b32 v193, v207, v191
	ds_bpermute_b32 v192, v207, v190
	v_mov_b32_dpp v194, v159 row_ror:2 row_mask:0xf bank_mask:0xf
	v_mov_b32_e32 v215, 0
	v_mul_f32_e32 v158, v134, v158
	v_cndmask_b32_e64 v168, v194, 0, s[8:9]
	v_mov_b32_dpp v215, v222 row_ror:1 row_mask:0xf bank_mask:0xf
	v_fmac_f32_e32 v158, v138, v159
	v_mov_b32_dpp v211, v222 row_ror:2 row_mask:0xf bank_mask:0xf
	v_fmac_f32_e32 v158, v130, v168
	v_cndmask_b32_e64 v168, v215, 0, s[0:1]
	v_mul_f32_e32 v159, v139, v222
	v_cndmask_b32_e64 v223, v211, 0, s[8:9]
	v_fmac_f32_e32 v159, v135, v168
	v_cmp_gt_f32_e32 vcc, s84, v188
	v_fmac_f32_e32 v159, v131, v223
	s_and_saveexec_b64 s[10:11], s[4:5]
	s_xor_b64 s[10:11], exec, s[10:11]
	s_cbranch_execz .LBB0_1056
	v_mul_f32_e32 v152, v195, v152
	v_mul_f32_e32 v153, v195, v153
	v_cvt_pk_bf16_f32 v152, v152, v153
	v_mul_f32_e32 v153, v195, v154
	v_mul_f32_e32 v154, v195, v155
	v_cvt_pk_bf16_f32 v153, v153, v154
	v_mul_f32_e32 v154, v195, v156
	v_mul_f32_e32 v155, v195, v157
	v_cvt_pk_bf16_f32 v154, v154, v155
	v_mul_f32_e32 v155, v195, v158
	v_mul_f32_e32 v156, v195, v159
	v_cvt_pk_bf16_f32 v155, v155, v156
	v_lshlrev_b64 v[156:157], 12, v[186:187]
	v_lshl_add_u64 v[156:157], s[18:19], 0, v[156:157]
	v_lshl_add_u64 v[156:157], v[178:179], 1, v[156:157]
	global_store_dwordx4 v[156:157], v[152:155], off

; #define PG8_STAGE(bufoff, gbase, voff) do { _Pragma("unroll") for (int _i = 0; _i < 2; ++_i) \
;     __builtin_amdgcn_global_load_lds((const unsigned*)((const char*)(gbase) + (voff)[_i]), (LAS unsigned*)(lds + (bufoff) + ldsw + _i * 8192), 16, 0, 0); } while (0)
; #define PG8_LDA(dst, b, h) do { _Pragma("unroll") for (int m = 0; m < 4; ++m) _Pragma("unroll") for (int k = 0; k < 2; ++k) dst[m][k] = *(const LAS bf16x8*)(lds + PG8_SA(b, h) + aoff + m * 2048 + k * 1024); } while (0)
; #define PG8_LDB(dst, b, h) do { _Pragma("unroll") for (int n = 0; n < 2; ++n) _Pragma("unroll") for (int k = 0; k < 2; ++k) dst[n][k] = *(const LAS bf16x8*)(lds + PG8_SB(b, h) + boff + n * 2048 + k * 1024); } while (0)
; #define PG8_MMA(ai, bj, At, Bt) do { __builtin_amdgcn_s_setprio(1); _Pragma("unroll") for (int m = 0; m < 4; ++m) _Pragma("unroll") for (int n = 0; n < 2; ++n) _Pragma("unroll") for (int k = 0; k < 2; ++k) \
;     acc[ai][bj][m][n] = __builtin_amdgcn_mfma_f32_16x16x32_bf16(Bt[n][k], At[m][k], acc[ai][bj][m][n], 0, 0, 0); __builtin_amdgcn_s_setprio(0); } while (0)
; #define PG8_WAIT_V(n) asm volatile("s_waitcnt vmcnt(" #n ")" ::: "memory")
; #define PG8_WAIT_L(n) asm volatile("s_waitcnt lgkmcnt(" #n ")" ::: "memory")
; #define PG8_BAR __builtin_amdgcn_s_barrier()
; #define PG8_SCHED __builtin_amdgcn_sched_barrier(0)
; template <class Epi, class Sched = StaticOrder>
; DI void gemm_phase(LAS unsigned char* lds, const Gemm g, const Sched& S, const Epi& E) {
;     ...
;     for (int t = 0; t < nt; t += 2) {
;       const bool last = (t == nt - 2);
;       const char* a1 = cA + (size_t)(t + 1) * kstep;
;       const char* a2 = last ? nA : cA + (size_t)(t + 2) * kstep; const char* b2 = last ? nB : cB + (size_t)(t + 2) * kstep;
;       const char* a3 = a2 + kstep; const char* b3 = b2 + kstep;
;       PG8_LDB(B0, 0, 0); PG8_SCHED; PG8_LDA(At, 0, 0); PG8_STAGE(PG8_SA(1, 1), a1 + hstep, voffA);
;       PG8_WAIT_L(8); PG8_BAR; PG8_WAIT_L(0); PG8_MMA(0, 0, At, B0); PG8_BAR; PG8_SCHED;
;       PG8_LDB(B1, 0, 1); PG8_STAGE(PG8_SB(0, 0), b2, voffB);
;       PG8_BAR; PG8_WAIT_L(0); PG8_MMA(0, 1, At, B1); PG8_BAR;
;       PG8_LDA(At, 0, 1); PG8_STAGE(PG8_SA(0, 0), a2, voffA);
;       PG8_BAR; PG8_WAIT_L(0); PG8_MMA(1, 0, At, B0); PG8_BAR; PG8_SCHED;
;       PG8_STAGE(PG8_SB(0, 1), b2 + hstep, voffB);
;       PG8_WAIT_V(6); PG8_BAR; PG8_MMA(1, 1, At, B1); PG8_BAR;
.LBB0_1194:
	s_add_u32 s24, s22, 0xfff80080
	s_addc_u32 s25, s23, -1
	s_cmp_eq_u32 s54, 28
	s_cselect_b32 s27, s17, s25
	s_cselect_b32 s26, s43, s24
	s_cselect_b32 s25, s15, s53
	s_cselect_b32 s24, s51, s52
	s_add_i32 m0, s37, 0xc000
	ds_read_b128 v[144:147], v215
	ds_read_b128 v[148:151], v215 offset:1024
	ds_read_b128 v[152:155], v215 offset:2048
	ds_read_b128 v[156:159], v215 offset:3072
	ds_read_b128 v[160:163], v215 offset:4096
	ds_read_b128 v[164:167], v215 offset:5120
	ds_read_b128 v[168:171], v215 offset:6144
	ds_read_b128 v[172:175], v215 offset:7168
	global_load_lds_dwordx4 v184, s[22:23]
	s_add_i32 m0, s37, 0xe000
	s_nop 0
	global_load_lds_dwordx4 v186, s[22:23]
	s_waitcnt lgkmcnt(8)
	s_setprio 1
	s_barrier
	s_waitcnt lgkmcnt(0)
	v_mfma_f32_16x16x32_bf16 v[124:127], v[128:131], v[144:147], v[124:127]
	v_mfma_f32_16x16x32_bf16 v[120:123], v[136:139], v[144:147], v[120:123]
	v_mfma_f32_16x16x32_bf16 v[108:111], v[128:131], v[152:155], v[108:111]
	v_mfma_f32_16x16x32_bf16 v[104:107], v[136:139], v[152:155], v[104:107]
	v_mfma_f32_16x16x32_bf16 v[92:95], v[128:131], v[160:163], v[92:95]
	v_mfma_f32_16x16x32_bf16 v[88:91], v[136:139], v[160:163], v[88:91]
	v_mfma_f32_16x16x32_bf16 v[76:79], v[128:131], v[168:171], v[76:79]
	v_mfma_f32_16x16x32_bf16 v[72:75], v[136:139], v[168:171], v[72:75]
	v_mfma_f32_16x16x32_bf16 v[124:127], v[132:135], v[148:151], v[124:127]
	v_mfma_f32_16x16x32_bf16 v[120:123], v[140:143], v[148:151], v[120:123]
	v_mfma_f32_16x16x32_bf16 v[108:111], v[132:135], v[156:159], v[108:111]
	v_mfma_f32_16x16x32_bf16 v[104:107], v[140:143], v[156:159], v[104:107]
	v_mfma_f32_16x16x32_bf16 v[92:95], v[132:135], v[164:167], v[92:95]
	v_mfma_f32_16x16x32_bf16 v[88:91], v[140:143], v[164:167], v[88:91]
	v_mfma_f32_16x16x32_bf16 v[76:79], v[132:135], v[172:175], v[76:79]
	v_mfma_f32_16x16x32_bf16 v[72:75], v[140:143], v[172:175], v[72:75]
	s_barrier
	s_setprio 0
	s_add_i32 s55, s48, s35
	s_add_u32 s98, s24, 0x80
	s_addc_u32 s99, s25, 0
	s_add_u32 s100, s26, 0x80
	s_addc_u32 s101, s27, 0
	s_mov_b32 m0, s55
	ds_read_b128 v[192:195], v216
	ds_read_b128 v[196:199], v216 offset:1024
	ds_read_b128 v[200:203], v216 offset:2048
	ds_read_b128 v[204:207], v216 offset:3072
	global_load_lds_dwordx4 v180, s[24:25]
	s_add_i32 m0, s55, 0x2000
	s_nop 0
	global_load_lds_dwordx4 v176, s[24:25]
	s_setprio 1
	s_barrier
	s_waitcnt lgkmcnt(0)
	v_mfma_f32_16x16x32_bf16 v[116:119], v[192:195], v[144:147], v[116:119]
	v_mfma_f32_16x16x32_bf16 v[112:115], v[200:203], v[144:147], v[112:115]
	v_mfma_f32_16x16x32_bf16 v[100:103], v[192:195], v[152:155], v[100:103]
	v_mfma_f32_16x16x32_bf16 v[96:99], v[200:203], v[152:155], v[96:99]
	v_mfma_f32_16x16x32_bf16 v[84:87], v[192:195], v[160:163], v[84:87]
	v_mfma_f32_16x16x32_bf16 v[80:83], v[200:203], v[160:163], v[80:83]
	v_mfma_f32_16x16x32_bf16 v[68:71], v[192:195], v[168:171], v[68:71]
	v_mfma_f32_16x16x32_bf16 v[64:67], v[200:203], v[168:171], v[64:67]
	v_mfma_f32_16x16x32_bf16 v[116:119], v[196:199], v[148:151], v[116:119]
	v_mfma_f32_16x16x32_bf16 v[112:115], v[204:207], v[148:151], v[112:115]
	v_mfma_f32_16x16x32_bf16 v[100:103], v[196:199], v[156:159], v[100:103]
	v_mfma_f32_16x16x32_bf16 v[96:99], v[204:207], v[156:159], v[96:99]
	v_mfma_f32_16x16x32_bf16 v[84:87], v[196:199], v[164:167], v[84:87]
	v_mfma_f32_16x16x32_bf16 v[80:83], v[204:207], v[164:167], v[80:83]
	v_mfma_f32_16x16x32_bf16 v[68:71], v[196:199], v[172:175], v[68:71]
	v_mfma_f32_16x16x32_bf16 v[64:67], v[204:207], v[172:175], v[64:67]
	s_barrier
	s_setprio 0
	s_mov_b32 m0, s37
	ds_read_b128 v[144:147], v215 offset:16384
	ds_read_b128 v[148:151], v215 offset:17408
	ds_read_b128 v[152:155], v215 offset:18432
	ds_read_b128 v[156:159], v215 offset:19456
	ds_read_b128 v[160:163], v215 offset:20480
	ds_read_b128 v[164:167], v215 offset:21504
	ds_read_b128 v[168:171], v215 offset:22528
	ds_read_b128 v[172:175], v215 offset:23552
	global_load_lds_dwordx4 v182, s[26:27]
	s_mov_b32 m0, s38
	s_nop 0
	global_load_lds_dwordx4 v178, s[26:27]
	s_waitcnt vmcnt(10)
	s_setprio 1
	s_barrier
	s_waitcnt lgkmcnt(0)
	v_mfma_f32_16x16x32_bf16 v[60:63], v[128:131], v[144:147], v[60:63]
	v_mfma_f32_16x16x32_bf16 v[56:59], v[136:139], v[144:147], v[56:59]
	v_mfma_f32_16x16x32_bf16 v[44:47], v[128:131], v[152:155], v[44:47]
	v_mfma_f32_16x16x32_bf16 v[40:43], v[136:139], v[152:155], v[40:43]
	v_mfma_f32_16x16x32_bf16 v[28:31], v[128:131], v[160:163], v[28:31]
	v_mfma_f32_16x16x32_bf16 v[24:27], v[136:139], v[160:163], v[24:27]
	v_mfma_f32_16x16x32_bf16 v[12:15], v[128:131], v[168:171], v[12:15]
	v_mfma_f32_16x16x32_bf16 v[8:11], v[136:139], v[168:171], v[8:11]
	v_mfma_f32_16x16x32_bf16 v[60:63], v[132:135], v[148:151], v[60:63]
	v_mfma_f32_16x16x32_bf16 v[56:59], v[140:143], v[148:151], v[56:59]
	v_mfma_f32_16x16x32_bf16 v[44:47], v[132:135], v[156:159], v[44:47]
	v_mfma_f32_16x16x32_bf16 v[40:43], v[140:143], v[156:159], v[40:43]
	v_mfma_f32_16x16x32_bf16 v[28:31], v[132:135], v[164:167], v[28:31]
	v_mfma_f32_16x16x32_bf16 v[24:27], v[140:143], v[164:167], v[24:27]
	v_mfma_f32_16x16x32_bf16 v[12:15], v[132:135], v[172:175], v[12:15]
	v_mfma_f32_16x16x32_bf16 v[8:11], v[140:143], v[172:175], v[8:11]
	s_barrier
	s_setprio 0
	s_add_u32 s56, s24, 0x80000
	s_addc_u32 s57, s25, 0
	s_add_i32 s55, s49, s35
	s_mov_b32 m0, s55
	s_nop 0
	global_load_lds_dwordx4 v180, s[56:57]
	s_add_i32 m0, s55, 0x2000
	s_nop 0
	global_load_lds_dwordx4 v176, s[56:57]
	s_add_i32 s55, 0, 0x18000
	v_add_u32_e32 v140, s55, v212
	ds_read_b128 v[128:131], v140
	ds_read_b128 v[132:135], v140 offset:1024
	ds_read_b128 v[136:139], v140 offset:2048
	ds_read_b128 v[140:143], v140 offset:3072
	s_waitcnt vmcnt(6)
	s_setprio 1
	s_barrier
; #define PG8_STAGE(bufoff, gbase, voff) do { _Pragma("unroll") for (int _i = 0; _i < 2; ++_i) \
;     __builtin_amdgcn_global_load_lds((const unsigned*)((const char*)(gbase) + (voff)[_i]), (LAS unsigned*)(lds + (bufoff) + ldsw + _i * 8192), 16, 0, 0); } while (0)
; #define PG8_LDA(dst, b, h) do { _Pragma("unroll") for (int m = 0; m < 4; ++m) _Pragma("unroll") for (int k = 0; k < 2; ++k) dst[m][k] = *(const LAS bf16x8*)(lds + PG8_SA(b, h) + aoff + m * 2048 + k * 1024); } while (0)
; #define PG8_LDB(dst, b, h) do { _Pragma("unroll") for (int n = 0; n < 2; ++n) _Pragma("unroll") for (int k = 0; k < 2; ++k) dst[n][k] = *(const LAS bf16x8*)(lds + PG8_SB(b, h) + boff + n * 2048 + k * 1024); } while (0)
; #define PG8_MMA(ai, bj, At, Bt) do { __builtin_amdgcn_s_setprio(1); _Pragma("unroll") for (int m = 0; m < 4; ++m) _Pragma("unroll") for (int n = 0; n < 2; ++n) _Pragma("unroll") for (int k = 0; k < 2; ++k) \
;     acc[ai][bj][m][n] = __builtin_amdgcn_mfma_f32_16x16x32_bf16(Bt[n][k], At[m][k], acc[ai][bj][m][n], 0, 0, 0); __builtin_amdgcn_s_setprio(0); } while (0)
; #define PG8_WAIT_V(n) asm volatile("s_waitcnt vmcnt(" #n ")" ::: "memory")
; #define PG8_WAIT_L(n) asm volatile("s_waitcnt lgkmcnt(" #n ")" ::: "memory")
; #define PG8_BAR __builtin_amdgcn_s_barrier()
; #define PG8_SCHED __builtin_amdgcn_sched_barrier(0)
; template <class Epi, class Sched = StaticOrder>
; DI void gemm_phase(LAS unsigned char* lds, const Gemm g, const Sched& S, const Epi& E) {
;     ...
;       PG8_WAIT_V(6); PG8_BAR; PG8_MMA(1, 1, At, B1); PG8_BAR;
;       PG8_LDB(B0, 1, 0); PG8_SCHED; PG8_LDA(At, 1, 0); PG8_STAGE(PG8_SA(0, 1), a2 + hstep, voffA);
;       PG8_WAIT_L(8); PG8_BAR; PG8_WAIT_L(0); PG8_MMA(0, 0, At, B0); PG8_BAR; PG8_SCHED;
;       PG8_LDB(B1, 1, 1); PG8_STAGE(PG8_SB(1, 0), b3, voffB);
;       PG8_BAR; PG8_WAIT_L(0); PG8_MMA(0, 1, At, B1); PG8_BAR;
;       PG8_LDA(At, 1, 1); PG8_STAGE(PG8_SA(1, 0), a3, voffA);
;       PG8_BAR; PG8_WAIT_L(0); PG8_MMA(1, 0, At, B0); PG8_BAR; PG8_SCHED;
	v_mfma_f32_16x16x32_bf16 v[52:55], v[192:195], v[144:147], v[52:55]
	v_mfma_f32_16x16x32_bf16 v[48:51], v[200:203], v[144:147], v[48:51]
	v_mfma_f32_16x16x32_bf16 v[36:39], v[192:195], v[152:155], v[36:39]
	v_mfma_f32_16x16x32_bf16 v[32:35], v[200:203], v[152:155], v[32:35]
	v_mfma_f32_16x16x32_bf16 v[20:23], v[192:195], v[160:163], v[20:23]
	v_mfma_f32_16x16x32_bf16 v[16:19], v[200:203], v[160:163], v[16:19]
	v_mfma_f32_16x16x32_bf16 v[4:7], v[192:195], v[168:171], v[4:7]
	v_mfma_f32_16x16x32_bf16 v[0:3], v[200:203], v[168:171], v[0:3]
	v_mfma_f32_16x16x32_bf16 v[52:55], v[196:199], v[148:151], v[52:55]
	v_mfma_f32_16x16x32_bf16 v[48:51], v[204:207], v[148:151], v[48:51]
	v_mfma_f32_16x16x32_bf16 v[36:39], v[196:199], v[156:159], v[36:39]
	v_mfma_f32_16x16x32_bf16 v[32:35], v[204:207], v[156:159], v[32:35]
	v_mfma_f32_16x16x32_bf16 v[20:23], v[196:199], v[164:167], v[20:23]
	v_mfma_f32_16x16x32_bf16 v[16:19], v[204:207], v[164:167], v[16:19]
	v_mfma_f32_16x16x32_bf16 v[4:7], v[196:199], v[172:175], v[4:7]
	v_mfma_f32_16x16x32_bf16 v[0:3], v[204:207], v[172:175], v[0:3]
	s_barrier
	s_setprio 0
	s_add_u32 s26, s26, 0x80000
	s_addc_u32 s27, s27, 0
	s_mov_b32 m0, s39
	ds_read_b128 v[144:147], v215 offset:32768
	ds_read_b128 v[148:151], v215 offset:33792
	ds_read_b128 v[152:155], v215 offset:34816
	ds_read_b128 v[156:159], v215 offset:35840
	ds_read_b128 v[160:163], v215 offset:36864
	ds_read_b128 v[164:167], v215 offset:37888
	ds_read_b128 v[168:171], v215 offset:38912
	ds_read_b128 v[172:175], v215 offset:39936
	global_load_lds_dwordx4 v182, s[26:27]
	s_mov_b32 m0, s40
	s_nop 0
	global_load_lds_dwordx4 v178, s[26:27]
	s_waitcnt lgkmcnt(8)
	s_setprio 1
	s_barrier
	s_waitcnt lgkmcnt(0)
	v_mfma_f32_16x16x32_bf16 v[124:127], v[128:131], v[144:147], v[124:127]
	v_mfma_f32_16x16x32_bf16 v[120:123], v[136:139], v[144:147], v[120:123]
	v_mfma_f32_16x16x32_bf16 v[108:111], v[128:131], v[152:155], v[108:111]
	v_mfma_f32_16x16x32_bf16 v[104:107], v[136:139], v[152:155], v[104:107]
	v_mfma_f32_16x16x32_bf16 v[92:95], v[128:131], v[160:163], v[92:95]
	v_mfma_f32_16x16x32_bf16 v[88:91], v[136:139], v[160:163], v[88:91]
	v_mfma_f32_16x16x32_bf16 v[76:79], v[128:131], v[168:171], v[76:79]
	v_mfma_f32_16x16x32_bf16 v[72:75], v[136:139], v[168:171], v[72:75]
	v_mfma_f32_16x16x32_bf16 v[124:127], v[132:135], v[148:151], v[124:127]
	v_mfma_f32_16x16x32_bf16 v[120:123], v[140:143], v[148:151], v[120:123]
	v_mfma_f32_16x16x32_bf16 v[108:111], v[132:135], v[156:159], v[108:111]
	v_mfma_f32_16x16x32_bf16 v[104:107], v[140:143], v[156:159], v[104:107]
	v_mfma_f32_16x16x32_bf16 v[92:95], v[132:135], v[164:167], v[92:95]
	v_mfma_f32_16x16x32_bf16 v[88:91], v[140:143], v[164:167], v[88:91]
	v_mfma_f32_16x16x32_bf16 v[76:79], v[132:135], v[172:175], v[76:79]
	v_mfma_f32_16x16x32_bf16 v[72:75], v[140:143], v[172:175], v[72:75]
	s_barrier
	s_setprio 0
	s_add_i32 s26, 0, 0x1c000
	s_add_i32 s27, s55, s35
	v_add_u32_e32 v204, s26, v212
	s_mov_b32 m0, s27
	ds_read_b128 v[192:195], v204
	ds_read_b128 v[196:199], v204 offset:1024
	ds_read_b128 v[200:203], v204 offset:2048
	ds_read_b128 v[204:207], v204 offset:3072
	global_load_lds_dwordx4 v180, s[98:99]
	s_add_i32 m0, s27, 0x2000
	s_nop 0
	global_load_lds_dwordx4 v176, s[98:99]
	s_setprio 1
	s_barrier
	s_waitcnt lgkmcnt(0)
	v_mfma_f32_16x16x32_bf16 v[116:119], v[192:195], v[144:147], v[116:119]
	v_mfma_f32_16x16x32_bf16 v[112:115], v[200:203], v[144:147], v[112:115]
	v_mfma_f32_16x16x32_bf16 v[100:103], v[192:195], v[152:155], v[100:103]
	v_mfma_f32_16x16x32_bf16 v[96:99], v[200:203], v[152:155], v[96:99]
	v_mfma_f32_16x16x32_bf16 v[84:87], v[192:195], v[160:163], v[84:87]
	v_mfma_f32_16x16x32_bf16 v[80:83], v[200:203], v[160:163], v[80:83]
	v_mfma_f32_16x16x32_bf16 v[68:71], v[192:195], v[168:171], v[68:71]
	v_mfma_f32_16x16x32_bf16 v[64:67], v[200:203], v[168:171], v[64:67]
	v_mfma_f32_16x16x32_bf16 v[116:119], v[196:199], v[148:151], v[116:119]
	v_mfma_f32_16x16x32_bf16 v[112:115], v[204:207], v[148:151], v[112:115]
	v_mfma_f32_16x16x32_bf16 v[100:103], v[196:199], v[156:159], v[100:103]
	v_mfma_f32_16x16x32_bf16 v[96:99], v[204:207], v[156:159], v[96:99]
	v_mfma_f32_16x16x32_bf16 v[84:87], v[196:199], v[164:167], v[84:87]
	v_mfma_f32_16x16x32_bf16 v[80:83], v[204:207], v[164:167], v[80:83]
	v_mfma_f32_16x16x32_bf16 v[68:71], v[196:199], v[172:175], v[68:71]
	v_mfma_f32_16x16x32_bf16 v[64:67], v[204:207], v[172:175], v[64:67]
	s_barrier
	s_setprio 0
	s_mov_b32 m0, s44
	ds_read_b128 v[144:147], v215 offset:49152
	ds_read_b128 v[148:151], v215 offset:50176
	ds_read_b128 v[152:155], v215 offset:51200
	ds_read_b128 v[156:159], v215 offset:52224
	ds_read_b128 v[160:163], v215 offset:53248
	ds_read_b128 v[164:167], v215 offset:54272
	ds_read_b128 v[168:171], v215 offset:55296
	ds_read_b128 v[172:175], v215 offset:56320
	global_load_lds_dwordx4 v182, s[100:101]
	s_mov_b32 m0, s45
	s_nop 0
	global_load_lds_dwordx4 v178, s[100:101]
	s_waitcnt vmcnt(10)
	s_setprio 1
	s_barrier
	s_waitcnt lgkmcnt(0)
	v_mfma_f32_16x16x32_bf16 v[60:63], v[128:131], v[144:147], v[60:63]
	v_mfma_f32_16x16x32_bf16 v[56:59], v[136:139], v[144:147], v[56:59]
	v_mfma_f32_16x16x32_bf16 v[44:47], v[128:131], v[152:155], v[44:47]
	v_mfma_f32_16x16x32_bf16 v[40:43], v[136:139], v[152:155], v[40:43]
	v_mfma_f32_16x16x32_bf16 v[28:31], v[128:131], v[160:163], v[28:31]
	v_mfma_f32_16x16x32_bf16 v[24:27], v[136:139], v[160:163], v[24:27]
	v_mfma_f32_16x16x32_bf16 v[12:15], v[128:131], v[168:171], v[12:15]
	v_mfma_f32_16x16x32_bf16 v[8:11], v[136:139], v[168:171], v[8:11]
	v_mfma_f32_16x16x32_bf16 v[60:63], v[132:135], v[148:151], v[60:63]
	v_mfma_f32_16x16x32_bf16 v[56:59], v[140:143], v[148:151], v[56:59]
	v_mfma_f32_16x16x32_bf16 v[44:47], v[132:135], v[156:159], v[44:47]
	v_mfma_f32_16x16x32_bf16 v[40:43], v[140:143], v[156:159], v[40:43]
	v_mfma_f32_16x16x32_bf16 v[28:31], v[132:135], v[164:167], v[28:31]
	v_mfma_f32_16x16x32_bf16 v[24:27], v[140:143], v[164:167], v[24:27]
	v_mfma_f32_16x16x32_bf16 v[12:15], v[132:135], v[172:175], v[12:15]
	v_mfma_f32_16x16x32_bf16 v[8:11], v[140:143], v[172:175], v[8:11]
	s_barrier
; DI unsigned pack2(float lo, float hi) { f32x2 v = {lo, hi}; bf16v2 r = __builtin_convertvector(v, bf16v2); return __builtin_bit_cast(unsigned, r); }
; #define PG8_STAGE(bufoff, gbase, voff) do { _Pragma("unroll") for (int _i = 0; _i < 2; ++_i) \
;     __builtin_amdgcn_global_load_lds((const unsigned*)((const char*)(gbase) + (voff)[_i]), (LAS unsigned*)(lds + (bufoff) + ldsw + _i * 8192), 16, 0, 0); } while (0)
; #define PG8_WAIT_V(n) asm volatile("s_waitcnt vmcnt(" #n ")" ::: "memory")
; #define PG8_BAR __builtin_amdgcn_s_barrier()
;   DI void operator()(const f32x4 (&acc)[2][2][4][2], const Unit& u, int wr, int wc, int fr, int fq) const {
;     const int row0 = u.pm * BM + wr * 64 + fr, col0 = u.pn * BM + wc * 32 + 8 * fq;
; #pragma unroll
;     for (int ai = 0; ai < 2; ++ai) {
;       f32x4 bv[4][2][2];
; #pragma unroll
;       for (int m = 0; m < 4; ++m)
; #pragma unroll
;         for (int bj = 0; bj < 2; ++bj) {
;           const float* bp = base + (size_t)(row0 + ai * HALF + m * 16) * 2048 + col0 + bj * HALF;
;           bv[m][bj][0] = *(const f32x4*)bp; bv[m][bj][1] = *(const f32x4*)(bp + 4);
;         }
; #pragma unroll
;       for (int m = 0; m < 4; ++m) {
;         const int row = row0 + ai * HALF + m * 16;
;         const size_t off = (size_t)row * 2048 + col0;
;         float ss = 0.f;
; #pragma unroll
;         for (int bj = 0; bj < 2; ++bj) {
;           const f32x4 v0 = acc[ai][bj][m][0] + bv[m][bj][0], v1 = acc[ai][bj][m][1] + bv[m][bj][1];
;           *(f32x4*)(C + off + bj * HALF) = v0; *(f32x4*)(C + off + bj * HALF + 4) = v1;
;           if (xb) {
;             u32x4 w; w.x = pack2(v0[0], v0[1]); w.y = pack2(v0[2], v0[3]); w.z = pack2(v1[0], v1[1]); w.w = pack2(v1[2], v1[3]);
;             *(u32x4*)(xb + off + bj * HALF) = w;
;             ss += v0[0] * v0[0] + v0[1] * v0[1] + v0[2] * v0[2] + v0[3] * v0[3] + v1[0] * v1[0] + v1[1] * v1[1] + v1[2] * v1[2] + v1[3] * v1[3];
;           }
;         }
;         if (xb) {
;           ss += __shfl_xor(ss, 16); ss += __shfl_xor(ss, 32);
;           if (fq == 0) ssq[(size_t)row * 32 + u.pn * 4 + wc] = ss;
;         }
;       }
;     }
; template <class Epi, class Sched = StaticOrder>
; DI void gemm_phase(LAS unsigned char* lds, const Gemm g, const Sched& S, const Epi& E) {
;     ...
;       PG8_STAGE(PG8_SB(1, 1), b3 + hstep, voffB);
;       PG8_WAIT_V(6); PG8_BAR; PG8_MMA(1, 1, At, B1); PG8_BAR;
	s_setprio 0
	s_add_u32 s24, s24, 0x80080
	s_addc_u32 s25, s25, 0
	s_add_i32 s26, s26, s35
	s_mov_b32 m0, s26
	s_nop 0
	global_load_lds_dwordx4 v180, s[24:25]
	s_add_i32 m0, s26, 0x2000
	s_nop 0
	global_load_lds_dwordx4 v176, s[24:25]
	ds_read_b128 v[128:131], v214
	ds_read_b128 v[132:135], v214 offset:1024
	ds_read_b128 v[136:139], v214 offset:2048
	ds_read_b128 v[140:143], v214 offset:3072
	s_waitcnt vmcnt(6)
	s_setprio 1
	s_barrier
	v_mfma_f32_16x16x32_bf16 v[52:55], v[192:195], v[144:147], v[52:55]
	v_mfma_f32_16x16x32_bf16 v[48:51], v[200:203], v[144:147], v[48:51]
	v_mfma_f32_16x16x32_bf16 v[36:39], v[192:195], v[152:155], v[36:39]
	v_mfma_f32_16x16x32_bf16 v[32:35], v[200:203], v[152:155], v[32:35]
	v_mfma_f32_16x16x32_bf16 v[20:23], v[192:195], v[160:163], v[20:23]
	v_mfma_f32_16x16x32_bf16 v[16:19], v[200:203], v[160:163], v[16:19]
	v_mfma_f32_16x16x32_bf16 v[4:7], v[192:195], v[168:171], v[4:7]
	v_mfma_f32_16x16x32_bf16 v[0:3], v[200:203], v[168:171], v[0:3]
	v_mfma_f32_16x16x32_bf16 v[52:55], v[196:199], v[148:151], v[52:55]
	v_mfma_f32_16x16x32_bf16 v[48:51], v[204:207], v[148:151], v[48:51]
	v_mfma_f32_16x16x32_bf16 v[36:39], v[196:199], v[156:159], v[36:39]
	v_mfma_f32_16x16x32_bf16 v[32:35], v[204:207], v[156:159], v[32:35]
	v_mfma_f32_16x16x32_bf16 v[20:23], v[196:199], v[164:167], v[20:23]
	v_mfma_f32_16x16x32_bf16 v[16:19], v[204:207], v[164:167], v[16:19]
	v_mfma_f32_16x16x32_bf16 v[4:7], v[196:199], v[172:175], v[4:7]
	v_mfma_f32_16x16x32_bf16 v[0:3], v[204:207], v[172:175], v[0:3]
	s_add_i32 s54, s54, 2
	s_add_u32 s22, s22, 0x100
	s_addc_u32 s23, s23, 0
	s_add_u32 s52, s52, 0x100
	s_addc_u32 s53, s53, 0
	s_cmp_gt_u32 s54, 29
	s_barrier
	s_setprio 0
	s_cbranch_scc0 .LBB0_1194
	s_waitcnt lgkmcnt(0)
	v_lshl_add_u32 v194, s12, 8, v211
	v_lshl_or_b32 v192, s42, 8, v213
	v_readlane_b32 s52, v243, 3
	v_ashrrev_i32_e32 v193, 31, v192
	v_readlane_b32 s66, v243, 17
	v_readlane_b32 s67, v243, 18
	v_ashrrev_i32_e32 v195, 31, v194
	v_lshlrev_b64 v[128:129], 13, v[194:195]
	v_lshl_add_u64 v[196:197], v[192:193], 2, s[66:67]
	v_lshl_add_u64 v[236:237], v[196:197], 0, v[128:129]
	global_load_dwordx4 v[220:223], v[236:237], off
	global_load_dwordx4 v[224:227], v[236:237], off offset:16
	global_load_dwordx4 v[228:231], v[236:237], off offset:512
	global_load_dwordx4 v[232:235], v[236:237], off offset:528
	v_or_b32_e32 v206, 16, v194
	v_or_b32_e32 v202, 32, v194
	v_or_b32_e32 v198, 48, v194
	v_ashrrev_i32_e32 v207, 31, v206
	v_ashrrev_i32_e32 v203, 31, v202
	v_ashrrev_i32_e32 v199, 31, v198
	v_lshlrev_b64 v[128:129], 13, v[206:207]
	v_lshlrev_b64 v[130:131], 13, v[202:203]
	v_lshlrev_b64 v[132:133], 13, v[198:199]
	v_lshl_add_u64 v[208:209], v[196:197], 0, v[128:129]
	v_lshl_add_u64 v[204:205], v[196:197], 0, v[130:131]
	v_lshl_add_u64 v[200:201], v[196:197], 0, v[132:133]
	global_load_dwordx4 v[168:171], v[208:209], off offset:16
	global_load_dwordx4 v[172:175], v[208:209], off
	global_load_dwordx4 v[160:163], v[208:209], off offset:528
	global_load_dwordx4 v[164:167], v[208:209], off offset:512
	global_load_dwordx4 v[152:155], v[204:205], off offset:16
	global_load_dwordx4 v[156:159], v[204:205], off
	global_load_dwordx4 v[144:147], v[204:205], off offset:528
	global_load_dwordx4 v[148:151], v[204:205], off offset:512
	global_load_dwordx4 v[136:139], v[200:201], off offset:16
	global_load_dwordx4 v[140:143], v[200:201], off
	global_load_dwordx4 v[128:131], v[200:201], off offset:528
	global_load_dwordx4 v[132:135], v[200:201], off offset:512
	v_and_b32_e32 v218, 64, v217
	v_xor_b32_e32 v238, 16, v217
	v_add_u32_e32 v240, 64, v218
	v_xor_b32_e32 v239, 32, v217
	v_cmp_lt_i32_e32 vcc, v238, v240
	v_lshlrev_b64 v[218:219], 11, v[194:195]
	s_lshl_b32 s22, s42, 2
	v_cndmask_b32_e32 v241, v217, v238, vcc
	v_cmp_lt_i32_e32 vcc, v239, v240
	s_ashr_i32 s23, s22, 31
	v_readlane_b32 s53, v243, 4
	v_cndmask_b32_e32 v240, v217, v239, vcc
	v_lshl_add_u64 v[238:239], v[218:219], 0, v[192:193]
	v_lshlrev_b32_e32 v218, 2, v241
	v_lshl_add_u64 v[238:239], v[238:239], 1, s[2:3]
	v_readlane_b32 s54, v243, 5
	v_readlane_b32 s55, v243, 6
	v_readlane_b32 s56, v243, 7
	v_readlane_b32 s57, v243, 8
	v_readlane_b32 s58, v243, 9
	v_readlane_b32 s59, v243, 10
	v_readlane_b32 s60, v243, 11
	v_readlane_b32 s61, v243, 12
	v_readlane_b32 s62, v243, 13
	v_readlane_b32 s63, v243, 14
	v_readlane_b32 s64, v243, 15
	v_readlane_b32 s65, v243, 16
	s_waitcnt vmcnt(0)
	v_pk_add_f32 v[126:127], v[126:127], v[222:223]
	v_pk_add_f32 v[124:125], v[124:125], v[220:221]
	v_pk_add_f32 v[116:117], v[116:117], v[228:229]
	v_pk_add_f32 v[122:123], v[122:123], v[226:227]
	v_pk_add_f32 v[120:121], v[120:121], v[224:225]
	v_pk_add_f32 v[220:221], v[112:113], v[232:233]
	global_store_dwordx4 v[236:237], v[124:127], off
	global_store_dwordx4 v[236:237], v[120:123], off offset:16
	v_cvt_pk_bf16_f32 v112, v124, v125
	v_mul_f32_e32 v125, v125, v125
	v_mul_f32_e32 v219, v117, v117
	v_pk_add_f32 v[118:119], v[118:119], v[230:231]
	v_fmac_f32_e32 v125, v124, v124
	v_fmac_f32_e32 v219, v116, v116
	v_fmac_f32_e32 v125, v126, v126
	v_fmac_f32_e32 v219, v118, v118
	v_fmac_f32_e32 v125, v127, v127
	v_fmac_f32_e32 v219, v119, v119
	v_fmac_f32_e32 v125, v120, v120
	v_fmac_f32_e32 v219, v220, v220
	v_pk_add_f32 v[222:223], v[114:115], v[234:235]
	v_fmac_f32_e32 v125, v121, v121
	v_fmac_f32_e32 v219, v221, v221
	v_fmac_f32_e32 v125, v122, v122
	v_fmac_f32_e32 v219, v222, v222
	v_fmac_f32_e32 v125, v123, v123
	v_fmac_f32_e32 v219, v223, v223
	v_cvt_pk_bf16_f32 v114, v120, v121
	v_add_f32_e32 v121, v125, v219
	v_cvt_pk_bf16_f32 v115, v122, v123
	ds_bpermute_b32 v122, v218, v121
	v_cvt_pk_bf16_f32 v113, v126, v127
	global_store_dwordx4 v[238:239], v[112:115], off
	global_store_dwordx4 v[236:237], v[116:119], off offset:512
	global_store_dwordx4 v[236:237], v[220:223], off offset:528
	v_lshlrev_b32_e32 v126, 2, v240
	v_cvt_pk_bf16_f32 v120, v116, v117
	s_waitcnt lgkmcnt(0)
	v_add_f32_e32 v112, v121, v122
	ds_bpermute_b32 v113, v126, v112
	v_cvt_pk_bf16_f32 v121, v118, v119
	v_cvt_pk_bf16_f32 v122, v220, v221
	v_cvt_pk_bf16_f32 v123, v222, v223
	global_store_dwordx4 v[238:239], v[120:123], off offset:256
	s_and_saveexec_b64 s[24:25], s[0:1]
	s_cbranch_execz .LBB0_1197
	s_waitcnt lgkmcnt(0)
	v_add_f32_e32 v114, v112, v113
	v_lshlrev_b64 v[112:113], 7, v[194:195]
	v_lshl_add_u64 v[112:113], s[8:9], 0, v[112:113]
	v_lshl_add_u64 v[112:113], s[22:23], 2, v[112:113]
	s_lshl_b32 s12, s41, 2
	v_lshl_add_u64 v[112:113], v[112:113], 0, s[12:13]
	global_store_dword v[112:113], v114, off

; #define PG8_STAGE(bufoff, gbase, voff) do { _Pragma("unroll") for (int _i = 0; _i < 2; ++_i) \
;     __builtin_amdgcn_global_load_lds((const unsigned*)((const char*)(gbase) + (voff)[_i]), (LAS unsigned*)(lds + (bufoff) + ldsw + _i * 8192), 16, 0, 0); } while (0)
; #define PG8_LDA(dst, b, h) do { _Pragma("unroll") for (int m = 0; m < 4; ++m) _Pragma("unroll") for (int k = 0; k < 2; ++k) dst[m][k] = *(const LAS bf16x8*)(lds + PG8_SA(b, h) + aoff + m * 2048 + k * 1024); } while (0)
; #define PG8_LDB(dst, b, h) do { _Pragma("unroll") for (int n = 0; n < 2; ++n) _Pragma("unroll") for (int k = 0; k < 2; ++k) dst[n][k] = *(const LAS bf16x8*)(lds + PG8_SB(b, h) + boff + n * 2048 + k * 1024); } while (0)
; #define PG8_MMA(ai, bj, At, Bt) do { __builtin_amdgcn_s_setprio(1); _Pragma("unroll") for (int m = 0; m < 4; ++m) _Pragma("unroll") for (int n = 0; n < 2; ++n) _Pragma("unroll") for (int k = 0; k < 2; ++k) \
;     acc[ai][bj][m][n] = __builtin_amdgcn_mfma_f32_16x16x32_bf16(Bt[n][k], At[m][k], acc[ai][bj][m][n], 0, 0, 0); __builtin_amdgcn_s_setprio(0); } while (0)
; #define PG8_WAIT_V(n) asm volatile("s_waitcnt vmcnt(" #n ")" ::: "memory")
; #define PG8_WAIT_L(n) asm volatile("s_waitcnt lgkmcnt(" #n ")" ::: "memory")
; #define PG8_BAR __builtin_amdgcn_s_barrier()
; #define PG8_SCHED __builtin_amdgcn_sched_barrier(0)
; template <class Epi, class Sched = StaticOrder>
; DI void gemm_phase(LAS unsigned char* lds, const Gemm g, const Sched& S, const Epi& E) {
;     ...
;     for (int t = 0; t < nt; t += 2) {
;       const bool last = (t == nt - 2);
;       const char* a1 = cA + (size_t)(t + 1) * kstep;
;       const char* a2 = last ? nA : cA + (size_t)(t + 2) * kstep; const char* b2 = last ? nB : cB + (size_t)(t + 2) * kstep;
;       const char* a3 = a2 + kstep; const char* b3 = b2 + kstep;
;       PG8_LDB(B0, 0, 0); PG8_SCHED; PG8_LDA(At, 0, 0); PG8_STAGE(PG8_SA(1, 1), a1 + hstep, voffA);
;       PG8_WAIT_L(8); PG8_BAR; PG8_WAIT_L(0); PG8_MMA(0, 0, At, B0); PG8_BAR; PG8_SCHED;
;       PG8_LDB(B1, 0, 1); PG8_STAGE(PG8_SB(0, 0), b2, voffB);
;       PG8_BAR; PG8_WAIT_L(0); PG8_MMA(0, 1, At, B1); PG8_BAR;
;       PG8_LDA(At, 0, 1); PG8_STAGE(PG8_SA(0, 0), a2, voffA);
;       PG8_BAR; PG8_WAIT_L(0); PG8_MMA(1, 0, At, B0); PG8_BAR; PG8_SCHED;
;       PG8_STAGE(PG8_SB(0, 1), b2 + hstep, voffB);
;       PG8_WAIT_V(6); PG8_BAR; PG8_MMA(1, 1, At, B1); PG8_BAR;
.LBB0_1277:
	s_add_u32 s48, s14, 0xfff80080
	s_addc_u32 s49, s15, -1
	s_cmp_eq_u32 s58, 28
	s_cselect_b32 s51, s41, s49
	s_cselect_b32 s50, s42, s48
	s_cselect_b32 s49, s39, s53
	s_cselect_b32 s48, s43, s52
	s_add_i32 m0, s64, 0xc000
	ds_read_b128 v[80:83], v202
	ds_read_b128 v[84:87], v202 offset:1024
	ds_read_b128 v[88:91], v202 offset:2048
	ds_read_b128 v[92:95], v202 offset:3072
	ds_read_b128 v[180:183], v202 offset:4096
	ds_read_b128 v[184:187], v202 offset:5120
	ds_read_b128 v[188:191], v202 offset:6144
	ds_read_b128 v[192:195], v202 offset:7168
	global_load_lds_dwordx4 v170, s[14:15]
	s_add_i32 m0, s64, 0xe000
	s_nop 0
	global_load_lds_dwordx4 v172, s[14:15]
	s_waitcnt lgkmcnt(8)
	s_setprio 1
	s_barrier
	s_waitcnt lgkmcnt(0)
	v_mfma_f32_16x16x32_bf16 v[156:159], v[64:67], v[80:83], v[156:159]
	v_mfma_f32_16x16x32_bf16 v[144:147], v[72:75], v[80:83], v[144:147]
	v_mfma_f32_16x16x32_bf16 v[140:143], v[64:67], v[88:91], v[140:143]
	v_mfma_f32_16x16x32_bf16 v[132:135], v[72:75], v[88:91], v[132:135]
	v_mfma_f32_16x16x32_bf16 v[124:127], v[64:67], v[180:183], v[124:127]
	v_mfma_f32_16x16x32_bf16 v[116:119], v[72:75], v[180:183], v[116:119]
	v_mfma_f32_16x16x32_bf16 v[112:115], v[64:67], v[188:191], v[112:115]
	v_mfma_f32_16x16x32_bf16 v[108:111], v[72:75], v[188:191], v[108:111]
	v_mfma_f32_16x16x32_bf16 v[156:159], v[68:71], v[84:87], v[156:159]
	v_mfma_f32_16x16x32_bf16 v[144:147], v[76:79], v[84:87], v[144:147]
	v_mfma_f32_16x16x32_bf16 v[140:143], v[68:71], v[92:95], v[140:143]
	v_mfma_f32_16x16x32_bf16 v[132:135], v[76:79], v[92:95], v[132:135]
	v_mfma_f32_16x16x32_bf16 v[124:127], v[68:71], v[184:187], v[124:127]
	v_mfma_f32_16x16x32_bf16 v[116:119], v[76:79], v[184:187], v[116:119]
	v_mfma_f32_16x16x32_bf16 v[112:115], v[68:71], v[192:195], v[112:115]
	v_mfma_f32_16x16x32_bf16 v[108:111], v[76:79], v[192:195], v[108:111]
	s_barrier
	s_setprio 0
	s_add_i32 s59, s72, s62
	s_add_u32 s98, s48, 0x80
	s_addc_u32 s99, s49, 0
	s_add_u32 s100, s50, 0x80
	s_addc_u32 s101, s51, 0
	s_mov_b32 m0, s59
	ds_read_b128 v[206:209], v203
	ds_read_b128 v[212:215], v203 offset:1024
	ds_read_b128 v[216:219], v203 offset:2048
	ds_read_b128 v[220:223], v203 offset:3072
	global_load_lds_dwordx4 v164, s[48:49]
	s_add_i32 m0, s59, 0x2000
	s_nop 0
	global_load_lds_dwordx4 v160, s[48:49]
	s_setprio 1
	s_barrier
	s_waitcnt lgkmcnt(0)
	v_mfma_f32_16x16x32_bf16 v[152:155], v[206:209], v[80:83], v[152:155]
	v_mfma_f32_16x16x32_bf16 v[80:83], v[216:219], v[80:83], v[148:151]
	v_mfma_f32_16x16x32_bf16 v[152:155], v[212:215], v[84:87], v[152:155]
	v_mfma_f32_16x16x32_bf16 v[80:83], v[220:223], v[84:87], v[80:83]
	v_mfma_f32_16x16x32_bf16 v[84:87], v[206:209], v[88:91], v[136:139]
	v_mfma_f32_16x16x32_bf16 v[88:91], v[216:219], v[88:91], v[128:131]
	v_mfma_f32_16x16x32_bf16 v[104:107], v[216:219], v[180:183], v[104:107]
	v_mfma_f32_16x16x32_bf16 v[100:103], v[206:209], v[188:191], v[100:103]
	v_mfma_f32_16x16x32_bf16 v[96:99], v[216:219], v[188:191], v[96:99]
	v_mfma_f32_16x16x32_bf16 v[84:87], v[212:215], v[92:95], v[84:87]
	v_mfma_f32_16x16x32_bf16 v[88:91], v[220:223], v[92:95], v[88:91]
	v_mfma_f32_16x16x32_bf16 v[92:95], v[206:209], v[180:183], v[120:123]
	v_mfma_f32_16x16x32_bf16 v[104:107], v[220:223], v[184:187], v[104:107]
	v_mfma_f32_16x16x32_bf16 v[100:103], v[212:215], v[192:195], v[100:103]
	v_mfma_f32_16x16x32_bf16 v[96:99], v[220:223], v[192:195], v[96:99]
	v_mfma_f32_16x16x32_bf16 v[92:95], v[212:215], v[184:187], v[92:95]
	s_barrier
	s_setprio 0
	s_mov_b32 m0, s64
	ds_read_b128 v[120:123], v202 offset:16384
	ds_read_b128 v[128:131], v202 offset:17408
	ds_read_b128 v[136:139], v202 offset:18432
	ds_read_b128 v[148:151], v202 offset:19456
	ds_read_b128 v[180:183], v202 offset:20480
	ds_read_b128 v[184:187], v202 offset:21504
	ds_read_b128 v[188:191], v202 offset:22528
	ds_read_b128 v[192:195], v202 offset:23552
	global_load_lds_dwordx4 v166, s[50:51]
	s_mov_b32 m0, s65
	s_nop 0
	global_load_lds_dwordx4 v162, s[50:51]
	s_waitcnt vmcnt(10)
	s_setprio 1
	s_barrier
	s_waitcnt lgkmcnt(0)
	v_mfma_f32_16x16x32_bf16 v[60:63], v[64:67], v[120:123], v[60:63]
	v_mfma_f32_16x16x32_bf16 v[48:51], v[72:75], v[120:123], v[48:51]
	v_mfma_f32_16x16x32_bf16 v[44:47], v[64:67], v[136:139], v[44:47]
	v_mfma_f32_16x16x32_bf16 v[36:39], v[72:75], v[136:139], v[36:39]
	v_mfma_f32_16x16x32_bf16 v[28:31], v[64:67], v[180:183], v[28:31]
	v_mfma_f32_16x16x32_bf16 v[20:23], v[72:75], v[180:183], v[20:23]
	v_mfma_f32_16x16x32_bf16 v[16:19], v[64:67], v[188:191], v[16:19]
	v_mfma_f32_16x16x32_bf16 v[12:15], v[72:75], v[188:191], v[12:15]
	v_mfma_f32_16x16x32_bf16 v[60:63], v[68:71], v[128:131], v[60:63]
	v_mfma_f32_16x16x32_bf16 v[48:51], v[76:79], v[128:131], v[48:51]
	v_mfma_f32_16x16x32_bf16 v[44:47], v[68:71], v[148:151], v[44:47]
	v_mfma_f32_16x16x32_bf16 v[36:39], v[76:79], v[148:151], v[36:39]
	v_mfma_f32_16x16x32_bf16 v[28:31], v[68:71], v[184:187], v[28:31]
	v_mfma_f32_16x16x32_bf16 v[20:23], v[76:79], v[184:187], v[20:23]
	v_mfma_f32_16x16x32_bf16 v[16:19], v[68:71], v[192:195], v[16:19]
	v_mfma_f32_16x16x32_bf16 v[12:15], v[76:79], v[192:195], v[12:15]
	s_barrier
	s_setprio 0
	s_add_u32 s78, s48, 0x80000
	s_addc_u32 s79, s49, 0
	s_add_i32 s59, s73, s62
	s_mov_b32 m0, s59
	s_nop 0
	global_load_lds_dwordx4 v164, s[78:79]
	s_add_i32 m0, s59, 0x2000
	s_nop 0
	global_load_lds_dwordx4 v160, s[78:79]
	s_add_i32 s59, 0, 0x18000
	v_add_u32_e32 v76, s59, v198
	ds_read_b128 v[64:67], v76
	ds_read_b128 v[68:71], v76 offset:1024
	ds_read_b128 v[72:75], v76 offset:2048
	ds_read_b128 v[76:79], v76 offset:3072
	s_waitcnt vmcnt(6)
	s_setprio 1
	s_barrier
; #define PG8_STAGE(bufoff, gbase, voff) do { _Pragma("unroll") for (int _i = 0; _i < 2; ++_i) \
;     __builtin_amdgcn_global_load_lds((const unsigned*)((const char*)(gbase) + (voff)[_i]), (LAS unsigned*)(lds + (bufoff) + ldsw + _i * 8192), 16, 0, 0); } while (0)
; #define PG8_LDA(dst, b, h) do { _Pragma("unroll") for (int m = 0; m < 4; ++m) _Pragma("unroll") for (int k = 0; k < 2; ++k) dst[m][k] = *(const LAS bf16x8*)(lds + PG8_SA(b, h) + aoff + m * 2048 + k * 1024); } while (0)
; #define PG8_LDB(dst, b, h) do { _Pragma("unroll") for (int n = 0; n < 2; ++n) _Pragma("unroll") for (int k = 0; k < 2; ++k) dst[n][k] = *(const LAS bf16x8*)(lds + PG8_SB(b, h) + boff + n * 2048 + k * 1024); } while (0)
; #define PG8_MMA(ai, bj, At, Bt) do { __builtin_amdgcn_s_setprio(1); _Pragma("unroll") for (int m = 0; m < 4; ++m) _Pragma("unroll") for (int n = 0; n < 2; ++n) _Pragma("unroll") for (int k = 0; k < 2; ++k) \
;     acc[ai][bj][m][n] = __builtin_amdgcn_mfma_f32_16x16x32_bf16(Bt[n][k], At[m][k], acc[ai][bj][m][n], 0, 0, 0); __builtin_amdgcn_s_setprio(0); } while (0)
; #define PG8_WAIT_V(n) asm volatile("s_waitcnt vmcnt(" #n ")" ::: "memory")
; #define PG8_WAIT_L(n) asm volatile("s_waitcnt lgkmcnt(" #n ")" ::: "memory")
; #define PG8_BAR __builtin_amdgcn_s_barrier()
; #define PG8_SCHED __builtin_amdgcn_sched_barrier(0)
; template <class Epi, class Sched = StaticOrder>
; DI void gemm_phase(LAS unsigned char* lds, const Gemm g, const Sched& S, const Epi& E) {
;     ...
;       PG8_WAIT_V(6); PG8_BAR; PG8_MMA(1, 1, At, B1); PG8_BAR;
;       PG8_LDB(B0, 1, 0); PG8_SCHED; PG8_LDA(At, 1, 0); PG8_STAGE(PG8_SA(0, 1), a2 + hstep, voffA);
;       PG8_WAIT_L(8); PG8_BAR; PG8_WAIT_L(0); PG8_MMA(0, 0, At, B0); PG8_BAR; PG8_SCHED;
;       PG8_LDB(B1, 1, 1); PG8_STAGE(PG8_SB(1, 0), b3, voffB);
;       PG8_BAR; PG8_WAIT_L(0); PG8_MMA(0, 1, At, B1); PG8_BAR;
;       PG8_LDA(At, 1, 1); PG8_STAGE(PG8_SA(1, 0), a3, voffA);
;       PG8_BAR; PG8_WAIT_L(0); PG8_MMA(1, 0, At, B0); PG8_BAR; PG8_SCHED;
	v_mfma_f32_16x16x32_bf16 v[56:59], v[206:209], v[120:123], v[56:59]
	v_mfma_f32_16x16x32_bf16 v[52:55], v[216:219], v[120:123], v[52:55]
	v_mfma_f32_16x16x32_bf16 v[40:43], v[206:209], v[136:139], v[40:43]
	v_mfma_f32_16x16x32_bf16 v[32:35], v[216:219], v[136:139], v[32:35]
	v_mfma_f32_16x16x32_bf16 v[24:27], v[206:209], v[180:183], v[24:27]
	v_mfma_f32_16x16x32_bf16 v[8:11], v[216:219], v[180:183], v[8:11]
	v_mfma_f32_16x16x32_bf16 v[4:7], v[206:209], v[188:191], v[4:7]
	v_mfma_f32_16x16x32_bf16 v[0:3], v[216:219], v[188:191], v[0:3]
	v_mfma_f32_16x16x32_bf16 v[56:59], v[212:215], v[128:131], v[56:59]
	v_mfma_f32_16x16x32_bf16 v[52:55], v[220:223], v[128:131], v[52:55]
	v_mfma_f32_16x16x32_bf16 v[40:43], v[212:215], v[148:151], v[40:43]
	v_mfma_f32_16x16x32_bf16 v[32:35], v[220:223], v[148:151], v[32:35]
	v_mfma_f32_16x16x32_bf16 v[24:27], v[212:215], v[184:187], v[24:27]
	v_mfma_f32_16x16x32_bf16 v[8:11], v[220:223], v[184:187], v[8:11]
	v_mfma_f32_16x16x32_bf16 v[4:7], v[212:215], v[192:195], v[4:7]
	v_mfma_f32_16x16x32_bf16 v[0:3], v[220:223], v[192:195], v[0:3]
	s_barrier
	s_setprio 0
	s_add_u32 s50, s50, 0x80000
	s_addc_u32 s51, s51, 0
	s_mov_b32 m0, s66
	ds_read_b128 v[120:123], v202 offset:32768
	ds_read_b128 v[128:131], v202 offset:33792
	ds_read_b128 v[180:183], v202 offset:34816
	ds_read_b128 v[184:187], v202 offset:35840
	ds_read_b128 v[188:191], v202 offset:36864
	ds_read_b128 v[192:195], v202 offset:37888
	ds_read_b128 v[206:209], v202 offset:38912
	ds_read_b128 v[212:215], v202 offset:39936
	global_load_lds_dwordx4 v166, s[50:51]
	s_mov_b32 m0, s67
	s_nop 0
	global_load_lds_dwordx4 v162, s[50:51]
	s_waitcnt lgkmcnt(8)
	s_setprio 1
	s_barrier
	s_waitcnt lgkmcnt(0)
	v_mfma_f32_16x16x32_bf16 v[136:139], v[64:67], v[120:123], v[156:159]
	v_mfma_f32_16x16x32_bf16 v[156:159], v[68:71], v[128:131], v[136:139]
	v_mfma_f32_16x16x32_bf16 v[136:139], v[72:75], v[120:123], v[144:147]
	v_mfma_f32_16x16x32_bf16 v[144:147], v[76:79], v[128:131], v[136:139]
	v_mfma_f32_16x16x32_bf16 v[136:139], v[64:67], v[180:183], v[140:143]
	v_mfma_f32_16x16x32_bf16 v[132:135], v[72:75], v[180:183], v[132:135]
	v_mfma_f32_16x16x32_bf16 v[124:127], v[64:67], v[188:191], v[124:127]
	v_mfma_f32_16x16x32_bf16 v[116:119], v[72:75], v[188:191], v[116:119]
	v_mfma_f32_16x16x32_bf16 v[112:115], v[64:67], v[206:209], v[112:115]
	v_mfma_f32_16x16x32_bf16 v[108:111], v[72:75], v[206:209], v[108:111]
	v_mfma_f32_16x16x32_bf16 v[140:143], v[68:71], v[184:187], v[136:139]
	v_mfma_f32_16x16x32_bf16 v[132:135], v[76:79], v[184:187], v[132:135]
	v_mfma_f32_16x16x32_bf16 v[124:127], v[68:71], v[192:195], v[124:127]
	v_mfma_f32_16x16x32_bf16 v[116:119], v[76:79], v[192:195], v[116:119]
	v_mfma_f32_16x16x32_bf16 v[112:115], v[68:71], v[212:215], v[112:115]
	v_mfma_f32_16x16x32_bf16 v[108:111], v[76:79], v[212:215], v[108:111]
	s_barrier
	s_setprio 0
	s_add_i32 s50, 0, 0x1c000
	v_add_u32_e32 v136, s50, v198
	s_add_i32 s51, s59, s62
	ds_read_b128 v[216:219], v136
	ds_read_b128 v[220:223], v136 offset:1024
	ds_read_b128 v[224:227], v136 offset:2048
	ds_read_b128 v[228:231], v136 offset:3072
	s_mov_b32 m0, s51
	s_nop 0
	global_load_lds_dwordx4 v164, s[98:99]
	s_add_i32 m0, s51, 0x2000
	s_nop 0
	global_load_lds_dwordx4 v160, s[98:99]
	s_setprio 1
	s_barrier
	s_waitcnt lgkmcnt(0)
	v_mfma_f32_16x16x32_bf16 v[80:83], v[224:227], v[120:123], v[80:83]
	v_mfma_f32_16x16x32_bf16 v[136:139], v[216:219], v[120:123], v[152:155]
	v_mfma_f32_16x16x32_bf16 v[148:151], v[228:231], v[128:131], v[80:83]
	v_mfma_f32_16x16x32_bf16 v[80:83], v[216:219], v[180:183], v[84:87]
	v_mfma_f32_16x16x32_bf16 v[152:155], v[220:223], v[128:131], v[136:139]
	v_mfma_f32_16x16x32_bf16 v[136:139], v[220:223], v[184:187], v[80:83]
	v_mfma_f32_16x16x32_bf16 v[80:83], v[224:227], v[180:183], v[88:91]
	v_mfma_f32_16x16x32_bf16 v[128:131], v[228:231], v[184:187], v[80:83]
	v_mfma_f32_16x16x32_bf16 v[80:83], v[216:219], v[188:191], v[92:95]
	v_mfma_f32_16x16x32_bf16 v[120:123], v[220:223], v[192:195], v[80:83]
	v_mfma_f32_16x16x32_bf16 v[80:83], v[224:227], v[188:191], v[104:107]
	v_mfma_f32_16x16x32_bf16 v[104:107], v[228:231], v[192:195], v[80:83]
	v_mfma_f32_16x16x32_bf16 v[80:83], v[216:219], v[206:209], v[100:103]
	v_mfma_f32_16x16x32_bf16 v[100:103], v[220:223], v[212:215], v[80:83]
	v_mfma_f32_16x16x32_bf16 v[80:83], v[224:227], v[206:209], v[96:99]
	v_mfma_f32_16x16x32_bf16 v[96:99], v[228:231], v[212:215], v[80:83]
	s_barrier
	s_setprio 0
	s_mov_b32 m0, s55
	s_nop 2
	ds_read_b128 v[80:83], v202 offset:49152
	ds_read_b128 v[84:87], v202 offset:50176
	ds_read_b128 v[88:91], v202 offset:51200
	ds_read_b128 v[92:95], v202 offset:52224
	ds_read_b128 v[180:183], v202 offset:53248
	ds_read_b128 v[184:187], v202 offset:54272
	ds_read_b128 v[188:191], v202 offset:55296
	ds_read_b128 v[192:195], v202 offset:56320
	global_load_lds_dwordx4 v166, s[100:101]
	s_mov_b32 m0, s68
	s_nop 0
	global_load_lds_dwordx4 v162, s[100:101]
	s_waitcnt vmcnt(10)
	s_setprio 1
	s_barrier
	s_waitcnt lgkmcnt(0)
	v_mfma_f32_16x16x32_bf16 v[60:63], v[64:67], v[80:83], v[60:63]
	v_mfma_f32_16x16x32_bf16 v[48:51], v[72:75], v[80:83], v[48:51]
	v_mfma_f32_16x16x32_bf16 v[44:47], v[64:67], v[88:91], v[44:47]
	v_mfma_f32_16x16x32_bf16 v[36:39], v[72:75], v[88:91], v[36:39]
	v_mfma_f32_16x16x32_bf16 v[28:31], v[64:67], v[180:183], v[28:31]
	v_mfma_f32_16x16x32_bf16 v[20:23], v[72:75], v[180:183], v[20:23]
	v_mfma_f32_16x16x32_bf16 v[16:19], v[64:67], v[188:191], v[16:19]
	v_mfma_f32_16x16x32_bf16 v[12:15], v[72:75], v[188:191], v[12:15]
	v_mfma_f32_16x16x32_bf16 v[60:63], v[68:71], v[84:87], v[60:63]
	v_mfma_f32_16x16x32_bf16 v[48:51], v[76:79], v[84:87], v[48:51]
	v_mfma_f32_16x16x32_bf16 v[44:47], v[68:71], v[92:95], v[44:47]
	v_mfma_f32_16x16x32_bf16 v[36:39], v[76:79], v[92:95], v[36:39]
	v_mfma_f32_16x16x32_bf16 v[28:31], v[68:71], v[184:187], v[28:31]
	v_mfma_f32_16x16x32_bf16 v[20:23], v[76:79], v[184:187], v[20:23]
	v_mfma_f32_16x16x32_bf16 v[16:19], v[68:71], v[192:195], v[16:19]
	v_mfma_f32_16x16x32_bf16 v[12:15], v[76:79], v[192:195], v[12:15]
	s_barrier
; #define PG8_STAGE(bufoff, gbase, voff) do { _Pragma("unroll") for (int _i = 0; _i < 2; ++_i) \
;     __builtin_amdgcn_global_load_lds((const unsigned*)((const char*)(gbase) + (voff)[_i]), (LAS unsigned*)(lds + (bufoff) + ldsw + _i * 8192), 16, 0, 0); } while (0)
; #define PG8_MMA(ai, bj, At, Bt) do { __builtin_amdgcn_s_setprio(1); _Pragma("unroll") for (int m = 0; m < 4; ++m) _Pragma("unroll") for (int n = 0; n < 2; ++n) _Pragma("unroll") for (int k = 0; k < 2; ++k) \
;     acc[ai][bj][m][n] = __builtin_amdgcn_mfma_f32_16x16x32_bf16(Bt[n][k], At[m][k], acc[ai][bj][m][n], 0, 0, 0); __builtin_amdgcn_s_setprio(0); } while (0)
; #define PG8_WAIT_V(n) asm volatile("s_waitcnt vmcnt(" #n ")" ::: "memory")
; #define PG8_BAR __builtin_amdgcn_s_barrier()
; DI float row_rstd(const float* ssq, int row, int fq) {
;   const f32x4 a = *(const f32x4*)(ssq + (size_t)row * 32 + fq * 8), b = *(const f32x4*)(ssq + (size_t)row * 32 + fq * 8 + 4);
;   float sm = ((a[0] + a[1]) + (a[2] + a[3])) + ((b[0] + b[1]) + (b[2] + b[3]));
;   sm += __shfl_xor(sm, 16); sm += __shfl_xor(sm, 32);
;   return rsqrtf(sm * (1.0f / 2048.f) + 1e-6f);
; }
;   DI void operator()(const f32x4 (&acc)[2][2][4][2], const Unit& u, int wr, int wc, int fr, int fq) const {
;     const int col = u.pn * 128 + wc * 32 + 8 * fq;
;     float w0[8], w1[8], w2[8], bb[8];
; #pragma unroll
;     for (int e = 0; e < 8; ++e) { w0[e] = cw[col + e]; w1[e] = cw[5632 + col + e]; w2[e] = cw[2 * 5632 + col + e]; bb[e] = cb[col + e]; }
; #pragma unroll
;     for (int ai = 0; ai < 2; ++ai) {
;       const int row0 = u.pm * BM + ai * HALF + wr * 64, span = row0 >> 6;
;       float rsv[4];
; #pragma unroll
;       for (int m = 0; m < 4; ++m) rsv[m] = row_rstd(ssq, row0 + 16 * m + fr, fq);
; template <class Epi, class Sched = StaticOrder>
; DI void gemm_phase(LAS unsigned char* lds, const Gemm g, const Sched& S, const Epi& E) {
;     ...
;       PG8_STAGE(PG8_SB(1, 1), b3 + hstep, voffB);
;       PG8_WAIT_V(6); PG8_BAR; PG8_MMA(1, 1, At, B1); PG8_BAR;
	s_setprio 0
	s_add_u32 s48, s48, 0x80080
	s_addc_u32 s49, s49, 0
	s_add_i32 s50, s50, s62
	s_mov_b32 m0, s50
	s_nop 0
	global_load_lds_dwordx4 v164, s[48:49]
	s_add_i32 m0, s50, 0x2000
	s_nop 0
	global_load_lds_dwordx4 v160, s[48:49]
	ds_read_b128 v[64:67], v201
	ds_read_b128 v[68:71], v201 offset:1024
	ds_read_b128 v[72:75], v201 offset:2048
	ds_read_b128 v[76:79], v201 offset:3072
	s_waitcnt vmcnt(6)
	s_setprio 1
	s_barrier
	v_mfma_f32_16x16x32_bf16 v[56:59], v[216:219], v[80:83], v[56:59]
	v_mfma_f32_16x16x32_bf16 v[52:55], v[224:227], v[80:83], v[52:55]
	v_mfma_f32_16x16x32_bf16 v[40:43], v[216:219], v[88:91], v[40:43]
	v_mfma_f32_16x16x32_bf16 v[32:35], v[224:227], v[88:91], v[32:35]
	v_mfma_f32_16x16x32_bf16 v[24:27], v[216:219], v[180:183], v[24:27]
	v_mfma_f32_16x16x32_bf16 v[8:11], v[224:227], v[180:183], v[8:11]
	v_mfma_f32_16x16x32_bf16 v[4:7], v[216:219], v[188:191], v[4:7]
	v_mfma_f32_16x16x32_bf16 v[0:3], v[224:227], v[188:191], v[0:3]
	v_mfma_f32_16x16x32_bf16 v[56:59], v[220:223], v[84:87], v[56:59]
	v_mfma_f32_16x16x32_bf16 v[52:55], v[228:231], v[84:87], v[52:55]
	v_mfma_f32_16x16x32_bf16 v[40:43], v[220:223], v[92:95], v[40:43]
	v_mfma_f32_16x16x32_bf16 v[32:35], v[228:231], v[92:95], v[32:35]
	v_mfma_f32_16x16x32_bf16 v[24:27], v[220:223], v[184:187], v[24:27]
	v_mfma_f32_16x16x32_bf16 v[8:11], v[228:231], v[184:187], v[8:11]
	v_mfma_f32_16x16x32_bf16 v[4:7], v[220:223], v[192:195], v[4:7]
	v_mfma_f32_16x16x32_bf16 v[0:3], v[228:231], v[192:195], v[0:3]
	s_add_i32 s58, s58, 2
	s_add_u32 s14, s14, 0x100
	s_addc_u32 s15, s15, 0
	s_add_u32 s52, s52, 0x100
	s_addc_u32 s53, s53, 0
	s_cmp_gt_u32 s58, 29
	s_barrier
	s_setprio 0
	s_cbranch_scc0 .LBB0_1277
	s_waitcnt lgkmcnt(0)
	s_lshl_b32 s39, s12, 8
	s_add_i32 s39, s39, s54
	v_or_b32_e32 v190, s39, v179
	v_ashrrev_i32_e32 v191, 31, v190
	v_lshlrev_b64 v[64:65], 7, v[190:191]
	v_or_b32_e32 v188, 16, v190
	v_lshl_add_u64 v[64:65], v[168:169], 0, v[64:65]
	v_ashrrev_i32_e32 v189, 31, v188
	global_load_dwordx4 v[192:195], v[64:65], off
	global_load_dwordx4 v[206:209], v[64:65], off offset:16
	v_lshlrev_b64 v[64:65], 7, v[188:189]
	v_lshl_add_u64 v[64:65], v[168:169], 0, v[64:65]
	global_load_dwordx4 v[212:215], v[64:65], off
	global_load_dwordx4 v[216:219], v[64:65], off offset:16
	v_or_b32_e32 v186, 32, v190
	v_ashrrev_i32_e32 v187, 31, v186
	v_lshlrev_b64 v[64:65], 7, v[186:187]
	v_or_b32_e32 v184, 48, v190
	v_lshl_add_u64 v[64:65], v[168:169], 0, v[64:65]
	v_ashrrev_i32_e32 v185, 31, v184
	global_load_dwordx4 v[220:223], v[64:65], off
	global_load_dwordx4 v[224:227], v[64:65], off offset:16
	v_lshlrev_b64 v[64:65], 7, v[184:185]
	v_lshl_add_u64 v[64:65], v[168:169], 0, v[64:65]
	global_load_dwordx4 v[228:231], v[64:65], off
	global_load_dwordx4 v[232:235], v[64:65], off offset:16
	v_lshl_or_b32 v180, s13, 7, v200
	v_and_b32_e32 v65, 64, v204
	v_xor_b32_e32 v64, 16, v204
	v_ashrrev_i32_e32 v181, 31, v180
	v_add_u32_e32 v65, 64, v65
	v_xor_b32_e32 v66, 32, v204
	v_lshlrev_b64 v[182:183], 2, v[180:181]
	v_cmp_lt_i32_e32 vcc, v64, v65
	v_lshl_add_u64 v[88:89], s[16:17], 0, v[182:183]
	v_lshl_add_u64 v[72:73], s[18:19], 0, v[182:183]
	v_cndmask_b32_e32 v64, v204, v64, vcc
	v_cmp_lt_i32_e32 vcc, v66, v65
	v_lshl_add_u64 v[74:75], v[88:89], 0, s[30:31]
	v_lshl_add_u64 v[76:77], v[88:89], 0, s[34:35]
	v_cndmask_b32_e32 v65, v204, v66, vcc
	v_add_co_u32_e32 v90, vcc, 0x5000, v88
	v_lshlrev_b32_e32 v187, 2, v64
	s_nop 0
	v_addc_co_u32_e32 v91, vcc, 0, v89, vcc
	v_add_co_u32_e32 v92, vcc, 0xb000, v88
	v_lshlrev_b32_e32 v185, 2, v65
	s_nop 0
	v_addc_co_u32_e32 v93, vcc, 0, v89, vcc
	global_load_dwordx4 v[64:67], v[88:89], off offset:16
	global_load_dwordx4 v[80:83], v[88:89], off
	global_load_dwordx4 v[68:71], v[72:73], off offset:16
	global_load_dwordx4 v[84:87], v[72:73], off
	s_nop 0
	global_load_dwordx4 v[72:75], v[74:75], off offset:16
	s_nop 0
	global_load_dwordx4 v[76:79], v[76:77], off offset:16
	s_nop 0
	global_load_dwordx4 v[88:91], v[90:91], off offset:2048
	s_nop 0
	global_load_dwordx4 v[92:95], v[92:93], off
	v_mov_b32_e32 v211, 0
	v_mov_b32_e32 v205, 0
	s_waitcnt vmcnt(0)
	v_mov_b32_e32 v196, v192
	v_mov_b32_e32 v197, v206
	v_mov_b32_e32 v206, v193
	v_mov_b32_e32 v192, v194
	v_mov_b32_e32 v193, v208
	v_mov_b32_e32 v208, v195
	v_pk_add_f32 v[194:195], v[196:197], v[206:207]
	v_pk_add_f32 v[192:193], v[192:193], v[208:209]
	v_mov_b32_e32 v196, v212
	v_mov_b32_e32 v197, v216
	v_mov_b32_e32 v216, v213
	v_mov_b32_e32 v206, v214
	v_mov_b32_e32 v207, v218
	v_mov_b32_e32 v218, v215
	v_pk_add_f32 v[192:193], v[194:195], v[192:193]
	v_pk_add_f32 v[194:195], v[196:197], v[216:217]
	v_pk_add_f32 v[196:197], v[206:207], v[218:219]
	v_mov_b32_e32 v208, v220
	v_pk_add_f32 v[194:195], v[194:195], v[196:197]
	v_mov_b32_e32 v197, v192
	v_mov_b32_e32 v196, v194
	v_mov_b32_e32 v192, v195
	v_pk_add_f32 v[192:193], v[196:197], v[192:193]
	ds_bpermute_b32 v195, v187, v193
	ds_bpermute_b32 v194, v187, v192
	v_mov_b32_e32 v209, v224
	v_mov_b32_e32 v224, v221
	v_mov_b32_e32 v212, v222
	v_mov_b32_e32 v213, v226
	s_waitcnt lgkmcnt(0)
	v_pk_add_f32 v[192:193], v[192:193], v[194:195]
	ds_bpermute_b32 v195, v185, v193
	ds_bpermute_b32 v194, v185, v192
	v_mov_b32_e32 v226, v223
	v_mov_b32_e32 v196, v228
	v_mov_b32_e32 v197, v232
	v_mov_b32_e32 v232, v229
	s_waitcnt lgkmcnt(0)
; DI unsigned pack2(float lo, float hi) { f32x2 v = {lo, hi}; bf16v2 r = __builtin_convertvector(v, bf16v2); return __builtin_bit_cast(unsigned, r); }
; DI float silu_f(float x) { return x * sigmoid_f(x); }
; DI float dpp_ror1(float v) { return __int_as_float(__builtin_amdgcn_update_dpp(0, __float_as_int(v), 0x121, 0xf, 0xf, false)); }
; DI float dpp_ror2(float v) { return __int_as_float(__builtin_amdgcn_update_dpp(0, __float_as_int(v), 0x122, 0xf, 0xf, false)); }
;   DI void operator()(const f32x4 (&acc)[2][2][4][2], const Unit& u, int wr, int wc, int fr, int fq) const {
;     ...
;       const int row0 = u.pm * BM + ai * HALF + wr * 64, span = row0 >> 6;
;       float rsv[4];
; #pragma unroll
;       for (int m = 0; m < 4; ++m) rsv[m] = row_rstd(ssq, row0 + 16 * m + fr, fq);
;       float p1[8], p2[8];
; #pragma unroll
;       for (int e = 0; e < 8; ++e) { p1[e] = 0.f; p2[e] = 0.f; }
; #pragma unroll
;       for (int m = 0; m < 4; ++m) {
;         float g[8], uu[8], a[8];
;         const float rs = rsv[m];
; #pragma unroll
;         for (int e = 0; e < 4; ++e) { g[e] = acc[ai][0][m][0][e] * rs; g[4 + e] = acc[ai][0][m][1][e] * rs; uu[e] = acc[ai][1][m][0][e] * rs; uu[4 + e] = acc[ai][1][m][1][e] * rs; }
; #pragma unroll
;         for (int e = 0; e < 8; ++e) {
;           const float x1 = dpp_ror1(g[e]), x2 = dpp_ror2(g[e]);
;           const float pr1 = (fr == 0) ? p1[e] : x1, pr2 = (fr < 2) ? p2[e] : x2;
;           a[e] = w2[e] * g[e] + w1[e] * pr1 + w0[e] * pr2 + bb[e];
;           p1[e] = x1; p2[e] = x2;
;         }
;         if (m == 0 && fr < 2) {
;           float* ha = headA + (size_t)(span * 2 + fr) * 5632 + col; float* hu = headU + (size_t)(span * 2 + fr) * 5632 + col;
;           *(f32x4*)ha = (f32x4){a[0], a[1], a[2], a[3]}; *(f32x4*)(ha + 4) = (f32x4){a[4], a[5], a[6], a[7]};
;           *(f32x4*)hu = (f32x4){uu[0], uu[1], uu[2], uu[3]}; *(f32x4*)(hu + 4) = (f32x4){uu[4], uu[5], uu[6], uu[7]};
;         } else {
;           u32x4 w;
;           w.x = pack2(silu_f(a[0]) * uu[0], silu_f(a[1]) * uu[1]);
;           w.y = pack2(silu_f(a[2]) * uu[2], silu_f(a[3]) * uu[3]);
;           w.z = pack2(silu_f(a[4]) * uu[4], silu_f(a[5]) * uu[5]);
;           w.w = pack2(silu_f(a[6]) * uu[6], silu_f(a[7]) * uu[7]);
;           *(u32x4*)(H + (size_t)(row0 + 16 * m + fr) * 5632 + col) = w;
	v_pk_add_f32 v[192:193], v[192:193], v[194:195]
	v_mov_b32_e32 v206, v230
	v_pk_fma_f32 v[192:193], v[192:193], s[36:37], v[178:179] op_sel_hi:[1,0,0]
	v_mov_b32_e32 v207, v234
	v_mul_f32_e32 v189, 0x4b800000, v193
	v_cmp_gt_f32_e64 s[12:13], s74, v193
	v_mov_b32_e32 v234, v231
	v_pk_add_f32 v[208:209], v[208:209], v[224:225]
	v_cndmask_b32_e64 v189, v193, v189, s[12:13]
	v_rsq_f32_e32 v189, v189
	v_pk_add_f32 v[212:213], v[212:213], v[226:227]
	v_pk_add_f32 v[196:197], v[196:197], v[232:233]
	v_pk_add_f32 v[194:195], v[206:207], v[234:235]
	v_mul_f32_e32 v191, 0x45800000, v189
	v_cndmask_b32_e64 v220, v189, v191, s[12:13]
	v_pk_add_f32 v[208:209], v[208:209], v[212:213]
	v_pk_add_f32 v[194:195], v[196:197], v[194:195]
	v_pk_mul_f32 v[156:157], v[156:157], v[220:221] op_sel_hi:[1,0]
	v_mov_b32_e32 v216, 0
	v_mov_b32_e32 v218, 0
	v_mov_b32_e32 v196, v194
	v_mov_b32_e32 v197, v208
	v_mov_b32_e32 v208, v195
	v_mov_b32_dpp v216, v156 row_ror:1 row_mask:0xf bank_mask:0xf
	v_mov_b32_dpp v218, v157 row_ror:1 row_mask:0xf bank_mask:0xf
	v_pk_add_f32 v[194:195], v[196:197], v[208:209]
	v_cndmask_b32_e64 v207, v218, 0, s[0:1]
	v_cndmask_b32_e64 v206, v216, 0, s[0:1]
	v_pk_mul_f32 v[158:159], v[158:159], v[220:221] op_sel_hi:[1,0]
	v_mov_b32_e32 v212, 0
	v_mov_b32_e32 v214, 0
	ds_bpermute_b32 v197, v187, v195
	ds_bpermute_b32 v196, v187, v194
	v_mov_b32_e32 v215, 0
	v_mov_b32_e32 v217, 0
	v_pk_mul_f32 v[206:207], v[88:89], v[206:207]
	v_mov_b32_dpp v212, v158 row_ror:1 row_mask:0xf bank_mask:0xf
	v_mov_b32_dpp v214, v159 row_ror:1 row_mask:0xf bank_mask:0xf
	v_mov_b32_dpp v215, v156 row_ror:2 row_mask:0xf bank_mask:0xf
	v_mov_b32_dpp v217, v157 row_ror:2 row_mask:0xf bank_mask:0xf
	v_pk_fma_f32 v[156:157], v[92:93], v[156:157], v[206:207]
	v_mov_b32_e32 v213, 0
	v_cndmask_b32_e64 v207, v214, 0, s[0:1]
	v_cndmask_b32_e64 v206, v212, 0, s[0:1]
	v_cndmask_b32_e64 v209, v217, 0, s[4:5]
	v_cndmask_b32_e64 v208, v215, 0, s[4:5]
	v_mov_b32_dpp v211, v158 row_ror:2 row_mask:0xf bank_mask:0xf
	v_mov_b32_dpp v213, v159 row_ror:2 row_mask:0xf bank_mask:0xf
	v_pk_mul_f32 v[206:207], v[90:91], v[206:207]
	v_pk_fma_f32 v[156:157], v[80:81], v[208:209], v[156:157]
	v_cndmask_b32_e64 v209, v213, 0, s[4:5]
	v_cndmask_b32_e64 v208, v211, 0, s[4:5]
	v_pk_fma_f32 v[158:159], v[94:95], v[158:159], v[206:207]
	v_pk_mul_f32 v[144:145], v[144:145], v[220:221] op_sel_hi:[1,0]
	v_pk_fma_f32 v[158:159], v[82:83], v[208:209], v[158:159]
	v_mov_b32_e32 v207, 0
	v_mov_b32_e32 v209, 0
	v_pk_mul_f32 v[146:147], v[146:147], v[220:221] op_sel_hi:[1,0]
	v_mov_b32_e32 v191, 0
	s_waitcnt lgkmcnt(0)
	v_pk_add_f32 v[194:195], v[194:195], v[196:197]
	v_mov_b32_dpp v207, v144 row_ror:1 row_mask:0xf bank_mask:0xf
	v_mov_b32_dpp v209, v145 row_ror:1 row_mask:0xf bank_mask:0xf
	v_mov_b32_dpp v191, v146 row_ror:1 row_mask:0xf bank_mask:0xf
	v_mov_b32_dpp v205, v147 row_ror:1 row_mask:0xf bank_mask:0xf
	ds_bpermute_b32 v197, v185, v195
	ds_bpermute_b32 v196, v185, v194
	v_pk_mul_f32 v[152:153], v[152:153], v[220:221] op_sel_hi:[1,0]
	v_pk_mul_f32 v[148:149], v[148:149], v[220:221] op_sel_hi:[1,0]
	v_pk_mul_f32 v[154:155], v[154:155], v[220:221] op_sel_hi:[1,0]
	v_pk_mul_f32 v[150:151], v[150:151], v[220:221] op_sel_hi:[1,0]
	v_mov_b32_e32 v206, 0
	v_mov_b32_e32 v208, 0
	v_cndmask_b32_e64 v223, v209, 0, s[0:1]
	v_cndmask_b32_e64 v222, v207, 0, s[0:1]
	v_mov_b32_e32 v189, 0
	v_mov_b32_e32 v193, 0
	v_cndmask_b32_e64 v221, v205, 0, s[0:1]
	v_cndmask_b32_e64 v220, v191, 0, s[0:1]
	v_mov_b32_dpp v206, v144 row_ror:2 row_mask:0xf bank_mask:0xf
	v_mov_b32_dpp v208, v145 row_ror:2 row_mask:0xf bank_mask:0xf
	v_pk_mul_f32 v[222:223], v[72:73], v[222:223]
	v_mov_b32_dpp v189, v146 row_ror:2 row_mask:0xf bank_mask:0xf
	v_mov_b32_dpp v193, v147 row_ror:2 row_mask:0xf bank_mask:0xf
	v_pk_mul_f32 v[220:221], v[74:75], v[220:221]
	v_cndmask_b32_e64 v225, v208, 0, s[4:5]
	v_cndmask_b32_e64 v224, v206, 0, s[4:5]
	v_pk_fma_f32 v[144:145], v[76:77], v[144:145], v[222:223]
	v_cndmask_b32_e64 v223, v193, 0, s[4:5]
	v_cndmask_b32_e64 v222, v189, 0, s[4:5]
	v_pk_fma_f32 v[146:147], v[78:79], v[146:147], v[220:221]
	v_pk_fma_f32 v[144:145], v[64:65], v[224:225], v[144:145]
	v_pk_fma_f32 v[146:147], v[66:67], v[222:223], v[146:147]
	v_cmp_gt_f32_e32 vcc, s74, v192
	v_pk_add_f32 v[156:157], v[84:85], v[156:157]
	v_pk_add_f32 v[158:159], v[86:87], v[158:159]
	v_pk_add_f32 v[144:145], v[68:69], v[144:145]
	v_pk_add_f32 v[146:147], v[70:71], v[146:147]
	s_and_saveexec_b64 s[12:13], s[10:11]
	s_xor_b64 s[12:13], exec, s[12:13]
	s_cbranch_execz .LBB0_1280
	v_mul_f32_e32 v219, 0xbfb8aa3b, v156
	v_exp_f32_e32 v219, v219
	v_mul_f32_e32 v220, 0xbfb8aa3b, v157
	v_exp_f32_e32 v220, v220
	v_mul_f32_e32 v222, 0xbfb8aa3b, v159
	v_add_f32_e32 v219, 1.0, v219
	v_exp_f32_e32 v223, v222
	v_add_f32_e32 v221, 1.0, v220
	v_rcp_f32_e32 v220, v219
	v_mul_f32_e32 v219, 0xbfb8aa3b, v158
	v_exp_f32_e32 v219, v219
	v_rcp_f32_e32 v221, v221
	v_add_f32_e32 v219, 1.0, v219
	v_rcp_f32_e32 v222, v219
	v_add_f32_e32 v219, 1.0, v223
	v_rcp_f32_e32 v223, v219
	v_pk_mul_f32 v[156:157], v[156:157], v[220:221]
	s_nop 0
	v_pk_mul_f32 v[152:153], v[152:153], v[156:157]
	v_pk_mul_f32 v[156:157], v[158:159], v[222:223]
	v_cvt_pk_bf16_f32 v152, v152, v153
	v_mul_f32_e32 v153, 0xbfb8aa3b, v144
	v_pk_mul_f32 v[154:155], v[154:155], v[156:157]
	v_exp_f32_e32 v156, v153
	v_mul_f32_e32 v153, 0xbfb8aa3b, v145
	v_exp_f32_e32 v157, v153
	v_cvt_pk_bf16_f32 v153, v154, v155
	v_add_f32_e32 v154, 1.0, v156
	v_mul_f32_e32 v156, 0xbfb8aa3b, v146
	v_add_f32_e32 v155, 1.0, v157
	v_mul_f32_e32 v157, 0xbfb8aa3b, v147
	v_exp_f32_e32 v156, v156
	v_exp_f32_e32 v157, v157
	v_rcp_f32_e32 v154, v154
	v_rcp_f32_e32 v155, v155
	v_add_f32_e32 v156, 1.0, v156
	v_add_f32_e32 v157, 1.0, v157
	v_rcp_f32_e32 v156, v156
	v_rcp_f32_e32 v157, v157
	v_pk_mul_f32 v[144:145], v[144:145], v[154:155]
	s_nop 0
	v_pk_mul_f32 v[144:145], v[148:149], v[144:145]
	s_nop 0
	v_cvt_pk_bf16_f32 v154, v144, v145
	v_pk_mul_f32 v[144:145], v[146:147], v[156:157]
	s_nop 0
	v_pk_mul_f32 v[144:145], v[150:151], v[144:145]
	s_nop 0
	v_cvt_pk_bf16_f32 v155, v144, v145
	v_mov_b64_e32 v[144:145], s[20:21]
	v_mad_i64_i32 v[144:145], s[14:15], v190, s75, v[144:145]
	v_lshl_add_u64 v[144:145], v[180:181], 1, v[144:145]
	global_store_dwordx4 v[144:145], v[152:155], off

; #define PG8_STAGE(bufoff, gbase, voff) do { _Pragma("unroll") for (int _i = 0; _i < 2; ++_i) \
;     __builtin_amdgcn_global_load_lds((const unsigned*)((const char*)(gbase) + (voff)[_i]), (LAS unsigned*)(lds + (bufoff) + ldsw + _i * 8192), 16, 0, 0); } while (0)
; #define PG8_LDA(dst, b, h) do { _Pragma("unroll") for (int m = 0; m < 4; ++m) _Pragma("unroll") for (int k = 0; k < 2; ++k) dst[m][k] = *(const LAS bf16x8*)(lds + PG8_SA(b, h) + aoff + m * 2048 + k * 1024); } while (0)
; #define PG8_LDB(dst, b, h) do { _Pragma("unroll") for (int n = 0; n < 2; ++n) _Pragma("unroll") for (int k = 0; k < 2; ++k) dst[n][k] = *(const LAS bf16x8*)(lds + PG8_SB(b, h) + boff + n * 2048 + k * 1024); } while (0)
; #define PG8_MMA(ai, bj, At, Bt) do { __builtin_amdgcn_s_setprio(1); _Pragma("unroll") for (int m = 0; m < 4; ++m) _Pragma("unroll") for (int n = 0; n < 2; ++n) _Pragma("unroll") for (int k = 0; k < 2; ++k) \
;     acc[ai][bj][m][n] = __builtin_amdgcn_mfma_f32_16x16x32_bf16(Bt[n][k], At[m][k], acc[ai][bj][m][n], 0, 0, 0); __builtin_amdgcn_s_setprio(0); } while (0)
; #define PG8_WAIT_V(n) asm volatile("s_waitcnt vmcnt(" #n ")" ::: "memory")
; #define PG8_WAIT_L(n) asm volatile("s_waitcnt lgkmcnt(" #n ")" ::: "memory")
; template <class Epi, class Sched = StaticOrder>
; DI void gemm_phase(LAS unsigned char* lds, const Gemm g, const Sched& S, const Epi& E) {
;     ...
;     for (int t = 0; t < nt; t += 2) {
;       const bool last = (t == nt - 2);
;       const char* a1 = cA + (size_t)(t + 1) * kstep;
;       const char* a2 = last ? nA : cA + (size_t)(t + 2) * kstep; const char* b2 = last ? nB : cB + (size_t)(t + 2) * kstep;
;       const char* a3 = a2 + kstep; const char* b3 = b2 + kstep;
;       PG8_LDB(B0, 0, 0); PG8_SCHED; PG8_LDA(At, 0, 0); PG8_STAGE(PG8_SA(1, 1), a1 + hstep, voffA);
;       PG8_WAIT_L(8); PG8_BAR; PG8_WAIT_L(0); PG8_MMA(0, 0, At, B0); PG8_BAR; PG8_SCHED;
;       PG8_LDB(B1, 0, 1); PG8_STAGE(PG8_SB(0, 0), b2, voffB);
;       PG8_BAR; PG8_WAIT_L(0); PG8_MMA(0, 1, At, B1); PG8_BAR;
;       PG8_LDA(At, 0, 1); PG8_STAGE(PG8_SA(0, 0), a2, voffA);
;       PG8_BAR; PG8_WAIT_L(0); PG8_MMA(1, 0, At, B0); PG8_BAR; PG8_SCHED;
;       PG8_STAGE(PG8_SB(0, 1), b2 + hstep, voffB);
;       PG8_WAIT_V(6); PG8_BAR; PG8_MMA(1, 1, At, B1); PG8_BAR;
;       PG8_LDB(B0, 1, 0); PG8_SCHED; PG8_LDA(At, 1, 0); PG8_STAGE(PG8_SA(0, 1), a2 + hstep, voffA);
.LBB0_1424:
	s_add_u32 s18, s16, 0xffea0080
	s_addc_u32 s19, s17, -1
	s_cmpk_eq_i32 s47, 0x54
	s_cselect_b32 s21, s3, s19
	s_cselect_b32 s20, s2, s18
	s_cselect_b32 s19, s5, s46
	s_cselect_b32 s18, s4, s45
	s_add_i32 m0, s30, 0xc000
	ds_read_b128 v[166:169], v160
	ds_read_b128 v[170:173], v160 offset:1024
	ds_read_b128 v[174:177], v160 offset:2048
	ds_read_b128 v[178:181], v160 offset:3072
	ds_read_b128 v[182:185], v160 offset:4096
	ds_read_b128 v[186:189], v160 offset:5120
	ds_read_b128 v[190:193], v160 offset:6144
	ds_read_b128 v[194:197], v160 offset:7168
	global_load_lds_dwordx4 v136, s[16:17]
	s_add_i32 m0, s30, 0xe000
	s_nop 0
	global_load_lds_dwordx4 v138, s[16:17]
	s_waitcnt lgkmcnt(8)
	s_setprio 1
	s_barrier
	s_waitcnt lgkmcnt(0)
	v_mfma_f32_16x16x32_bf16 v[124:127], v[144:147], v[166:169], v[124:127]
	v_mfma_f32_16x16x32_bf16 v[120:123], v[152:155], v[166:169], v[120:123]
	v_mfma_f32_16x16x32_bf16 v[116:119], v[144:147], v[174:177], v[116:119]
	v_mfma_f32_16x16x32_bf16 v[112:115], v[152:155], v[174:177], v[112:115]
	v_mfma_f32_16x16x32_bf16 v[104:107], v[144:147], v[182:185], v[104:107]
	v_mfma_f32_16x16x32_bf16 v[96:99], v[152:155], v[182:185], v[96:99]
	v_mfma_f32_16x16x32_bf16 v[88:91], v[144:147], v[190:193], v[88:91]
	v_mfma_f32_16x16x32_bf16 v[80:83], v[152:155], v[190:193], v[80:83]
	v_mfma_f32_16x16x32_bf16 v[124:127], v[148:151], v[170:173], v[124:127]
	v_mfma_f32_16x16x32_bf16 v[120:123], v[162:165], v[170:173], v[120:123]
	v_mfma_f32_16x16x32_bf16 v[116:119], v[148:151], v[178:181], v[116:119]
	v_mfma_f32_16x16x32_bf16 v[112:115], v[162:165], v[178:181], v[112:115]
	v_mfma_f32_16x16x32_bf16 v[104:107], v[148:151], v[186:189], v[104:107]
	v_mfma_f32_16x16x32_bf16 v[96:99], v[162:165], v[186:189], v[96:99]
	v_mfma_f32_16x16x32_bf16 v[88:91], v[148:151], v[194:197], v[88:91]
	v_mfma_f32_16x16x32_bf16 v[80:83], v[162:165], v[194:197], v[80:83]
	s_barrier
	s_setprio 0
	s_add_i32 s48, s39, s28
	s_add_u32 s98, s18, 0x80
	s_addc_u32 s99, s19, 0
	s_add_u32 s100, s20, 0x80
	s_addc_u32 s101, s21, 0
	s_mov_b32 m0, s48
	ds_read_b128 v[198:201], v161
	ds_read_b128 v[202:205], v161 offset:1024
	ds_read_b128 v[206:209], v161 offset:2048
	ds_read_b128 v[210:213], v161 offset:3072
	global_load_lds_dwordx4 v132, s[18:19]
	s_add_i32 m0, s48, 0x2000
	s_nop 0
	global_load_lds_dwordx4 v128, s[18:19]
	s_setprio 1
	s_barrier
	s_waitcnt lgkmcnt(0)
	v_mfma_f32_16x16x32_bf16 v[108:111], v[198:201], v[166:169], v[108:111]
	v_mfma_f32_16x16x32_bf16 v[100:103], v[206:209], v[166:169], v[100:103]
	v_mfma_f32_16x16x32_bf16 v[92:95], v[198:201], v[174:177], v[92:95]
	v_mfma_f32_16x16x32_bf16 v[84:87], v[206:209], v[174:177], v[84:87]
	v_mfma_f32_16x16x32_bf16 v[76:79], v[198:201], v[182:185], v[76:79]
	v_mfma_f32_16x16x32_bf16 v[72:75], v[206:209], v[182:185], v[72:75]
	v_mfma_f32_16x16x32_bf16 v[68:71], v[198:201], v[190:193], v[68:71]
	v_mfma_f32_16x16x32_bf16 v[64:67], v[206:209], v[190:193], v[64:67]
	v_mfma_f32_16x16x32_bf16 v[108:111], v[202:205], v[170:173], v[108:111]
	v_mfma_f32_16x16x32_bf16 v[100:103], v[210:213], v[170:173], v[100:103]
	v_mfma_f32_16x16x32_bf16 v[92:95], v[202:205], v[178:181], v[92:95]
	v_mfma_f32_16x16x32_bf16 v[84:87], v[210:213], v[178:181], v[84:87]
	v_mfma_f32_16x16x32_bf16 v[76:79], v[202:205], v[186:189], v[76:79]
	v_mfma_f32_16x16x32_bf16 v[72:75], v[210:213], v[186:189], v[72:75]
	v_mfma_f32_16x16x32_bf16 v[68:71], v[202:205], v[194:197], v[68:71]
	v_mfma_f32_16x16x32_bf16 v[64:67], v[210:213], v[194:197], v[64:67]
	s_barrier
	s_setprio 0
	s_mov_b32 m0, s30
	ds_read_b128 v[166:169], v160 offset:16384
	ds_read_b128 v[170:173], v160 offset:17408
	ds_read_b128 v[174:177], v160 offset:18432
	ds_read_b128 v[178:181], v160 offset:19456
	ds_read_b128 v[182:185], v160 offset:20480
	ds_read_b128 v[186:189], v160 offset:21504
	ds_read_b128 v[190:193], v160 offset:22528
	ds_read_b128 v[194:197], v160 offset:23552
	global_load_lds_dwordx4 v134, s[20:21]
	s_mov_b32 m0, s31
	s_nop 0
	global_load_lds_dwordx4 v130, s[20:21]
	s_waitcnt vmcnt(10)
	s_setprio 1
	s_barrier
	s_waitcnt lgkmcnt(0)
	v_mfma_f32_16x16x32_bf16 v[60:63], v[144:147], v[166:169], v[60:63]
	v_mfma_f32_16x16x32_bf16 v[56:59], v[152:155], v[166:169], v[56:59]
	v_mfma_f32_16x16x32_bf16 v[52:55], v[144:147], v[174:177], v[52:55]
	v_mfma_f32_16x16x32_bf16 v[44:47], v[152:155], v[174:177], v[44:47]
	v_mfma_f32_16x16x32_bf16 v[36:39], v[144:147], v[182:185], v[36:39]
	v_mfma_f32_16x16x32_bf16 v[28:31], v[152:155], v[182:185], v[28:31]
	v_mfma_f32_16x16x32_bf16 v[20:23], v[144:147], v[190:193], v[20:23]
	v_mfma_f32_16x16x32_bf16 v[12:15], v[152:155], v[190:193], v[12:15]
	v_mfma_f32_16x16x32_bf16 v[60:63], v[148:151], v[170:173], v[60:63]
	v_mfma_f32_16x16x32_bf16 v[56:59], v[162:165], v[170:173], v[56:59]
	v_mfma_f32_16x16x32_bf16 v[52:55], v[148:151], v[178:181], v[52:55]
	v_mfma_f32_16x16x32_bf16 v[44:47], v[162:165], v[178:181], v[44:47]
	v_mfma_f32_16x16x32_bf16 v[36:39], v[148:151], v[186:189], v[36:39]
	v_mfma_f32_16x16x32_bf16 v[28:31], v[162:165], v[186:189], v[28:31]
	v_mfma_f32_16x16x32_bf16 v[20:23], v[148:151], v[194:197], v[20:23]
	v_mfma_f32_16x16x32_bf16 v[12:15], v[162:165], v[194:197], v[12:15]
	s_barrier
	s_setprio 0
	s_add_u32 s48, s18, 0x160000
	s_addc_u32 s49, s19, 0
	s_add_i32 s50, s40, s28
	s_mov_b32 m0, s50
	s_nop 0
	global_load_lds_dwordx4 v132, s[48:49]
	s_add_i32 m0, s50, 0x2000
	s_nop 0
	global_load_lds_dwordx4 v128, s[48:49]
	s_add_i32 s48, 0, 0x18000
	v_add_u32_e32 v162, s48, v157
	ds_read_b128 v[144:147], v162
	ds_read_b128 v[148:151], v162 offset:1024
	ds_read_b128 v[152:155], v162 offset:2048
	ds_read_b128 v[162:165], v162 offset:3072
	s_waitcnt vmcnt(6)
	s_setprio 1
	s_barrier
; #define PG8_STAGE(bufoff, gbase, voff) do { _Pragma("unroll") for (int _i = 0; _i < 2; ++_i) \
;     __builtin_amdgcn_global_load_lds((const unsigned*)((const char*)(gbase) + (voff)[_i]), (LAS unsigned*)(lds + (bufoff) + ldsw + _i * 8192), 16, 0, 0); } while (0)
; #define PG8_LDA(dst, b, h) do { _Pragma("unroll") for (int m = 0; m < 4; ++m) _Pragma("unroll") for (int k = 0; k < 2; ++k) dst[m][k] = *(const LAS bf16x8*)(lds + PG8_SA(b, h) + aoff + m * 2048 + k * 1024); } while (0)
; #define PG8_LDB(dst, b, h) do { _Pragma("unroll") for (int n = 0; n < 2; ++n) _Pragma("unroll") for (int k = 0; k < 2; ++k) dst[n][k] = *(const LAS bf16x8*)(lds + PG8_SB(b, h) + boff + n * 2048 + k * 1024); } while (0)
; #define PG8_MMA(ai, bj, At, Bt) do { __builtin_amdgcn_s_setprio(1); _Pragma("unroll") for (int m = 0; m < 4; ++m) _Pragma("unroll") for (int n = 0; n < 2; ++n) _Pragma("unroll") for (int k = 0; k < 2; ++k) \
;     acc[ai][bj][m][n] = __builtin_amdgcn_mfma_f32_16x16x32_bf16(Bt[n][k], At[m][k], acc[ai][bj][m][n], 0, 0, 0); __builtin_amdgcn_s_setprio(0); } while (0)
; #define PG8_WAIT_V(n) asm volatile("s_waitcnt vmcnt(" #n ")" ::: "memory")
; #define PG8_WAIT_L(n) asm volatile("s_waitcnt lgkmcnt(" #n ")" ::: "memory")
; #define PG8_BAR __builtin_amdgcn_s_barrier()
; #define PG8_SCHED __builtin_amdgcn_sched_barrier(0)
; template <class Epi, class Sched = StaticOrder>
; DI void gemm_phase(LAS unsigned char* lds, const Gemm g, const Sched& S, const Epi& E) {
;     ...
;       PG8_LDB(B0, 1, 0); PG8_SCHED; PG8_LDA(At, 1, 0); PG8_STAGE(PG8_SA(0, 1), a2 + hstep, voffA);
;       PG8_WAIT_L(8); PG8_BAR; PG8_WAIT_L(0); PG8_MMA(0, 0, At, B0); PG8_BAR; PG8_SCHED;
;       PG8_LDB(B1, 1, 1); PG8_STAGE(PG8_SB(1, 0), b3, voffB);
;       PG8_BAR; PG8_WAIT_L(0); PG8_MMA(0, 1, At, B1); PG8_BAR;
;       PG8_LDA(At, 1, 1); PG8_STAGE(PG8_SA(1, 0), a3, voffA);
;       PG8_BAR; PG8_WAIT_L(0); PG8_MMA(1, 0, At, B0); PG8_BAR; PG8_SCHED;
;       PG8_STAGE(PG8_SB(1, 1), b3 + hstep, voffB);
;       PG8_WAIT_V(6); PG8_BAR; PG8_MMA(1, 1, At, B1); PG8_BAR;
	v_mfma_f32_16x16x32_bf16 v[48:51], v[198:201], v[166:169], v[48:51]
	v_mfma_f32_16x16x32_bf16 v[40:43], v[206:209], v[166:169], v[40:43]
	v_mfma_f32_16x16x32_bf16 v[32:35], v[198:201], v[174:177], v[32:35]
	v_mfma_f32_16x16x32_bf16 v[24:27], v[206:209], v[174:177], v[24:27]
	v_mfma_f32_16x16x32_bf16 v[16:19], v[198:201], v[182:185], v[16:19]
	v_mfma_f32_16x16x32_bf16 v[8:11], v[206:209], v[182:185], v[8:11]
	v_mfma_f32_16x16x32_bf16 v[4:7], v[198:201], v[190:193], v[4:7]
	v_mfma_f32_16x16x32_bf16 v[0:3], v[206:209], v[190:193], v[0:3]
	v_mfma_f32_16x16x32_bf16 v[48:51], v[202:205], v[170:173], v[48:51]
	v_mfma_f32_16x16x32_bf16 v[40:43], v[210:213], v[170:173], v[40:43]
	v_mfma_f32_16x16x32_bf16 v[32:35], v[202:205], v[178:181], v[32:35]
	v_mfma_f32_16x16x32_bf16 v[24:27], v[210:213], v[178:181], v[24:27]
	v_mfma_f32_16x16x32_bf16 v[16:19], v[202:205], v[186:189], v[16:19]
	v_mfma_f32_16x16x32_bf16 v[8:11], v[210:213], v[186:189], v[8:11]
	v_mfma_f32_16x16x32_bf16 v[4:7], v[202:205], v[194:197], v[4:7]
	v_mfma_f32_16x16x32_bf16 v[0:3], v[210:213], v[194:197], v[0:3]
	s_barrier
	s_setprio 0
	s_add_u32 s20, s20, 0x160000
	s_addc_u32 s21, s21, 0
	s_mov_b32 m0, s33
	ds_read_b128 v[166:169], v160 offset:32768
	ds_read_b128 v[170:173], v160 offset:33792
	ds_read_b128 v[174:177], v160 offset:34816
	ds_read_b128 v[178:181], v160 offset:35840
	ds_read_b128 v[182:185], v160 offset:36864
	ds_read_b128 v[186:189], v160 offset:37888
	ds_read_b128 v[190:193], v160 offset:38912
	ds_read_b128 v[194:197], v160 offset:39936
	global_load_lds_dwordx4 v134, s[20:21]
	s_mov_b32 m0, s34
	s_nop 0
	global_load_lds_dwordx4 v130, s[20:21]
	s_waitcnt lgkmcnt(8)
	s_setprio 1
	s_barrier
	s_waitcnt lgkmcnt(0)
	v_mfma_f32_16x16x32_bf16 v[124:127], v[144:147], v[166:169], v[124:127]
	v_mfma_f32_16x16x32_bf16 v[120:123], v[152:155], v[166:169], v[120:123]
	v_mfma_f32_16x16x32_bf16 v[116:119], v[144:147], v[174:177], v[116:119]
	v_mfma_f32_16x16x32_bf16 v[112:115], v[152:155], v[174:177], v[112:115]
	v_mfma_f32_16x16x32_bf16 v[104:107], v[144:147], v[182:185], v[104:107]
	v_mfma_f32_16x16x32_bf16 v[96:99], v[152:155], v[182:185], v[96:99]
	v_mfma_f32_16x16x32_bf16 v[88:91], v[144:147], v[190:193], v[88:91]
	v_mfma_f32_16x16x32_bf16 v[80:83], v[152:155], v[190:193], v[80:83]
	v_mfma_f32_16x16x32_bf16 v[124:127], v[148:151], v[170:173], v[124:127]
	v_mfma_f32_16x16x32_bf16 v[120:123], v[162:165], v[170:173], v[120:123]
	v_mfma_f32_16x16x32_bf16 v[116:119], v[148:151], v[178:181], v[116:119]
	v_mfma_f32_16x16x32_bf16 v[112:115], v[162:165], v[178:181], v[112:115]
	v_mfma_f32_16x16x32_bf16 v[104:107], v[148:151], v[186:189], v[104:107]
	v_mfma_f32_16x16x32_bf16 v[96:99], v[162:165], v[186:189], v[96:99]
	v_mfma_f32_16x16x32_bf16 v[88:91], v[148:151], v[194:197], v[88:91]
	v_mfma_f32_16x16x32_bf16 v[80:83], v[162:165], v[194:197], v[80:83]
	s_barrier
	s_setprio 0
	s_add_i32 s20, 0, 0x1c000
	s_add_i32 s21, s48, s28
	v_add_u32_e32 v210, s20, v157
	s_mov_b32 m0, s21
	ds_read_b128 v[198:201], v210
	ds_read_b128 v[202:205], v210 offset:1024
	ds_read_b128 v[206:209], v210 offset:2048
	ds_read_b128 v[210:213], v210 offset:3072
	global_load_lds_dwordx4 v132, s[98:99]
	s_add_i32 m0, s21, 0x2000
	s_nop 0
	global_load_lds_dwordx4 v128, s[98:99]
	s_setprio 1
	s_barrier
	s_waitcnt lgkmcnt(0)
	v_mfma_f32_16x16x32_bf16 v[108:111], v[198:201], v[166:169], v[108:111]
	v_mfma_f32_16x16x32_bf16 v[100:103], v[206:209], v[166:169], v[100:103]
	v_mfma_f32_16x16x32_bf16 v[92:95], v[198:201], v[174:177], v[92:95]
	v_mfma_f32_16x16x32_bf16 v[84:87], v[206:209], v[174:177], v[84:87]
	v_mfma_f32_16x16x32_bf16 v[76:79], v[198:201], v[182:185], v[76:79]
	v_mfma_f32_16x16x32_bf16 v[72:75], v[206:209], v[182:185], v[72:75]
	v_mfma_f32_16x16x32_bf16 v[68:71], v[198:201], v[190:193], v[68:71]
	v_mfma_f32_16x16x32_bf16 v[64:67], v[206:209], v[190:193], v[64:67]
	v_mfma_f32_16x16x32_bf16 v[108:111], v[202:205], v[170:173], v[108:111]
	v_mfma_f32_16x16x32_bf16 v[100:103], v[210:213], v[170:173], v[100:103]
	v_mfma_f32_16x16x32_bf16 v[92:95], v[202:205], v[178:181], v[92:95]
	v_mfma_f32_16x16x32_bf16 v[84:87], v[210:213], v[178:181], v[84:87]
	v_mfma_f32_16x16x32_bf16 v[76:79], v[202:205], v[186:189], v[76:79]
	v_mfma_f32_16x16x32_bf16 v[72:75], v[210:213], v[186:189], v[72:75]
	v_mfma_f32_16x16x32_bf16 v[68:71], v[202:205], v[194:197], v[68:71]
	v_mfma_f32_16x16x32_bf16 v[64:67], v[210:213], v[194:197], v[64:67]
	s_barrier
	s_setprio 0
	s_mov_b32 m0, s35
	ds_read_b128 v[166:169], v160 offset:49152
	ds_read_b128 v[170:173], v160 offset:50176
	ds_read_b128 v[174:177], v160 offset:51200
	ds_read_b128 v[178:181], v160 offset:52224
	ds_read_b128 v[182:185], v160 offset:53248
	ds_read_b128 v[186:189], v160 offset:54272
	ds_read_b128 v[190:193], v160 offset:55296
	ds_read_b128 v[194:197], v160 offset:56320
	global_load_lds_dwordx4 v134, s[100:101]
	s_mov_b32 m0, s36
	s_nop 0
	global_load_lds_dwordx4 v130, s[100:101]
	s_waitcnt vmcnt(10)
	s_setprio 1
	s_barrier
	s_waitcnt lgkmcnt(0)
	v_mfma_f32_16x16x32_bf16 v[60:63], v[144:147], v[166:169], v[60:63]
	v_mfma_f32_16x16x32_bf16 v[56:59], v[152:155], v[166:169], v[56:59]
	v_mfma_f32_16x16x32_bf16 v[52:55], v[144:147], v[174:177], v[52:55]
	v_mfma_f32_16x16x32_bf16 v[44:47], v[152:155], v[174:177], v[44:47]
	v_mfma_f32_16x16x32_bf16 v[36:39], v[144:147], v[182:185], v[36:39]
	v_mfma_f32_16x16x32_bf16 v[28:31], v[152:155], v[182:185], v[28:31]
	v_mfma_f32_16x16x32_bf16 v[20:23], v[144:147], v[190:193], v[20:23]
	v_mfma_f32_16x16x32_bf16 v[12:15], v[152:155], v[190:193], v[12:15]
	v_mfma_f32_16x16x32_bf16 v[60:63], v[148:151], v[170:173], v[60:63]
	v_mfma_f32_16x16x32_bf16 v[56:59], v[162:165], v[170:173], v[56:59]
	v_mfma_f32_16x16x32_bf16 v[52:55], v[148:151], v[178:181], v[52:55]
	v_mfma_f32_16x16x32_bf16 v[44:47], v[162:165], v[178:181], v[44:47]
	v_mfma_f32_16x16x32_bf16 v[36:39], v[148:151], v[186:189], v[36:39]
	v_mfma_f32_16x16x32_bf16 v[28:31], v[162:165], v[186:189], v[28:31]
	v_mfma_f32_16x16x32_bf16 v[20:23], v[148:151], v[194:197], v[20:23]
	v_mfma_f32_16x16x32_bf16 v[12:15], v[162:165], v[194:197], v[12:15]
	s_barrier
; #define PG8_STAGE(bufoff, gbase, voff) do { _Pragma("unroll") for (int _i = 0; _i < 2; ++_i) \
;     __builtin_amdgcn_global_load_lds((const unsigned*)((const char*)(gbase) + (voff)[_i]), (LAS unsigned*)(lds + (bufoff) + ldsw + _i * 8192), 16, 0, 0); } while (0)
; #define PG8_MMA(ai, bj, At, Bt) do { __builtin_amdgcn_s_setprio(1); _Pragma("unroll") for (int m = 0; m < 4; ++m) _Pragma("unroll") for (int n = 0; n < 2; ++n) _Pragma("unroll") for (int k = 0; k < 2; ++k) \
;     acc[ai][bj][m][n] = __builtin_amdgcn_mfma_f32_16x16x32_bf16(Bt[n][k], At[m][k], acc[ai][bj][m][n], 0, 0, 0); __builtin_amdgcn_s_setprio(0); } while (0)
; #define PG8_WAIT_V(n) asm volatile("s_waitcnt vmcnt(" #n ")" ::: "memory")
; #define PG8_BAR __builtin_amdgcn_s_barrier()
;   DI void operator()(const f32x4 (&acc)[2][2][4][2], const Unit& u, int wr, int wc, int fr, int fq) const {
;     const int row0 = u.pm * BM + wr * 64 + fr, col0 = u.pn * BM + wc * 32 + 8 * fq;
; #pragma unroll
;     for (int ai = 0; ai < 2; ++ai) {
;       f32x4 bv[4][2][2];
; #pragma unroll
;       for (int m = 0; m < 4; ++m)
; #pragma unroll
;         for (int bj = 0; bj < 2; ++bj) {
;           const float* bp = base + (size_t)(row0 + ai * HALF + m * 16) * 2048 + col0 + bj * HALF;
;           bv[m][bj][0] = *(const f32x4*)bp; bv[m][bj][1] = *(const f32x4*)(bp + 4);
;         }
; template <class Epi, class Sched = StaticOrder>
; DI void gemm_phase(LAS unsigned char* lds, const Gemm g, const Sched& S, const Epi& E) {
;     ...
;       PG8_STAGE(PG8_SB(1, 1), b3 + hstep, voffB);
;       PG8_WAIT_V(6); PG8_BAR; PG8_MMA(1, 1, At, B1); PG8_BAR;
;     }
;     E(acc, cur, wr, wc, fr, fq);
	s_setprio 0
	s_add_u32 s18, s18, 0x160080
	s_addc_u32 s19, s19, 0
	s_add_i32 s20, s20, s28
	s_mov_b32 m0, s20
	s_nop 0
	global_load_lds_dwordx4 v132, s[18:19]
	s_add_i32 m0, s20, 0x2000
	s_nop 0
	global_load_lds_dwordx4 v128, s[18:19]
	ds_read_b128 v[144:147], v159
	ds_read_b128 v[148:151], v159 offset:1024
	ds_read_b128 v[152:155], v159 offset:2048
	ds_read_b128 v[162:165], v159 offset:3072
	s_waitcnt vmcnt(6)
	s_setprio 1
	s_barrier
	v_mfma_f32_16x16x32_bf16 v[48:51], v[198:201], v[166:169], v[48:51]
	v_mfma_f32_16x16x32_bf16 v[40:43], v[206:209], v[166:169], v[40:43]
	v_mfma_f32_16x16x32_bf16 v[32:35], v[198:201], v[174:177], v[32:35]
	v_mfma_f32_16x16x32_bf16 v[24:27], v[206:209], v[174:177], v[24:27]
	v_mfma_f32_16x16x32_bf16 v[16:19], v[198:201], v[182:185], v[16:19]
	v_mfma_f32_16x16x32_bf16 v[8:11], v[206:209], v[182:185], v[8:11]
	v_mfma_f32_16x16x32_bf16 v[4:7], v[198:201], v[190:193], v[4:7]
	v_mfma_f32_16x16x32_bf16 v[0:3], v[206:209], v[190:193], v[0:3]
	v_mfma_f32_16x16x32_bf16 v[48:51], v[202:205], v[170:173], v[48:51]
	v_mfma_f32_16x16x32_bf16 v[40:43], v[210:213], v[170:173], v[40:43]
	v_mfma_f32_16x16x32_bf16 v[32:35], v[202:205], v[178:181], v[32:35]
	v_mfma_f32_16x16x32_bf16 v[24:27], v[210:213], v[178:181], v[24:27]
	v_mfma_f32_16x16x32_bf16 v[16:19], v[202:205], v[186:189], v[16:19]
	v_mfma_f32_16x16x32_bf16 v[8:11], v[210:213], v[186:189], v[8:11]
	v_mfma_f32_16x16x32_bf16 v[4:7], v[202:205], v[194:197], v[4:7]
	v_mfma_f32_16x16x32_bf16 v[0:3], v[210:213], v[194:197], v[0:3]
	s_add_i32 s47, s47, 2
	s_add_u32 s16, s16, 0x100
	s_addc_u32 s17, s17, 0
	s_add_u32 s45, s45, 0x100
	s_addc_u32 s46, s46, 0
	s_cmpk_gt_u32 s47, 0x55
	s_barrier
	s_setprio 0
	s_cbranch_scc0 .LBB0_1424
	s_waitcnt lgkmcnt(0)
	v_lshl_or_b32 v144, s44, 8, v158
	v_lshl_add_u32 v154, s43, 8, v156
	v_ashrrev_i32_e32 v145, 31, v144
	v_lshlrev_b64 v[144:145], 2, v[144:145]
	v_ashrrev_i32_e32 v155, 31, v154
	v_lshl_add_u64 v[146:147], s[54:55], 0, v[144:145]
	v_lshlrev_b64 v[148:149], 13, v[154:155]
	v_or_b32_e32 v174, 16, v154
	v_lshl_add_u64 v[170:171], v[146:147], 0, v[148:149]
	v_ashrrev_i32_e32 v175, 31, v174
	global_load_dwordx4 v[150:153], v[170:171], off offset:16
	global_load_dwordx4 v[162:165], v[170:171], off
	global_load_dwordx4 v[166:169], v[170:171], off offset:528
	s_nop 0
	global_load_dwordx4 v[170:173], v[170:171], off offset:512
	v_lshlrev_b64 v[222:223], 13, v[174:175]
	v_or_b32_e32 v190, 32, v154
	v_lshl_add_u64 v[186:187], v[146:147], 0, v[222:223]
	v_ashrrev_i32_e32 v191, 31, v190
	global_load_dwordx4 v[174:177], v[186:187], off offset:16
	global_load_dwordx4 v[178:181], v[186:187], off
	global_load_dwordx4 v[182:185], v[186:187], off offset:528
	s_nop 0
	global_load_dwordx4 v[186:189], v[186:187], off offset:512
	v_lshlrev_b64 v[224:225], 13, v[190:191]
	v_or_b32_e32 v154, 48, v154
	v_lshl_add_u64 v[202:203], v[146:147], 0, v[224:225]
	v_ashrrev_i32_e32 v155, 31, v154
	global_load_dwordx4 v[190:193], v[202:203], off offset:16
	global_load_dwordx4 v[194:197], v[202:203], off
	global_load_dwordx4 v[198:201], v[202:203], off offset:528
	s_nop 0
	global_load_dwordx4 v[202:205], v[202:203], off offset:512
	v_lshlrev_b64 v[154:155], 13, v[154:155]
	v_lshl_add_u64 v[218:219], v[146:147], 0, v[154:155]
	global_load_dwordx4 v[206:209], v[218:219], off offset:16
	global_load_dwordx4 v[210:213], v[218:219], off
	global_load_dwordx4 v[214:217], v[218:219], off offset:528
	s_nop 0
	global_load_dwordx4 v[218:221], v[218:219], off offset:512
	s_and_b64 vcc, exec, s[0:1]
	s_mov_b32 s44, s41
	s_mov_b32 s43, s42
	s_mov_b64 s[18:19], s[4:5]
	s_mov_b64 s[16:17], s[2:3]
	s_waitcnt vmcnt(0)
; DI unsigned pack2(float lo, float hi) { f32x2 v = {lo, hi}; bf16v2 r = __builtin_convertvector(v, bf16v2); return __builtin_bit_cast(unsigned, r); }
; #define PG8_WAIT_V(n) asm volatile("s_waitcnt vmcnt(" #n ")" ::: "memory")
; #define PG8_BAR __builtin_amdgcn_s_barrier()
;   DI void operator()(const f32x4 (&acc)[2][2][4][2], const Unit& u, int wr, int wc, int fr, int fq) const {
;     ...
;       for (int m = 0; m < 4; ++m) {
;         const int row = row0 + ai * HALF + m * 16;
;         const size_t off = (size_t)row * 2048 + col0;
;         float ss = 0.f;
; #pragma unroll
;         for (int bj = 0; bj < 2; ++bj) {
;           const f32x4 v0 = acc[ai][bj][m][0] + bv[m][bj][0], v1 = acc[ai][bj][m][1] + bv[m][bj][1];
;           *(f32x4*)(C + off + bj * HALF) = v0; *(f32x4*)(C + off + bj * HALF + 4) = v1;
;           if (xb) {
;             u32x4 w; w.x = pack2(v0[0], v0[1]); w.y = pack2(v0[2], v0[3]); w.z = pack2(v1[0], v1[1]); w.w = pack2(v1[2], v1[3]);
;             *(u32x4*)(xb + off + bj * HALF) = w;
;             ss += v0[0] * v0[0] + v0[1] * v0[1] + v0[2] * v0[2] + v0[3] * v0[3] + v1[0] * v1[0] + v1[1] * v1[1] + v1[2] * v1[2] + v1[3] * v1[3];
;           }
;         }
;         if (xb) {
;           ss += __shfl_xor(ss, 16); ss += __shfl_xor(ss, 32);
;           if (fq == 0) ssq[(size_t)row * 32 + u.pn * 4 + wc] = ss;
;         }
;       }
;     }
; template <class Epi, class Sched = StaticOrder>
; DI void gemm_phase(LAS unsigned char* lds, const Gemm g, const Sched& S, const Epi& E) {
;     ...
;     E(acc, cur, wr, wc, fr, fq);
;     if (!has_next) break;
; #pragma unroll
;     for (int a = 0; a < 2; ++a)
; #pragma unroll
;       for (int b = 0; b < 2; ++b)
; #pragma unroll
;         for (int m = 0; m < 4; ++m)
; #pragma unroll
;           for (int n = 0; n < 2; ++n) acc[a][b][m][n] = (f32x4){0.f, 0.f, 0.f, 0.f};
;     cur = nxt; cA = nA; cB = nB; ++ui;
;   }
;   PG8_WAIT_V(0);
;   if (wr == 0) PG8_BAR;
;   PG8_BAR;
	v_pk_add_f32 v[120:121], v[120:121], v[150:151]
	v_lshl_add_u64 v[150:151], s[54:55], 0, v[148:149]
	v_pk_add_f32 v[126:127], v[126:127], v[164:165]
	v_pk_add_f32 v[124:125], v[124:125], v[162:163]
	v_lshl_add_u64 v[150:151], v[150:151], 0, v[144:145]
	v_pk_add_f32 v[110:111], v[110:111], v[172:173]
	v_pk_add_f32 v[108:109], v[108:109], v[170:171]
	v_pk_add_f32 v[122:123], v[122:123], v[152:153]
	global_store_dwordx4 v[150:151], v[124:127], off
	global_store_dwordx4 v[150:151], v[120:123], off offset:16
	v_pk_add_f32 v[102:103], v[102:103], v[168:169]
	v_pk_add_f32 v[100:101], v[100:101], v[166:167]
	global_store_dwordx4 v[150:151], v[108:111], off offset:512
	global_store_dwordx4 v[150:151], v[100:103], off offset:528
	v_pk_add_f32 v[94:95], v[94:95], v[188:189]
	v_pk_add_f32 v[108:109], v[112:113], v[174:175]
	v_lshl_add_u64 v[112:113], s[54:55], 0, v[222:223]
	v_pk_add_f32 v[102:103], v[118:119], v[180:181]
	v_pk_add_f32 v[100:101], v[116:117], v[178:179]
	v_lshl_add_u64 v[112:113], v[112:113], 0, v[144:145]
	v_pk_add_f32 v[92:93], v[92:93], v[186:187]
	v_pk_add_f32 v[110:111], v[114:115], v[176:177]
	global_store_dwordx4 v[112:113], v[100:103], off
	global_store_dwordx4 v[112:113], v[108:111], off offset:16
	v_pk_add_f32 v[86:87], v[86:87], v[184:185]
	v_pk_add_f32 v[84:85], v[84:85], v[182:183]
	global_store_dwordx4 v[112:113], v[92:95], off offset:512
	global_store_dwordx4 v[112:113], v[84:87], off offset:528
	v_pk_add_f32 v[78:79], v[78:79], v[204:205]
	v_pk_add_f32 v[92:93], v[96:97], v[190:191]
	v_lshl_add_u64 v[96:97], s[54:55], 0, v[224:225]
	v_pk_add_f32 v[86:87], v[106:107], v[196:197]
	v_pk_add_f32 v[84:85], v[104:105], v[194:195]
	v_lshl_add_u64 v[96:97], v[96:97], 0, v[144:145]
	v_pk_add_f32 v[76:77], v[76:77], v[202:203]
	v_pk_add_f32 v[94:95], v[98:99], v[192:193]
	global_store_dwordx4 v[96:97], v[84:87], off
	global_store_dwordx4 v[96:97], v[92:95], off offset:16
	v_pk_add_f32 v[74:75], v[74:75], v[200:201]
	v_pk_add_f32 v[72:73], v[72:73], v[198:199]
	global_store_dwordx4 v[96:97], v[76:79], off offset:512
	global_store_dwordx4 v[96:97], v[72:75], off offset:528
	v_pk_add_f32 v[70:71], v[70:71], v[220:221]
	v_pk_add_f32 v[76:77], v[80:81], v[206:207]
	v_lshl_add_u64 v[80:81], s[54:55], 0, v[154:155]
	v_pk_add_f32 v[74:75], v[90:91], v[212:213]
	v_pk_add_f32 v[72:73], v[88:89], v[210:211]
	v_lshl_add_u64 v[80:81], v[80:81], 0, v[144:145]
	v_pk_add_f32 v[68:69], v[68:69], v[218:219]
	v_pk_add_f32 v[64:65], v[64:65], v[214:215]
	v_lshl_add_u64 v[154:155], v[148:149], 0, s[10:11]
	v_pk_add_f32 v[78:79], v[82:83], v[208:209]
	global_store_dwordx4 v[80:81], v[72:75], off
	global_store_dwordx4 v[80:81], v[76:79], off offset:16
	v_pk_add_f32 v[66:67], v[66:67], v[216:217]
	global_store_dwordx4 v[80:81], v[68:71], off offset:512
	global_store_dwordx4 v[80:81], v[64:67], off offset:528
	v_lshl_add_u64 v[152:153], v[148:149], 0, s[12:13]
	v_lshl_add_u64 v[150:151], v[148:149], 0, s[14:15]
	v_lshl_add_u64 v[64:65], v[146:147], 0, v[154:155]
	global_load_dwordx4 v[108:111], v[64:65], off offset:16
	global_load_dwordx4 v[120:123], v[64:65], off
	global_load_dwordx4 v[92:95], v[64:65], off offset:528
	global_load_dwordx4 v[100:103], v[64:65], off offset:512
	v_lshl_add_u64 v[64:65], v[146:147], 0, v[152:153]
	global_load_dwordx4 v[88:91], v[64:65], off offset:16
	global_load_dwordx4 v[96:99], v[64:65], off
	global_load_dwordx4 v[76:79], v[64:65], off offset:528
	global_load_dwordx4 v[84:87], v[64:65], off offset:512
	v_lshl_add_u64 v[68:69], v[146:147], 0, v[150:151]
	global_load_dwordx4 v[72:75], v[68:69], off offset:16
	global_load_dwordx4 v[80:83], v[68:69], off
	global_load_dwordx4 v[64:67], v[68:69], off offset:528
	s_nop 0
	global_load_dwordx4 v[68:71], v[68:69], off offset:512
	v_lshl_add_u64 v[148:149], v[148:149], 0, s[6:7]
	v_lshl_add_u64 v[112:113], v[146:147], 0, v[148:149]
	global_load_dwordx4 v[116:119], v[112:113], off offset:16
	global_load_dwordx4 v[124:127], v[112:113], off
	global_load_dwordx4 v[104:107], v[112:113], off offset:528
	s_nop 0
	global_load_dwordx4 v[112:115], v[112:113], off offset:512
	s_waitcnt vmcnt(0)
	v_pk_add_f32 v[56:57], v[56:57], v[108:109]
	v_lshl_add_u64 v[108:109], s[54:55], 0, v[154:155]
	v_pk_add_f32 v[62:63], v[62:63], v[122:123]
	v_pk_add_f32 v[60:61], v[60:61], v[120:121]
	v_lshl_add_u64 v[108:109], v[108:109], 0, v[144:145]
	v_pk_add_f32 v[50:51], v[50:51], v[102:103]
	v_pk_add_f32 v[48:49], v[48:49], v[100:101]
	v_pk_add_f32 v[58:59], v[58:59], v[110:111]
	global_store_dwordx4 v[108:109], v[60:63], off
	global_store_dwordx4 v[108:109], v[56:59], off offset:16
	v_pk_add_f32 v[42:43], v[42:43], v[94:95]
	v_pk_add_f32 v[40:41], v[40:41], v[92:93]
	global_store_dwordx4 v[108:109], v[48:51], off offset:512
	global_store_dwordx4 v[108:109], v[40:43], off offset:528
	v_pk_add_f32 v[34:35], v[34:35], v[86:87]
	v_lshl_add_u64 v[48:49], s[54:55], 0, v[152:153]
	v_pk_add_f32 v[42:43], v[54:55], v[98:99]
	v_pk_add_f32 v[40:41], v[52:53], v[96:97]
	v_lshl_add_u64 v[48:49], v[48:49], 0, v[144:145]
	v_pk_add_f32 v[32:33], v[32:33], v[84:85]
	v_pk_add_f32 v[46:47], v[46:47], v[90:91]
	v_pk_add_f32 v[44:45], v[44:45], v[88:89]
	global_store_dwordx4 v[48:49], v[40:43], off
	global_store_dwordx4 v[48:49], v[44:47], off offset:16
	v_pk_add_f32 v[26:27], v[26:27], v[78:79]
	v_pk_add_f32 v[24:25], v[24:25], v[76:77]
	global_store_dwordx4 v[48:49], v[32:35], off offset:512
	global_store_dwordx4 v[48:49], v[24:27], off offset:528
	v_pk_add_f32 v[18:19], v[18:19], v[70:71]
	v_lshl_add_u64 v[32:33], s[54:55], 0, v[150:151]
	v_pk_add_f32 v[26:27], v[38:39], v[82:83]
	v_pk_add_f32 v[24:25], v[36:37], v[80:81]
	v_lshl_add_u64 v[32:33], v[32:33], 0, v[144:145]
	v_pk_add_f32 v[16:17], v[16:17], v[68:69]
	v_pk_add_f32 v[30:31], v[30:31], v[74:75]
	v_pk_add_f32 v[28:29], v[28:29], v[72:73]
	global_store_dwordx4 v[32:33], v[24:27], off
	global_store_dwordx4 v[32:33], v[28:31], off offset:16
	v_pk_add_f32 v[10:11], v[10:11], v[66:67]
	v_pk_add_f32 v[8:9], v[8:9], v[64:65]
	global_store_dwordx4 v[32:33], v[16:19], off offset:512
	global_store_dwordx4 v[32:33], v[8:11], off offset:528
	v_pk_add_f32 v[6:7], v[6:7], v[114:115]
	v_lshl_add_u64 v[16:17], s[54:55], 0, v[148:149]
	v_pk_add_f32 v[10:11], v[22:23], v[126:127]
	v_pk_add_f32 v[8:9], v[20:21], v[124:125]
	v_lshl_add_u64 v[16:17], v[16:17], 0, v[144:145]
	v_pk_add_f32 v[4:5], v[4:5], v[112:113]
	v_pk_add_f32 v[14:15], v[14:15], v[118:119]
	v_pk_add_f32 v[12:13], v[12:13], v[116:117]
	global_store_dwordx4 v[16:17], v[8:11], off
	global_store_dwordx4 v[16:17], v[12:15], off offset:16
	v_pk_add_f32 v[2:3], v[2:3], v[106:107]
	v_pk_add_f32 v[0:1], v[0:1], v[104:105]
	global_store_dwordx4 v[16:17], v[4:7], off offset:512
	global_store_dwordx4 v[16:17], v[0:3], off offset:528
	s_cbranch_vccz .LBB0_1417
	s_waitcnt vmcnt(0)
	s_cmpk_gt_u32 s23, 0xff
	s_cbranch_scc1 .LBB0_1428
	s_barrier
